# scan waves: hand-scheduled inner code (LDS operands prefetched 2 steps ahead, S*w+k*v precomputed under the DPP reduction, no loop SALU/nops)
# speedup vs baseline: 1.0767x; 1.0063x over previous
; __device__ void phase_scan(int l, unsigned char* lds) {
;     ...
;             const Job jb = job_decode(J, ci);
;             const int rl = wid * 4 + (lane >> 4), row = jb.rs * 16 + rl, c0 = (lane & 15) * 4;
;             const size_t sidx = ((((size_t)l * (jb.is_s ? NSB : NB) + jb.seq) * 8 + jb.h) * 64 + row) * 64 + c0;
;             if (jb.first) { s01 = (f32x2){0.f, 0.f}; s23 = s01;
;                 if (jb.is_s) { asm volatile("" ::: "memory");
;                     s01 = (f32x2){s_pref[0], s_pref[1]}; s23 = (f32x2){s_pref[2], s_pref[3]}; } }
;             if (Jn < NJOBS && Jn >= 256 && cn == 0 && Jn != J) { const Job jn = job_decode(Jn, 0);
;                 s_pref = *(const f32x4*)(st_wkv + (((((size_t)l * NSB + jn.seq) * 8 + jn.h) * 64 + jn.rs * 16 + rl) * 64 + c0)); }
;             float yreg0 = 0.f, yreg1 = 0.f;
;             for (int t8 = 0; t8 < (jb.nsteps < 16 ? jb.nsteps : 16); t8 += 4) {
; #pragma unroll
;                 for (int u = 0; u < 4; ++u) {
;                     const int tt = t8 + u;
;                     const unsigned char* tb = buf + tt * SC_TOKB + c0 * 4;
;                     const f32x4 a = *(const f32x4*)(tb), w = *(const f32x4*)(tb + 256), b = *(const f32x4*)(tb + 512), k = *(const f32x4*)(tb + 768), r = *(const f32x4*)(tb + 1024);
;                     const float v = *(const float*)(buf + tt * SC_TOKB + 1280 + rl * 4);
;                     const f32x2 a01 = (f32x2){a[0], a[1]}, a23 = (f32x2){a[2], a[3]}, w01 = (f32x2){w[0], w[1]}, w23 = (f32x2){w[2], w[3]}, b01 = (f32x2){b[0], b[1]}, b23 = (f32x2){b[2], b[3]};
;                     const f32x2 k01 = (f32x2){k[0], k[1]}, k23 = (f32x2){k[2], k[3]}, r01 = (f32x2){r[0], r[1]}, r23 = (f32x2){r[2], r[3]};
;                     const f32x2 pa = s01 * a01 + s23 * a23;
;                     const float sa = allsum16(pa.x + pa.y);
;                     const f32x2 kv01 = k01 * v, kv23 = k23 * v;
;                     s01 = s01 * w01 + (b01 * sa + kv01); s23 = s23 * w23 + (b23 * sa + kv23);
;                     const f32x2 py = s01 * r01 + s23 * r23;
;                     const float y = allsum16(py.x + py.y);
;                     if ((lane & 15) == (tt & 15)) yreg0 = y;
;                 }
;             }
.LBB0_532:
	s_mul_hi_u32 s9, s83, 0xaaaaaaab
	s_lshr_b32 s9, s9, 1
	s_mul_i32 s9, s9, 0xfffe0800
	s_xor_b64 s[20:21], s[20:21], -1
	v_add_u32_e32 v217, s9, v110
	v_add_u32_e32 v218, s9, v111
	v_mov_b32_e32 v18, 0
	v_mov_b32_e32 v26, 0
	s_cmp_eq_u32 s8, 32
	s_cbranch_scc0 .Lscan0_n8
	ds_read_b128 v[120:123], v217 offset:0
	ds_read_b128 v[124:127], v217 offset:256
	ds_read_b128 v[128:131], v217 offset:512
	ds_read_b128 v[132:135], v217 offset:768
	ds_read_b128 v[136:139], v217 offset:1024
	ds_read_b32 v28, v218 offset:0
	ds_read_b128 v[146:149], v217 offset:1344
	ds_read_b128 v[150:153], v217 offset:1600
	ds_read_b128 v[154:157], v217 offset:1856
	ds_read_b128 v[158:161], v217 offset:2112
	ds_read_b128 v[162:165], v217 offset:2368
	ds_read_b32 v30, v218 offset:1344
	s_waitcnt lgkmcnt(6)
	ds_read_b128 v[32:35], v217 offset:2688
	ds_read_b128 v[36:39], v217 offset:2944
	ds_read_b128 v[40:43], v217 offset:3200
	ds_read_b128 v[44:47], v217 offset:3456
	ds_read_b128 v[48:51], v217 offset:3712
	ds_read_b32 v92, v218 offset:2688
	v_pk_mul_f32 v[206:207], v[24:25], v[122:123]
	v_pk_mul_f32 v[210:211], v[132:133], v[28:29] op_sel_hi:[1,0]
	v_pk_fma_f32 v[206:207], v[22:23], v[120:121], v[206:207]
	v_pk_mul_f32 v[212:213], v[134:135], v[28:29] op_sel_hi:[1,0]
	v_pk_fma_f32 v[210:211], v[22:23], v[124:125], v[210:211]
	v_add_f32_e32 v214, v206, v207
	v_pk_fma_f32 v[212:213], v[24:25], v[126:127], v[212:213]
	s_nop 0
	v_add_f32_dpp v214, v214, v214 quad_perm:[1,0,3,2] row_mask:0xf bank_mask:0xf bound_ctrl:1
	s_nop 1
	v_add_f32_dpp v214, v214, v214 quad_perm:[2,3,0,1] row_mask:0xf bank_mask:0xf bound_ctrl:1
	s_nop 1
	v_add_f32_dpp v214, v214, v214 row_half_mirror row_mask:0xf bank_mask:0xf bound_ctrl:1
	s_nop 1
	v_add_f32_dpp v214, v214, v214 row_mirror row_mask:0xf bank_mask:0xf bound_ctrl:1
	v_pk_fma_f32 v[22:23], v[128:129], v[214:215], v[210:211] op_sel_hi:[1,0,1]
	v_pk_fma_f32 v[24:25], v[130:131], v[214:215], v[212:213] op_sel_hi:[1,0,1]
	s_waitcnt lgkmcnt(6)
	ds_read_b128 v[186:189], v217 offset:4032
	ds_read_b128 v[190:193], v217 offset:4288
	ds_read_b128 v[194:197], v217 offset:4544
	ds_read_b128 v[198:201], v217 offset:4800
	ds_read_b128 v[202:205], v217 offset:5056
	ds_read_b32 v52, v218 offset:4032
	v_pk_mul_f32 v[206:207], v[24:25], v[148:149]
	v_pk_mul_f32 v[208:209], v[24:25], v[138:139]
	v_pk_fma_f32 v[206:207], v[22:23], v[146:147], v[206:207]
	v_pk_fma_f32 v[208:209], v[22:23], v[136:137], v[208:209]
	v_pk_mul_f32 v[210:211], v[158:159], v[30:31] op_sel_hi:[1,0]
	v_add_f32_e32 v214, v206, v207
	v_add_f32_e32 v216, v208, v209
	v_pk_mul_f32 v[212:213], v[160:161], v[30:31] op_sel_hi:[1,0]
	v_add_f32_dpp v214, v214, v214 quad_perm:[1,0,3,2] row_mask:0xf bank_mask:0xf bound_ctrl:1
	v_add_f32_dpp v216, v216, v216 quad_perm:[1,0,3,2] row_mask:0xf bank_mask:0xf bound_ctrl:1
	v_pk_fma_f32 v[210:211], v[22:23], v[150:151], v[210:211]
	v_add_f32_dpp v214, v214, v214 quad_perm:[2,3,0,1] row_mask:0xf bank_mask:0xf bound_ctrl:1
	v_add_f32_dpp v216, v216, v216 quad_perm:[2,3,0,1] row_mask:0xf bank_mask:0xf bound_ctrl:1
	v_pk_fma_f32 v[212:213], v[24:25], v[152:153], v[212:213]
	v_add_f32_dpp v214, v214, v214 row_half_mirror row_mask:0xf bank_mask:0xf bound_ctrl:1
	v_add_f32_dpp v216, v216, v216 row_half_mirror row_mask:0xf bank_mask:0xf bound_ctrl:1
	v_cmp_eq_u32_e32 vcc, 0, v106
	v_add_f32_dpp v214, v214, v214 row_mirror row_mask:0xf bank_mask:0xf bound_ctrl:1
	v_add_f32_dpp v216, v216, v216 row_mirror row_mask:0xf bank_mask:0xf bound_ctrl:1
	v_pk_fma_f32 v[22:23], v[154:155], v[214:215], v[210:211] op_sel_hi:[1,0,1]
	v_pk_fma_f32 v[24:25], v[156:157], v[214:215], v[212:213] op_sel_hi:[1,0,1]
	v_cndmask_b32_e32 v18, v18, v216, vcc
	s_waitcnt lgkmcnt(6)
	ds_read_b128 v[120:123], v217 offset:5376
	ds_read_b128 v[124:127], v217 offset:5632
	ds_read_b128 v[128:131], v217 offset:5888
	ds_read_b128 v[132:135], v217 offset:6144
	ds_read_b128 v[136:139], v217 offset:6400
	ds_read_b32 v28, v218 offset:5376
	v_pk_mul_f32 v[206:207], v[24:25], v[34:35]
	v_pk_mul_f32 v[208:209], v[24:25], v[164:165]
	v_pk_fma_f32 v[206:207], v[22:23], v[32:33], v[206:207]
	v_pk_fma_f32 v[208:209], v[22:23], v[162:163], v[208:209]
	v_pk_mul_f32 v[210:211], v[44:45], v[92:93] op_sel_hi:[1,0]
	v_add_f32_e32 v214, v206, v207
	v_add_f32_e32 v216, v208, v209
	v_pk_mul_f32 v[212:213], v[46:47], v[92:93] op_sel_hi:[1,0]
	v_add_f32_dpp v214, v214, v214 quad_perm:[1,0,3,2] row_mask:0xf bank_mask:0xf bound_ctrl:1
	v_add_f32_dpp v216, v216, v216 quad_perm:[1,0,3,2] row_mask:0xf bank_mask:0xf bound_ctrl:1
	v_pk_fma_f32 v[210:211], v[22:23], v[36:37], v[210:211]
	v_add_f32_dpp v214, v214, v214 quad_perm:[2,3,0,1] row_mask:0xf bank_mask:0xf bound_ctrl:1
	v_add_f32_dpp v216, v216, v216 quad_perm:[2,3,0,1] row_mask:0xf bank_mask:0xf bound_ctrl:1
	v_pk_fma_f32 v[212:213], v[24:25], v[38:39], v[212:213]
	v_add_f32_dpp v214, v214, v214 row_half_mirror row_mask:0xf bank_mask:0xf bound_ctrl:1
	v_add_f32_dpp v216, v216, v216 row_half_mirror row_mask:0xf bank_mask:0xf bound_ctrl:1
	v_cmp_eq_u32_e32 vcc, 1, v106
	v_add_f32_dpp v214, v214, v214 row_mirror row_mask:0xf bank_mask:0xf bound_ctrl:1
	v_add_f32_dpp v216, v216, v216 row_mirror row_mask:0xf bank_mask:0xf bound_ctrl:1
	v_pk_fma_f32 v[22:23], v[40:41], v[214:215], v[210:211] op_sel_hi:[1,0,1]
	v_pk_fma_f32 v[24:25], v[42:43], v[214:215], v[212:213] op_sel_hi:[1,0,1]
	v_cndmask_b32_e32 v18, v18, v216, vcc
	s_waitcnt lgkmcnt(6)
; __device__ void phase_scan(int l, unsigned char* lds) {
;     ...
;             for (int t8 = 0; t8 < (jb.nsteps < 16 ? jb.nsteps : 16); t8 += 4) {
; #pragma unroll
;                 for (int u = 0; u < 4; ++u) {
;                     const int tt = t8 + u;
;                     const unsigned char* tb = buf + tt * SC_TOKB + c0 * 4;
;                     const f32x4 a = *(const f32x4*)(tb), w = *(const f32x4*)(tb + 256), b = *(const f32x4*)(tb + 512), k = *(const f32x4*)(tb + 768), r = *(const f32x4*)(tb + 1024);
;                     const float v = *(const float*)(buf + tt * SC_TOKB + 1280 + rl * 4);
;                     const f32x2 a01 = (f32x2){a[0], a[1]}, a23 = (f32x2){a[2], a[3]}, w01 = (f32x2){w[0], w[1]}, w23 = (f32x2){w[2], w[3]}, b01 = (f32x2){b[0], b[1]}, b23 = (f32x2){b[2], b[3]};
;                     const f32x2 k01 = (f32x2){k[0], k[1]}, k23 = (f32x2){k[2], k[3]}, r01 = (f32x2){r[0], r[1]}, r23 = (f32x2){r[2], r[3]};
;                     const f32x2 pa = s01 * a01 + s23 * a23;
;                     const float sa = allsum16(pa.x + pa.y);
;                     const f32x2 kv01 = k01 * v, kv23 = k23 * v;
;                     s01 = s01 * w01 + (b01 * sa + kv01); s23 = s23 * w23 + (b23 * sa + kv23);
;                     const f32x2 py = s01 * r01 + s23 * r23;
;                     const float y = allsum16(py.x + py.y);
;                     if ((lane & 15) == (tt & 15)) yreg0 = y;
;                 }
;             }
	ds_read_b128 v[146:149], v217 offset:6720
	ds_read_b128 v[150:153], v217 offset:6976
	ds_read_b128 v[154:157], v217 offset:7232
	ds_read_b128 v[158:161], v217 offset:7488
	ds_read_b128 v[162:165], v217 offset:7744
	ds_read_b32 v30, v218 offset:6720
	v_pk_mul_f32 v[206:207], v[24:25], v[188:189]
	v_pk_mul_f32 v[208:209], v[24:25], v[50:51]
	v_pk_fma_f32 v[206:207], v[22:23], v[186:187], v[206:207]
	v_pk_fma_f32 v[208:209], v[22:23], v[48:49], v[208:209]
	v_pk_mul_f32 v[210:211], v[198:199], v[52:53] op_sel_hi:[1,0]
	v_add_f32_e32 v214, v206, v207
	v_add_f32_e32 v216, v208, v209
	v_pk_mul_f32 v[212:213], v[200:201], v[52:53] op_sel_hi:[1,0]
	v_add_f32_dpp v214, v214, v214 quad_perm:[1,0,3,2] row_mask:0xf bank_mask:0xf bound_ctrl:1
	v_add_f32_dpp v216, v216, v216 quad_perm:[1,0,3,2] row_mask:0xf bank_mask:0xf bound_ctrl:1
	v_pk_fma_f32 v[210:211], v[22:23], v[190:191], v[210:211]
	v_add_f32_dpp v214, v214, v214 quad_perm:[2,3,0,1] row_mask:0xf bank_mask:0xf bound_ctrl:1
	v_add_f32_dpp v216, v216, v216 quad_perm:[2,3,0,1] row_mask:0xf bank_mask:0xf bound_ctrl:1
	v_pk_fma_f32 v[212:213], v[24:25], v[192:193], v[212:213]
	v_add_f32_dpp v214, v214, v214 row_half_mirror row_mask:0xf bank_mask:0xf bound_ctrl:1
	v_add_f32_dpp v216, v216, v216 row_half_mirror row_mask:0xf bank_mask:0xf bound_ctrl:1
	v_cmp_eq_u32_e32 vcc, 2, v106
	v_add_f32_dpp v214, v214, v214 row_mirror row_mask:0xf bank_mask:0xf bound_ctrl:1
	v_add_f32_dpp v216, v216, v216 row_mirror row_mask:0xf bank_mask:0xf bound_ctrl:1
	v_pk_fma_f32 v[22:23], v[194:195], v[214:215], v[210:211] op_sel_hi:[1,0,1]
	v_pk_fma_f32 v[24:25], v[196:197], v[214:215], v[212:213] op_sel_hi:[1,0,1]
	v_cndmask_b32_e32 v18, v18, v216, vcc
	s_waitcnt lgkmcnt(6)
	ds_read_b128 v[32:35], v217 offset:8064
	ds_read_b128 v[36:39], v217 offset:8320
	ds_read_b128 v[40:43], v217 offset:8576
	ds_read_b128 v[44:47], v217 offset:8832
	ds_read_b128 v[48:51], v217 offset:9088
	ds_read_b32 v92, v218 offset:8064
	v_pk_mul_f32 v[206:207], v[24:25], v[122:123]
	v_pk_mul_f32 v[208:209], v[24:25], v[204:205]
	v_pk_fma_f32 v[206:207], v[22:23], v[120:121], v[206:207]
	v_pk_fma_f32 v[208:209], v[22:23], v[202:203], v[208:209]
	v_pk_mul_f32 v[210:211], v[132:133], v[28:29] op_sel_hi:[1,0]
	v_add_f32_e32 v214, v206, v207
	v_add_f32_e32 v216, v208, v209
	v_pk_mul_f32 v[212:213], v[134:135], v[28:29] op_sel_hi:[1,0]
	v_add_f32_dpp v214, v214, v214 quad_perm:[1,0,3,2] row_mask:0xf bank_mask:0xf bound_ctrl:1
	v_add_f32_dpp v216, v216, v216 quad_perm:[1,0,3,2] row_mask:0xf bank_mask:0xf bound_ctrl:1
	v_pk_fma_f32 v[210:211], v[22:23], v[124:125], v[210:211]
	v_add_f32_dpp v214, v214, v214 quad_perm:[2,3,0,1] row_mask:0xf bank_mask:0xf bound_ctrl:1
	v_add_f32_dpp v216, v216, v216 quad_perm:[2,3,0,1] row_mask:0xf bank_mask:0xf bound_ctrl:1
	v_pk_fma_f32 v[212:213], v[24:25], v[126:127], v[212:213]
	v_add_f32_dpp v214, v214, v214 row_half_mirror row_mask:0xf bank_mask:0xf bound_ctrl:1
	v_add_f32_dpp v216, v216, v216 row_half_mirror row_mask:0xf bank_mask:0xf bound_ctrl:1
	v_cmp_eq_u32_e32 vcc, 3, v106
	v_add_f32_dpp v214, v214, v214 row_mirror row_mask:0xf bank_mask:0xf bound_ctrl:1
	v_add_f32_dpp v216, v216, v216 row_mirror row_mask:0xf bank_mask:0xf bound_ctrl:1
	v_pk_fma_f32 v[22:23], v[128:129], v[214:215], v[210:211] op_sel_hi:[1,0,1]
	v_pk_fma_f32 v[24:25], v[130:131], v[214:215], v[212:213] op_sel_hi:[1,0,1]
	v_cndmask_b32_e32 v18, v18, v216, vcc
	s_waitcnt lgkmcnt(6)
	ds_read_b128 v[186:189], v217 offset:9408
	ds_read_b128 v[190:193], v217 offset:9664
	ds_read_b128 v[194:197], v217 offset:9920
	ds_read_b128 v[198:201], v217 offset:10176
	ds_read_b128 v[202:205], v217 offset:10432
	ds_read_b32 v52, v218 offset:9408
	v_pk_mul_f32 v[206:207], v[24:25], v[148:149]
	v_pk_mul_f32 v[208:209], v[24:25], v[138:139]
	v_pk_fma_f32 v[206:207], v[22:23], v[146:147], v[206:207]
	v_pk_fma_f32 v[208:209], v[22:23], v[136:137], v[208:209]
	v_pk_mul_f32 v[210:211], v[158:159], v[30:31] op_sel_hi:[1,0]
	v_add_f32_e32 v214, v206, v207
	v_add_f32_e32 v216, v208, v209
	v_pk_mul_f32 v[212:213], v[160:161], v[30:31] op_sel_hi:[1,0]
	v_add_f32_dpp v214, v214, v214 quad_perm:[1,0,3,2] row_mask:0xf bank_mask:0xf bound_ctrl:1
	v_add_f32_dpp v216, v216, v216 quad_perm:[1,0,3,2] row_mask:0xf bank_mask:0xf bound_ctrl:1
	v_pk_fma_f32 v[210:211], v[22:23], v[150:151], v[210:211]
	v_add_f32_dpp v214, v214, v214 quad_perm:[2,3,0,1] row_mask:0xf bank_mask:0xf bound_ctrl:1
	v_add_f32_dpp v216, v216, v216 quad_perm:[2,3,0,1] row_mask:0xf bank_mask:0xf bound_ctrl:1
	v_pk_fma_f32 v[212:213], v[24:25], v[152:153], v[212:213]
	v_add_f32_dpp v214, v214, v214 row_half_mirror row_mask:0xf bank_mask:0xf bound_ctrl:1
	v_add_f32_dpp v216, v216, v216 row_half_mirror row_mask:0xf bank_mask:0xf bound_ctrl:1
	v_cmp_eq_u32_e32 vcc, 4, v106
	v_add_f32_dpp v214, v214, v214 row_mirror row_mask:0xf bank_mask:0xf bound_ctrl:1
	v_add_f32_dpp v216, v216, v216 row_mirror row_mask:0xf bank_mask:0xf bound_ctrl:1
	v_pk_fma_f32 v[22:23], v[154:155], v[214:215], v[210:211] op_sel_hi:[1,0,1]
	v_pk_fma_f32 v[24:25], v[156:157], v[214:215], v[212:213] op_sel_hi:[1,0,1]
	v_cndmask_b32_e32 v18, v18, v216, vcc
	s_waitcnt lgkmcnt(6)
; __device__ void phase_scan(int l, unsigned char* lds) {
;     ...
;             for (int t8 = 0; t8 < (jb.nsteps < 16 ? jb.nsteps : 16); t8 += 4) {
; #pragma unroll
;                 for (int u = 0; u < 4; ++u) {
;                     const int tt = t8 + u;
;                     const unsigned char* tb = buf + tt * SC_TOKB + c0 * 4;
;                     const f32x4 a = *(const f32x4*)(tb), w = *(const f32x4*)(tb + 256), b = *(const f32x4*)(tb + 512), k = *(const f32x4*)(tb + 768), r = *(const f32x4*)(tb + 1024);
;                     const float v = *(const float*)(buf + tt * SC_TOKB + 1280 + rl * 4);
;                     const f32x2 a01 = (f32x2){a[0], a[1]}, a23 = (f32x2){a[2], a[3]}, w01 = (f32x2){w[0], w[1]}, w23 = (f32x2){w[2], w[3]}, b01 = (f32x2){b[0], b[1]}, b23 = (f32x2){b[2], b[3]};
;                     const f32x2 k01 = (f32x2){k[0], k[1]}, k23 = (f32x2){k[2], k[3]}, r01 = (f32x2){r[0], r[1]}, r23 = (f32x2){r[2], r[3]};
;                     const f32x2 pa = s01 * a01 + s23 * a23;
;                     const float sa = allsum16(pa.x + pa.y);
;                     const f32x2 kv01 = k01 * v, kv23 = k23 * v;
;                     s01 = s01 * w01 + (b01 * sa + kv01); s23 = s23 * w23 + (b23 * sa + kv23);
;                     const f32x2 py = s01 * r01 + s23 * r23;
;                     const float y = allsum16(py.x + py.y);
;                     if ((lane & 15) == (tt & 15)) yreg0 = y;
;                 }
;             }
	ds_read_b128 v[120:123], v217 offset:10752
	ds_read_b128 v[124:127], v217 offset:11008
	ds_read_b128 v[128:131], v217 offset:11264
	ds_read_b128 v[132:135], v217 offset:11520
	ds_read_b128 v[136:139], v217 offset:11776
	ds_read_b32 v28, v218 offset:10752
	v_pk_mul_f32 v[206:207], v[24:25], v[34:35]
	v_pk_mul_f32 v[208:209], v[24:25], v[164:165]
	v_pk_fma_f32 v[206:207], v[22:23], v[32:33], v[206:207]
	v_pk_fma_f32 v[208:209], v[22:23], v[162:163], v[208:209]
	v_pk_mul_f32 v[210:211], v[44:45], v[92:93] op_sel_hi:[1,0]
	v_add_f32_e32 v214, v206, v207
	v_add_f32_e32 v216, v208, v209
	v_pk_mul_f32 v[212:213], v[46:47], v[92:93] op_sel_hi:[1,0]
	v_add_f32_dpp v214, v214, v214 quad_perm:[1,0,3,2] row_mask:0xf bank_mask:0xf bound_ctrl:1
	v_add_f32_dpp v216, v216, v216 quad_perm:[1,0,3,2] row_mask:0xf bank_mask:0xf bound_ctrl:1
	v_pk_fma_f32 v[210:211], v[22:23], v[36:37], v[210:211]
	v_add_f32_dpp v214, v214, v214 quad_perm:[2,3,0,1] row_mask:0xf bank_mask:0xf bound_ctrl:1
	v_add_f32_dpp v216, v216, v216 quad_perm:[2,3,0,1] row_mask:0xf bank_mask:0xf bound_ctrl:1
	v_pk_fma_f32 v[212:213], v[24:25], v[38:39], v[212:213]
	v_add_f32_dpp v214, v214, v214 row_half_mirror row_mask:0xf bank_mask:0xf bound_ctrl:1
	v_add_f32_dpp v216, v216, v216 row_half_mirror row_mask:0xf bank_mask:0xf bound_ctrl:1
	v_cmp_eq_u32_e32 vcc, 5, v106
	v_add_f32_dpp v214, v214, v214 row_mirror row_mask:0xf bank_mask:0xf bound_ctrl:1
	v_add_f32_dpp v216, v216, v216 row_mirror row_mask:0xf bank_mask:0xf bound_ctrl:1
	v_pk_fma_f32 v[22:23], v[40:41], v[214:215], v[210:211] op_sel_hi:[1,0,1]
	v_pk_fma_f32 v[24:25], v[42:43], v[214:215], v[212:213] op_sel_hi:[1,0,1]
	v_cndmask_b32_e32 v18, v18, v216, vcc
	s_waitcnt lgkmcnt(6)
	ds_read_b128 v[146:149], v217 offset:12096
	ds_read_b128 v[150:153], v217 offset:12352
	ds_read_b128 v[154:157], v217 offset:12608
	ds_read_b128 v[158:161], v217 offset:12864
	ds_read_b128 v[162:165], v217 offset:13120
	ds_read_b32 v30, v218 offset:12096
	v_pk_mul_f32 v[206:207], v[24:25], v[188:189]
	v_pk_mul_f32 v[208:209], v[24:25], v[50:51]
	v_pk_fma_f32 v[206:207], v[22:23], v[186:187], v[206:207]
	v_pk_fma_f32 v[208:209], v[22:23], v[48:49], v[208:209]
	v_pk_mul_f32 v[210:211], v[198:199], v[52:53] op_sel_hi:[1,0]
	v_add_f32_e32 v214, v206, v207
	v_add_f32_e32 v216, v208, v209
	v_pk_mul_f32 v[212:213], v[200:201], v[52:53] op_sel_hi:[1,0]
	v_add_f32_dpp v214, v214, v214 quad_perm:[1,0,3,2] row_mask:0xf bank_mask:0xf bound_ctrl:1
	v_add_f32_dpp v216, v216, v216 quad_perm:[1,0,3,2] row_mask:0xf bank_mask:0xf bound_ctrl:1
	v_pk_fma_f32 v[210:211], v[22:23], v[190:191], v[210:211]
	v_add_f32_dpp v214, v214, v214 quad_perm:[2,3,0,1] row_mask:0xf bank_mask:0xf bound_ctrl:1
	v_add_f32_dpp v216, v216, v216 quad_perm:[2,3,0,1] row_mask:0xf bank_mask:0xf bound_ctrl:1
	v_pk_fma_f32 v[212:213], v[24:25], v[192:193], v[212:213]
	v_add_f32_dpp v214, v214, v214 row_half_mirror row_mask:0xf bank_mask:0xf bound_ctrl:1
	v_add_f32_dpp v216, v216, v216 row_half_mirror row_mask:0xf bank_mask:0xf bound_ctrl:1
	v_cmp_eq_u32_e32 vcc, 6, v106
	v_add_f32_dpp v214, v214, v214 row_mirror row_mask:0xf bank_mask:0xf bound_ctrl:1
	v_add_f32_dpp v216, v216, v216 row_mirror row_mask:0xf bank_mask:0xf bound_ctrl:1
	v_pk_fma_f32 v[22:23], v[194:195], v[214:215], v[210:211] op_sel_hi:[1,0,1]
	v_pk_fma_f32 v[24:25], v[196:197], v[214:215], v[212:213] op_sel_hi:[1,0,1]
	v_cndmask_b32_e32 v18, v18, v216, vcc
	s_waitcnt lgkmcnt(6)
	ds_read_b128 v[32:35], v217 offset:13440
	ds_read_b128 v[36:39], v217 offset:13696
	ds_read_b128 v[40:43], v217 offset:13952
	ds_read_b128 v[44:47], v217 offset:14208
	ds_read_b128 v[48:51], v217 offset:14464
	ds_read_b32 v92, v218 offset:13440
	v_pk_mul_f32 v[206:207], v[24:25], v[122:123]
	v_pk_mul_f32 v[208:209], v[24:25], v[204:205]
	v_pk_fma_f32 v[206:207], v[22:23], v[120:121], v[206:207]
	v_pk_fma_f32 v[208:209], v[22:23], v[202:203], v[208:209]
	v_pk_mul_f32 v[210:211], v[132:133], v[28:29] op_sel_hi:[1,0]
	v_add_f32_e32 v214, v206, v207
	v_add_f32_e32 v216, v208, v209
	v_pk_mul_f32 v[212:213], v[134:135], v[28:29] op_sel_hi:[1,0]
	v_add_f32_dpp v214, v214, v214 quad_perm:[1,0,3,2] row_mask:0xf bank_mask:0xf bound_ctrl:1
	v_add_f32_dpp v216, v216, v216 quad_perm:[1,0,3,2] row_mask:0xf bank_mask:0xf bound_ctrl:1
	v_pk_fma_f32 v[210:211], v[22:23], v[124:125], v[210:211]
	v_add_f32_dpp v214, v214, v214 quad_perm:[2,3,0,1] row_mask:0xf bank_mask:0xf bound_ctrl:1
	v_add_f32_dpp v216, v216, v216 quad_perm:[2,3,0,1] row_mask:0xf bank_mask:0xf bound_ctrl:1
	v_pk_fma_f32 v[212:213], v[24:25], v[126:127], v[212:213]
	v_add_f32_dpp v214, v214, v214 row_half_mirror row_mask:0xf bank_mask:0xf bound_ctrl:1
	v_add_f32_dpp v216, v216, v216 row_half_mirror row_mask:0xf bank_mask:0xf bound_ctrl:1
	v_cmp_eq_u32_e32 vcc, 7, v106
	v_add_f32_dpp v214, v214, v214 row_mirror row_mask:0xf bank_mask:0xf bound_ctrl:1
	v_add_f32_dpp v216, v216, v216 row_mirror row_mask:0xf bank_mask:0xf bound_ctrl:1
	v_pk_fma_f32 v[22:23], v[128:129], v[214:215], v[210:211] op_sel_hi:[1,0,1]
	v_pk_fma_f32 v[24:25], v[130:131], v[214:215], v[212:213] op_sel_hi:[1,0,1]
	v_cndmask_b32_e32 v18, v18, v216, vcc
	s_waitcnt lgkmcnt(6)
; __device__ void phase_scan(int l, unsigned char* lds) {
;     ...
;             for (int t8 = 0; t8 < (jb.nsteps < 16 ? jb.nsteps : 16); t8 += 4) {
; #pragma unroll
;                 for (int u = 0; u < 4; ++u) {
;                     const int tt = t8 + u;
;                     const unsigned char* tb = buf + tt * SC_TOKB + c0 * 4;
;                     const f32x4 a = *(const f32x4*)(tb), w = *(const f32x4*)(tb + 256), b = *(const f32x4*)(tb + 512), k = *(const f32x4*)(tb + 768), r = *(const f32x4*)(tb + 1024);
;                     const float v = *(const float*)(buf + tt * SC_TOKB + 1280 + rl * 4);
;                     const f32x2 a01 = (f32x2){a[0], a[1]}, a23 = (f32x2){a[2], a[3]}, w01 = (f32x2){w[0], w[1]}, w23 = (f32x2){w[2], w[3]}, b01 = (f32x2){b[0], b[1]}, b23 = (f32x2){b[2], b[3]};
;                     const f32x2 k01 = (f32x2){k[0], k[1]}, k23 = (f32x2){k[2], k[3]}, r01 = (f32x2){r[0], r[1]}, r23 = (f32x2){r[2], r[3]};
;                     const f32x2 pa = s01 * a01 + s23 * a23;
;                     const float sa = allsum16(pa.x + pa.y);
;                     const f32x2 kv01 = k01 * v, kv23 = k23 * v;
;                     s01 = s01 * w01 + (b01 * sa + kv01); s23 = s23 * w23 + (b23 * sa + kv23);
;                     const f32x2 py = s01 * r01 + s23 * r23;
;                     const float y = allsum16(py.x + py.y);
;                     if ((lane & 15) == (tt & 15)) yreg0 = y;
;                 }
;             }
	ds_read_b128 v[186:189], v217 offset:14784
	ds_read_b128 v[190:193], v217 offset:15040
	ds_read_b128 v[194:197], v217 offset:15296
	ds_read_b128 v[198:201], v217 offset:15552
	ds_read_b128 v[202:205], v217 offset:15808
	ds_read_b32 v52, v218 offset:14784
	v_pk_mul_f32 v[206:207], v[24:25], v[148:149]
	v_pk_mul_f32 v[208:209], v[24:25], v[138:139]
	v_pk_fma_f32 v[206:207], v[22:23], v[146:147], v[206:207]
	v_pk_fma_f32 v[208:209], v[22:23], v[136:137], v[208:209]
	v_pk_mul_f32 v[210:211], v[158:159], v[30:31] op_sel_hi:[1,0]
	v_add_f32_e32 v214, v206, v207
	v_add_f32_e32 v216, v208, v209
	v_pk_mul_f32 v[212:213], v[160:161], v[30:31] op_sel_hi:[1,0]
	v_add_f32_dpp v214, v214, v214 quad_perm:[1,0,3,2] row_mask:0xf bank_mask:0xf bound_ctrl:1
	v_add_f32_dpp v216, v216, v216 quad_perm:[1,0,3,2] row_mask:0xf bank_mask:0xf bound_ctrl:1
	v_pk_fma_f32 v[210:211], v[22:23], v[150:151], v[210:211]
	v_add_f32_dpp v214, v214, v214 quad_perm:[2,3,0,1] row_mask:0xf bank_mask:0xf bound_ctrl:1
	v_add_f32_dpp v216, v216, v216 quad_perm:[2,3,0,1] row_mask:0xf bank_mask:0xf bound_ctrl:1
	v_pk_fma_f32 v[212:213], v[24:25], v[152:153], v[212:213]
	v_add_f32_dpp v214, v214, v214 row_half_mirror row_mask:0xf bank_mask:0xf bound_ctrl:1
	v_add_f32_dpp v216, v216, v216 row_half_mirror row_mask:0xf bank_mask:0xf bound_ctrl:1
	v_cmp_eq_u32_e32 vcc, 8, v106
	v_add_f32_dpp v214, v214, v214 row_mirror row_mask:0xf bank_mask:0xf bound_ctrl:1
	v_add_f32_dpp v216, v216, v216 row_mirror row_mask:0xf bank_mask:0xf bound_ctrl:1
	v_pk_fma_f32 v[22:23], v[154:155], v[214:215], v[210:211] op_sel_hi:[1,0,1]
	v_pk_fma_f32 v[24:25], v[156:157], v[214:215], v[212:213] op_sel_hi:[1,0,1]
	v_cndmask_b32_e32 v18, v18, v216, vcc
	s_waitcnt lgkmcnt(6)
	ds_read_b128 v[120:123], v217 offset:16128
	ds_read_b128 v[124:127], v217 offset:16384
	ds_read_b128 v[128:131], v217 offset:16640
	ds_read_b128 v[132:135], v217 offset:16896
	ds_read_b128 v[136:139], v217 offset:17152
	ds_read_b32 v28, v218 offset:16128
	v_pk_mul_f32 v[206:207], v[24:25], v[34:35]
	v_pk_mul_f32 v[208:209], v[24:25], v[164:165]
	v_pk_fma_f32 v[206:207], v[22:23], v[32:33], v[206:207]
	v_pk_fma_f32 v[208:209], v[22:23], v[162:163], v[208:209]
	v_pk_mul_f32 v[210:211], v[44:45], v[92:93] op_sel_hi:[1,0]
	v_add_f32_e32 v214, v206, v207
	v_add_f32_e32 v216, v208, v209
	v_pk_mul_f32 v[212:213], v[46:47], v[92:93] op_sel_hi:[1,0]
	v_add_f32_dpp v214, v214, v214 quad_perm:[1,0,3,2] row_mask:0xf bank_mask:0xf bound_ctrl:1
	v_add_f32_dpp v216, v216, v216 quad_perm:[1,0,3,2] row_mask:0xf bank_mask:0xf bound_ctrl:1
	v_pk_fma_f32 v[210:211], v[22:23], v[36:37], v[210:211]
	v_add_f32_dpp v214, v214, v214 quad_perm:[2,3,0,1] row_mask:0xf bank_mask:0xf bound_ctrl:1
	v_add_f32_dpp v216, v216, v216 quad_perm:[2,3,0,1] row_mask:0xf bank_mask:0xf bound_ctrl:1
	v_pk_fma_f32 v[212:213], v[24:25], v[38:39], v[212:213]
	v_add_f32_dpp v214, v214, v214 row_half_mirror row_mask:0xf bank_mask:0xf bound_ctrl:1
	v_add_f32_dpp v216, v216, v216 row_half_mirror row_mask:0xf bank_mask:0xf bound_ctrl:1
	v_cmp_eq_u32_e32 vcc, 9, v106
	v_add_f32_dpp v214, v214, v214 row_mirror row_mask:0xf bank_mask:0xf bound_ctrl:1
	v_add_f32_dpp v216, v216, v216 row_mirror row_mask:0xf bank_mask:0xf bound_ctrl:1
	v_pk_fma_f32 v[22:23], v[40:41], v[214:215], v[210:211] op_sel_hi:[1,0,1]
	v_pk_fma_f32 v[24:25], v[42:43], v[214:215], v[212:213] op_sel_hi:[1,0,1]
	v_cndmask_b32_e32 v18, v18, v216, vcc
	s_waitcnt lgkmcnt(6)
	ds_read_b128 v[146:149], v217 offset:17472
	ds_read_b128 v[150:153], v217 offset:17728
	ds_read_b128 v[154:157], v217 offset:17984
	ds_read_b128 v[158:161], v217 offset:18240
	ds_read_b128 v[162:165], v217 offset:18496
	ds_read_b32 v30, v218 offset:17472
	v_pk_mul_f32 v[206:207], v[24:25], v[188:189]
	v_pk_mul_f32 v[208:209], v[24:25], v[50:51]
	v_pk_fma_f32 v[206:207], v[22:23], v[186:187], v[206:207]
	v_pk_fma_f32 v[208:209], v[22:23], v[48:49], v[208:209]
	v_pk_mul_f32 v[210:211], v[198:199], v[52:53] op_sel_hi:[1,0]
	v_add_f32_e32 v214, v206, v207
	v_add_f32_e32 v216, v208, v209
	v_pk_mul_f32 v[212:213], v[200:201], v[52:53] op_sel_hi:[1,0]
	v_add_f32_dpp v214, v214, v214 quad_perm:[1,0,3,2] row_mask:0xf bank_mask:0xf bound_ctrl:1
	v_add_f32_dpp v216, v216, v216 quad_perm:[1,0,3,2] row_mask:0xf bank_mask:0xf bound_ctrl:1
	v_pk_fma_f32 v[210:211], v[22:23], v[190:191], v[210:211]
	v_add_f32_dpp v214, v214, v214 quad_perm:[2,3,0,1] row_mask:0xf bank_mask:0xf bound_ctrl:1
	v_add_f32_dpp v216, v216, v216 quad_perm:[2,3,0,1] row_mask:0xf bank_mask:0xf bound_ctrl:1
	v_pk_fma_f32 v[212:213], v[24:25], v[192:193], v[212:213]
	v_add_f32_dpp v214, v214, v214 row_half_mirror row_mask:0xf bank_mask:0xf bound_ctrl:1
	v_add_f32_dpp v216, v216, v216 row_half_mirror row_mask:0xf bank_mask:0xf bound_ctrl:1
	v_cmp_eq_u32_e32 vcc, 10, v106
	v_add_f32_dpp v214, v214, v214 row_mirror row_mask:0xf bank_mask:0xf bound_ctrl:1
	v_add_f32_dpp v216, v216, v216 row_mirror row_mask:0xf bank_mask:0xf bound_ctrl:1
	v_pk_fma_f32 v[22:23], v[194:195], v[214:215], v[210:211] op_sel_hi:[1,0,1]
	v_pk_fma_f32 v[24:25], v[196:197], v[214:215], v[212:213] op_sel_hi:[1,0,1]
	v_cndmask_b32_e32 v18, v18, v216, vcc
	s_waitcnt lgkmcnt(6)
; __device__ void phase_scan(int l, unsigned char* lds) {
;     ...
;             for (int t8 = 0; t8 < (jb.nsteps < 16 ? jb.nsteps : 16); t8 += 4) {
; #pragma unroll
;                 for (int u = 0; u < 4; ++u) {
;                     const int tt = t8 + u;
;                     const unsigned char* tb = buf + tt * SC_TOKB + c0 * 4;
;                     const f32x4 a = *(const f32x4*)(tb), w = *(const f32x4*)(tb + 256), b = *(const f32x4*)(tb + 512), k = *(const f32x4*)(tb + 768), r = *(const f32x4*)(tb + 1024);
;                     const float v = *(const float*)(buf + tt * SC_TOKB + 1280 + rl * 4);
;                     const f32x2 a01 = (f32x2){a[0], a[1]}, a23 = (f32x2){a[2], a[3]}, w01 = (f32x2){w[0], w[1]}, w23 = (f32x2){w[2], w[3]}, b01 = (f32x2){b[0], b[1]}, b23 = (f32x2){b[2], b[3]};
;                     const f32x2 k01 = (f32x2){k[0], k[1]}, k23 = (f32x2){k[2], k[3]}, r01 = (f32x2){r[0], r[1]}, r23 = (f32x2){r[2], r[3]};
;                     const f32x2 pa = s01 * a01 + s23 * a23;
;                     const float sa = allsum16(pa.x + pa.y);
;                     const f32x2 kv01 = k01 * v, kv23 = k23 * v;
;                     s01 = s01 * w01 + (b01 * sa + kv01); s23 = s23 * w23 + (b23 * sa + kv23);
;                     const f32x2 py = s01 * r01 + s23 * r23;
;                     const float y = allsum16(py.x + py.y);
;                     if ((lane & 15) == (tt & 15)) yreg0 = y;
;                 }
;             }
	ds_read_b128 v[32:35], v217 offset:18816
	ds_read_b128 v[36:39], v217 offset:19072
	ds_read_b128 v[40:43], v217 offset:19328
	ds_read_b128 v[44:47], v217 offset:19584
	ds_read_b128 v[48:51], v217 offset:19840
	ds_read_b32 v92, v218 offset:18816
	v_pk_mul_f32 v[206:207], v[24:25], v[122:123]
	v_pk_mul_f32 v[208:209], v[24:25], v[204:205]
	v_pk_fma_f32 v[206:207], v[22:23], v[120:121], v[206:207]
	v_pk_fma_f32 v[208:209], v[22:23], v[202:203], v[208:209]
	v_pk_mul_f32 v[210:211], v[132:133], v[28:29] op_sel_hi:[1,0]
	v_add_f32_e32 v214, v206, v207
	v_add_f32_e32 v216, v208, v209
	v_pk_mul_f32 v[212:213], v[134:135], v[28:29] op_sel_hi:[1,0]
	v_add_f32_dpp v214, v214, v214 quad_perm:[1,0,3,2] row_mask:0xf bank_mask:0xf bound_ctrl:1
	v_add_f32_dpp v216, v216, v216 quad_perm:[1,0,3,2] row_mask:0xf bank_mask:0xf bound_ctrl:1
	v_pk_fma_f32 v[210:211], v[22:23], v[124:125], v[210:211]
	v_add_f32_dpp v214, v214, v214 quad_perm:[2,3,0,1] row_mask:0xf bank_mask:0xf bound_ctrl:1
	v_add_f32_dpp v216, v216, v216 quad_perm:[2,3,0,1] row_mask:0xf bank_mask:0xf bound_ctrl:1
	v_pk_fma_f32 v[212:213], v[24:25], v[126:127], v[212:213]
	v_add_f32_dpp v214, v214, v214 row_half_mirror row_mask:0xf bank_mask:0xf bound_ctrl:1
	v_add_f32_dpp v216, v216, v216 row_half_mirror row_mask:0xf bank_mask:0xf bound_ctrl:1
	v_cmp_eq_u32_e32 vcc, 11, v106
	v_add_f32_dpp v214, v214, v214 row_mirror row_mask:0xf bank_mask:0xf bound_ctrl:1
	v_add_f32_dpp v216, v216, v216 row_mirror row_mask:0xf bank_mask:0xf bound_ctrl:1
	v_pk_fma_f32 v[22:23], v[128:129], v[214:215], v[210:211] op_sel_hi:[1,0,1]
	v_pk_fma_f32 v[24:25], v[130:131], v[214:215], v[212:213] op_sel_hi:[1,0,1]
	v_cndmask_b32_e32 v18, v18, v216, vcc
	s_waitcnt lgkmcnt(6)
	ds_read_b128 v[186:189], v217 offset:20160
	ds_read_b128 v[190:193], v217 offset:20416
	ds_read_b128 v[194:197], v217 offset:20672
	ds_read_b128 v[198:201], v217 offset:20928
	ds_read_b128 v[202:205], v217 offset:21184
	ds_read_b32 v52, v218 offset:20160
	v_pk_mul_f32 v[206:207], v[24:25], v[148:149]
	v_pk_mul_f32 v[208:209], v[24:25], v[138:139]
	v_pk_fma_f32 v[206:207], v[22:23], v[146:147], v[206:207]
	v_pk_fma_f32 v[208:209], v[22:23], v[136:137], v[208:209]
	v_pk_mul_f32 v[210:211], v[158:159], v[30:31] op_sel_hi:[1,0]
	v_add_f32_e32 v214, v206, v207
	v_add_f32_e32 v216, v208, v209
	v_pk_mul_f32 v[212:213], v[160:161], v[30:31] op_sel_hi:[1,0]
	v_add_f32_dpp v214, v214, v214 quad_perm:[1,0,3,2] row_mask:0xf bank_mask:0xf bound_ctrl:1
	v_add_f32_dpp v216, v216, v216 quad_perm:[1,0,3,2] row_mask:0xf bank_mask:0xf bound_ctrl:1
	v_pk_fma_f32 v[210:211], v[22:23], v[150:151], v[210:211]
	v_add_f32_dpp v214, v214, v214 quad_perm:[2,3,0,1] row_mask:0xf bank_mask:0xf bound_ctrl:1
	v_add_f32_dpp v216, v216, v216 quad_perm:[2,3,0,1] row_mask:0xf bank_mask:0xf bound_ctrl:1
	v_pk_fma_f32 v[212:213], v[24:25], v[152:153], v[212:213]
	v_add_f32_dpp v214, v214, v214 row_half_mirror row_mask:0xf bank_mask:0xf bound_ctrl:1
	v_add_f32_dpp v216, v216, v216 row_half_mirror row_mask:0xf bank_mask:0xf bound_ctrl:1
	v_cmp_eq_u32_e32 vcc, 12, v106
	v_add_f32_dpp v214, v214, v214 row_mirror row_mask:0xf bank_mask:0xf bound_ctrl:1
	v_add_f32_dpp v216, v216, v216 row_mirror row_mask:0xf bank_mask:0xf bound_ctrl:1
	v_pk_fma_f32 v[22:23], v[154:155], v[214:215], v[210:211] op_sel_hi:[1,0,1]
	v_pk_fma_f32 v[24:25], v[156:157], v[214:215], v[212:213] op_sel_hi:[1,0,1]
	v_cndmask_b32_e32 v18, v18, v216, vcc
	s_waitcnt lgkmcnt(6)
	ds_read_b128 v[120:123], v217 offset:21504
	ds_read_b128 v[124:127], v217 offset:21760
	ds_read_b128 v[128:131], v217 offset:22016
	ds_read_b128 v[132:135], v217 offset:22272
	ds_read_b128 v[136:139], v217 offset:22528
	ds_read_b32 v28, v218 offset:21504
	v_pk_mul_f32 v[206:207], v[24:25], v[34:35]
	v_pk_mul_f32 v[208:209], v[24:25], v[164:165]
	v_pk_fma_f32 v[206:207], v[22:23], v[32:33], v[206:207]
	v_pk_fma_f32 v[208:209], v[22:23], v[162:163], v[208:209]
	v_pk_mul_f32 v[210:211], v[44:45], v[92:93] op_sel_hi:[1,0]
	v_add_f32_e32 v214, v206, v207
	v_add_f32_e32 v216, v208, v209
	v_pk_mul_f32 v[212:213], v[46:47], v[92:93] op_sel_hi:[1,0]
	v_add_f32_dpp v214, v214, v214 quad_perm:[1,0,3,2] row_mask:0xf bank_mask:0xf bound_ctrl:1
	v_add_f32_dpp v216, v216, v216 quad_perm:[1,0,3,2] row_mask:0xf bank_mask:0xf bound_ctrl:1
	v_pk_fma_f32 v[210:211], v[22:23], v[36:37], v[210:211]
	v_add_f32_dpp v214, v214, v214 quad_perm:[2,3,0,1] row_mask:0xf bank_mask:0xf bound_ctrl:1
	v_add_f32_dpp v216, v216, v216 quad_perm:[2,3,0,1] row_mask:0xf bank_mask:0xf bound_ctrl:1
	v_pk_fma_f32 v[212:213], v[24:25], v[38:39], v[212:213]
	v_add_f32_dpp v214, v214, v214 row_half_mirror row_mask:0xf bank_mask:0xf bound_ctrl:1
	v_add_f32_dpp v216, v216, v216 row_half_mirror row_mask:0xf bank_mask:0xf bound_ctrl:1
	v_cmp_eq_u32_e32 vcc, 13, v106
	v_add_f32_dpp v214, v214, v214 row_mirror row_mask:0xf bank_mask:0xf bound_ctrl:1
	v_add_f32_dpp v216, v216, v216 row_mirror row_mask:0xf bank_mask:0xf bound_ctrl:1
	v_pk_fma_f32 v[22:23], v[40:41], v[214:215], v[210:211] op_sel_hi:[1,0,1]
	v_pk_fma_f32 v[24:25], v[42:43], v[214:215], v[212:213] op_sel_hi:[1,0,1]
	v_cndmask_b32_e32 v18, v18, v216, vcc
	s_waitcnt lgkmcnt(6)
; __device__ void phase_scan(int l, unsigned char* lds) {
;     ...
;             for (int t8 = 0; t8 < (jb.nsteps < 16 ? jb.nsteps : 16); t8 += 4) {
; #pragma unroll
;                 for (int u = 0; u < 4; ++u) {
;                     const int tt = t8 + u;
;                     const unsigned char* tb = buf + tt * SC_TOKB + c0 * 4;
;                     const f32x4 a = *(const f32x4*)(tb), w = *(const f32x4*)(tb + 256), b = *(const f32x4*)(tb + 512), k = *(const f32x4*)(tb + 768), r = *(const f32x4*)(tb + 1024);
;                     const float v = *(const float*)(buf + tt * SC_TOKB + 1280 + rl * 4);
;                     const f32x2 a01 = (f32x2){a[0], a[1]}, a23 = (f32x2){a[2], a[3]}, w01 = (f32x2){w[0], w[1]}, w23 = (f32x2){w[2], w[3]}, b01 = (f32x2){b[0], b[1]}, b23 = (f32x2){b[2], b[3]};
;                     const f32x2 k01 = (f32x2){k[0], k[1]}, k23 = (f32x2){k[2], k[3]}, r01 = (f32x2){r[0], r[1]}, r23 = (f32x2){r[2], r[3]};
;                     const f32x2 pa = s01 * a01 + s23 * a23;
;                     const float sa = allsum16(pa.x + pa.y);
;                     const f32x2 kv01 = k01 * v, kv23 = k23 * v;
;                     s01 = s01 * w01 + (b01 * sa + kv01); s23 = s23 * w23 + (b23 * sa + kv23);
;                     const f32x2 py = s01 * r01 + s23 * r23;
;                     const float y = allsum16(py.x + py.y);
;                     if ((lane & 15) == (tt & 15)) yreg0 = y;
;                 }
;             }
;             for (int t8 = 16; t8 < (jb.nsteps < 32 ? jb.nsteps : 32); t8 += 4) {
; #pragma unroll
;                 for (int u = 0; u < 4; ++u) {
;                     const int tt = t8 + u;
;                     const unsigned char* tb = buf + tt * SC_TOKB + c0 * 4;
;                     const f32x4 a = *(const f32x4*)(tb), w = *(const f32x4*)(tb + 256), b = *(const f32x4*)(tb + 512), k = *(const f32x4*)(tb + 768), r = *(const f32x4*)(tb + 1024);
;                     const float v = *(const float*)(buf + tt * SC_TOKB + 1280 + rl * 4);
;                     const f32x2 a01 = (f32x2){a[0], a[1]}, a23 = (f32x2){a[2], a[3]}, w01 = (f32x2){w[0], w[1]}, w23 = (f32x2){w[2], w[3]}, b01 = (f32x2){b[0], b[1]}, b23 = (f32x2){b[2], b[3]};
;                     const f32x2 k01 = (f32x2){k[0], k[1]}, k23 = (f32x2){k[2], k[3]}, r01 = (f32x2){r[0], r[1]}, r23 = (f32x2){r[2], r[3]};
;                     const f32x2 pa = s01 * a01 + s23 * a23;
	ds_read_b128 v[146:149], v217 offset:22848
	ds_read_b128 v[150:153], v217 offset:23104
	ds_read_b128 v[154:157], v217 offset:23360
	ds_read_b128 v[158:161], v217 offset:23616
	ds_read_b128 v[162:165], v217 offset:23872
	ds_read_b32 v30, v218 offset:22848
	v_pk_mul_f32 v[206:207], v[24:25], v[188:189]
	v_pk_mul_f32 v[208:209], v[24:25], v[50:51]
	v_pk_fma_f32 v[206:207], v[22:23], v[186:187], v[206:207]
	v_pk_fma_f32 v[208:209], v[22:23], v[48:49], v[208:209]
	v_pk_mul_f32 v[210:211], v[198:199], v[52:53] op_sel_hi:[1,0]
	v_add_f32_e32 v214, v206, v207
	v_add_f32_e32 v216, v208, v209
	v_pk_mul_f32 v[212:213], v[200:201], v[52:53] op_sel_hi:[1,0]
	v_add_f32_dpp v214, v214, v214 quad_perm:[1,0,3,2] row_mask:0xf bank_mask:0xf bound_ctrl:1
	v_add_f32_dpp v216, v216, v216 quad_perm:[1,0,3,2] row_mask:0xf bank_mask:0xf bound_ctrl:1
	v_pk_fma_f32 v[210:211], v[22:23], v[190:191], v[210:211]
	v_add_f32_dpp v214, v214, v214 quad_perm:[2,3,0,1] row_mask:0xf bank_mask:0xf bound_ctrl:1
	v_add_f32_dpp v216, v216, v216 quad_perm:[2,3,0,1] row_mask:0xf bank_mask:0xf bound_ctrl:1
	v_pk_fma_f32 v[212:213], v[24:25], v[192:193], v[212:213]
	v_add_f32_dpp v214, v214, v214 row_half_mirror row_mask:0xf bank_mask:0xf bound_ctrl:1
	v_add_f32_dpp v216, v216, v216 row_half_mirror row_mask:0xf bank_mask:0xf bound_ctrl:1
	v_cmp_eq_u32_e32 vcc, 14, v106
	v_add_f32_dpp v214, v214, v214 row_mirror row_mask:0xf bank_mask:0xf bound_ctrl:1
	v_add_f32_dpp v216, v216, v216 row_mirror row_mask:0xf bank_mask:0xf bound_ctrl:1
	v_pk_fma_f32 v[22:23], v[194:195], v[214:215], v[210:211] op_sel_hi:[1,0,1]
	v_pk_fma_f32 v[24:25], v[196:197], v[214:215], v[212:213] op_sel_hi:[1,0,1]
	v_cndmask_b32_e32 v18, v18, v216, vcc
	s_waitcnt lgkmcnt(6)
	ds_read_b128 v[32:35], v217 offset:24192
	ds_read_b128 v[36:39], v217 offset:24448
	ds_read_b128 v[40:43], v217 offset:24704
	ds_read_b128 v[44:47], v217 offset:24960
	ds_read_b128 v[48:51], v217 offset:25216
	ds_read_b32 v92, v218 offset:24192
	v_pk_mul_f32 v[206:207], v[24:25], v[122:123]
	v_pk_mul_f32 v[208:209], v[24:25], v[204:205]
	v_pk_fma_f32 v[206:207], v[22:23], v[120:121], v[206:207]
	v_pk_fma_f32 v[208:209], v[22:23], v[202:203], v[208:209]
	v_pk_mul_f32 v[210:211], v[132:133], v[28:29] op_sel_hi:[1,0]
	v_add_f32_e32 v214, v206, v207
	v_add_f32_e32 v216, v208, v209
	v_pk_mul_f32 v[212:213], v[134:135], v[28:29] op_sel_hi:[1,0]
	v_add_f32_dpp v214, v214, v214 quad_perm:[1,0,3,2] row_mask:0xf bank_mask:0xf bound_ctrl:1
	v_add_f32_dpp v216, v216, v216 quad_perm:[1,0,3,2] row_mask:0xf bank_mask:0xf bound_ctrl:1
	v_pk_fma_f32 v[210:211], v[22:23], v[124:125], v[210:211]
	v_add_f32_dpp v214, v214, v214 quad_perm:[2,3,0,1] row_mask:0xf bank_mask:0xf bound_ctrl:1
	v_add_f32_dpp v216, v216, v216 quad_perm:[2,3,0,1] row_mask:0xf bank_mask:0xf bound_ctrl:1
	v_pk_fma_f32 v[212:213], v[24:25], v[126:127], v[212:213]
	v_add_f32_dpp v214, v214, v214 row_half_mirror row_mask:0xf bank_mask:0xf bound_ctrl:1
	v_add_f32_dpp v216, v216, v216 row_half_mirror row_mask:0xf bank_mask:0xf bound_ctrl:1
	v_cmp_eq_u32_e32 vcc, 15, v106
	v_add_f32_dpp v214, v214, v214 row_mirror row_mask:0xf bank_mask:0xf bound_ctrl:1
	v_add_f32_dpp v216, v216, v216 row_mirror row_mask:0xf bank_mask:0xf bound_ctrl:1
	v_pk_fma_f32 v[22:23], v[128:129], v[214:215], v[210:211] op_sel_hi:[1,0,1]
	v_pk_fma_f32 v[24:25], v[130:131], v[214:215], v[212:213] op_sel_hi:[1,0,1]
	v_cndmask_b32_e32 v18, v18, v216, vcc
	s_waitcnt lgkmcnt(6)
	ds_read_b128 v[186:189], v217 offset:25536
	ds_read_b128 v[190:193], v217 offset:25792
	ds_read_b128 v[194:197], v217 offset:26048
	ds_read_b128 v[198:201], v217 offset:26304
	ds_read_b128 v[202:205], v217 offset:26560
	ds_read_b32 v52, v218 offset:25536
	v_pk_mul_f32 v[206:207], v[24:25], v[148:149]
	v_pk_mul_f32 v[208:209], v[24:25], v[138:139]
	v_pk_fma_f32 v[206:207], v[22:23], v[146:147], v[206:207]
	v_pk_fma_f32 v[208:209], v[22:23], v[136:137], v[208:209]
	v_pk_mul_f32 v[210:211], v[158:159], v[30:31] op_sel_hi:[1,0]
	v_add_f32_e32 v214, v206, v207
	v_add_f32_e32 v216, v208, v209
	v_pk_mul_f32 v[212:213], v[160:161], v[30:31] op_sel_hi:[1,0]
	v_add_f32_dpp v214, v214, v214 quad_perm:[1,0,3,2] row_mask:0xf bank_mask:0xf bound_ctrl:1
	v_add_f32_dpp v216, v216, v216 quad_perm:[1,0,3,2] row_mask:0xf bank_mask:0xf bound_ctrl:1
	v_pk_fma_f32 v[210:211], v[22:23], v[150:151], v[210:211]
	v_add_f32_dpp v214, v214, v214 quad_perm:[2,3,0,1] row_mask:0xf bank_mask:0xf bound_ctrl:1
	v_add_f32_dpp v216, v216, v216 quad_perm:[2,3,0,1] row_mask:0xf bank_mask:0xf bound_ctrl:1
	v_pk_fma_f32 v[212:213], v[24:25], v[152:153], v[212:213]
	v_add_f32_dpp v214, v214, v214 row_half_mirror row_mask:0xf bank_mask:0xf bound_ctrl:1
	v_add_f32_dpp v216, v216, v216 row_half_mirror row_mask:0xf bank_mask:0xf bound_ctrl:1
	v_cmp_eq_u32_e32 vcc, 0, v106
	v_add_f32_dpp v214, v214, v214 row_mirror row_mask:0xf bank_mask:0xf bound_ctrl:1
	v_add_f32_dpp v216, v216, v216 row_mirror row_mask:0xf bank_mask:0xf bound_ctrl:1
	v_pk_fma_f32 v[22:23], v[154:155], v[214:215], v[210:211] op_sel_hi:[1,0,1]
	v_pk_fma_f32 v[24:25], v[156:157], v[214:215], v[212:213] op_sel_hi:[1,0,1]
	v_cndmask_b32_e32 v26, v26, v216, vcc
	s_waitcnt lgkmcnt(6)
; __device__ void phase_scan(int l, unsigned char* lds) {
;     ...
;             for (int t8 = 16; t8 < (jb.nsteps < 32 ? jb.nsteps : 32); t8 += 4) {
; #pragma unroll
;                 for (int u = 0; u < 4; ++u) {
;                     const int tt = t8 + u;
;                     const unsigned char* tb = buf + tt * SC_TOKB + c0 * 4;
;                     const f32x4 a = *(const f32x4*)(tb), w = *(const f32x4*)(tb + 256), b = *(const f32x4*)(tb + 512), k = *(const f32x4*)(tb + 768), r = *(const f32x4*)(tb + 1024);
;                     const float v = *(const float*)(buf + tt * SC_TOKB + 1280 + rl * 4);
;                     const f32x2 a01 = (f32x2){a[0], a[1]}, a23 = (f32x2){a[2], a[3]}, w01 = (f32x2){w[0], w[1]}, w23 = (f32x2){w[2], w[3]}, b01 = (f32x2){b[0], b[1]}, b23 = (f32x2){b[2], b[3]};
;                     const f32x2 k01 = (f32x2){k[0], k[1]}, k23 = (f32x2){k[2], k[3]}, r01 = (f32x2){r[0], r[1]}, r23 = (f32x2){r[2], r[3]};
;                     const f32x2 pa = s01 * a01 + s23 * a23;
;                     const float sa = allsum16(pa.x + pa.y);
;                     const f32x2 kv01 = k01 * v, kv23 = k23 * v;
;                     s01 = s01 * w01 + (b01 * sa + kv01); s23 = s23 * w23 + (b23 * sa + kv23);
;                     const f32x2 py = s01 * r01 + s23 * r23;
;                     const float y = allsum16(py.x + py.y);
;                     if ((lane & 15) == (tt & 15)) yreg1 = y;
;                 }
;             }
	ds_read_b128 v[120:123], v217 offset:26880
	ds_read_b128 v[124:127], v217 offset:27136
	ds_read_b128 v[128:131], v217 offset:27392
	ds_read_b128 v[132:135], v217 offset:27648
	ds_read_b128 v[136:139], v217 offset:27904
	ds_read_b32 v28, v218 offset:26880
	v_pk_mul_f32 v[206:207], v[24:25], v[34:35]
	v_pk_mul_f32 v[208:209], v[24:25], v[164:165]
	v_pk_fma_f32 v[206:207], v[22:23], v[32:33], v[206:207]
	v_pk_fma_f32 v[208:209], v[22:23], v[162:163], v[208:209]
	v_pk_mul_f32 v[210:211], v[44:45], v[92:93] op_sel_hi:[1,0]
	v_add_f32_e32 v214, v206, v207
	v_add_f32_e32 v216, v208, v209
	v_pk_mul_f32 v[212:213], v[46:47], v[92:93] op_sel_hi:[1,0]
	v_add_f32_dpp v214, v214, v214 quad_perm:[1,0,3,2] row_mask:0xf bank_mask:0xf bound_ctrl:1
	v_add_f32_dpp v216, v216, v216 quad_perm:[1,0,3,2] row_mask:0xf bank_mask:0xf bound_ctrl:1
	v_pk_fma_f32 v[210:211], v[22:23], v[36:37], v[210:211]
	v_add_f32_dpp v214, v214, v214 quad_perm:[2,3,0,1] row_mask:0xf bank_mask:0xf bound_ctrl:1
	v_add_f32_dpp v216, v216, v216 quad_perm:[2,3,0,1] row_mask:0xf bank_mask:0xf bound_ctrl:1
	v_pk_fma_f32 v[212:213], v[24:25], v[38:39], v[212:213]
	v_add_f32_dpp v214, v214, v214 row_half_mirror row_mask:0xf bank_mask:0xf bound_ctrl:1
	v_add_f32_dpp v216, v216, v216 row_half_mirror row_mask:0xf bank_mask:0xf bound_ctrl:1
	v_cmp_eq_u32_e32 vcc, 1, v106
	v_add_f32_dpp v214, v214, v214 row_mirror row_mask:0xf bank_mask:0xf bound_ctrl:1
	v_add_f32_dpp v216, v216, v216 row_mirror row_mask:0xf bank_mask:0xf bound_ctrl:1
	v_pk_fma_f32 v[22:23], v[40:41], v[214:215], v[210:211] op_sel_hi:[1,0,1]
	v_pk_fma_f32 v[24:25], v[42:43], v[214:215], v[212:213] op_sel_hi:[1,0,1]
	v_cndmask_b32_e32 v26, v26, v216, vcc
	s_waitcnt lgkmcnt(6)
	ds_read_b128 v[146:149], v217 offset:28224
	ds_read_b128 v[150:153], v217 offset:28480
	ds_read_b128 v[154:157], v217 offset:28736
	ds_read_b128 v[158:161], v217 offset:28992
	ds_read_b128 v[162:165], v217 offset:29248
	ds_read_b32 v30, v218 offset:28224
	v_pk_mul_f32 v[206:207], v[24:25], v[188:189]
	v_pk_mul_f32 v[208:209], v[24:25], v[50:51]
	v_pk_fma_f32 v[206:207], v[22:23], v[186:187], v[206:207]
	v_pk_fma_f32 v[208:209], v[22:23], v[48:49], v[208:209]
	v_pk_mul_f32 v[210:211], v[198:199], v[52:53] op_sel_hi:[1,0]
	v_add_f32_e32 v214, v206, v207
	v_add_f32_e32 v216, v208, v209
	v_pk_mul_f32 v[212:213], v[200:201], v[52:53] op_sel_hi:[1,0]
	v_add_f32_dpp v214, v214, v214 quad_perm:[1,0,3,2] row_mask:0xf bank_mask:0xf bound_ctrl:1
	v_add_f32_dpp v216, v216, v216 quad_perm:[1,0,3,2] row_mask:0xf bank_mask:0xf bound_ctrl:1
	v_pk_fma_f32 v[210:211], v[22:23], v[190:191], v[210:211]
	v_add_f32_dpp v214, v214, v214 quad_perm:[2,3,0,1] row_mask:0xf bank_mask:0xf bound_ctrl:1
	v_add_f32_dpp v216, v216, v216 quad_perm:[2,3,0,1] row_mask:0xf bank_mask:0xf bound_ctrl:1
	v_pk_fma_f32 v[212:213], v[24:25], v[192:193], v[212:213]
	v_add_f32_dpp v214, v214, v214 row_half_mirror row_mask:0xf bank_mask:0xf bound_ctrl:1
	v_add_f32_dpp v216, v216, v216 row_half_mirror row_mask:0xf bank_mask:0xf bound_ctrl:1
	v_cmp_eq_u32_e32 vcc, 2, v106
	v_add_f32_dpp v214, v214, v214 row_mirror row_mask:0xf bank_mask:0xf bound_ctrl:1
	v_add_f32_dpp v216, v216, v216 row_mirror row_mask:0xf bank_mask:0xf bound_ctrl:1
	v_pk_fma_f32 v[22:23], v[194:195], v[214:215], v[210:211] op_sel_hi:[1,0,1]
	v_pk_fma_f32 v[24:25], v[196:197], v[214:215], v[212:213] op_sel_hi:[1,0,1]
	v_cndmask_b32_e32 v26, v26, v216, vcc
	s_waitcnt lgkmcnt(6)
	ds_read_b128 v[32:35], v217 offset:29568
	ds_read_b128 v[36:39], v217 offset:29824
	ds_read_b128 v[40:43], v217 offset:30080
	ds_read_b128 v[44:47], v217 offset:30336
	ds_read_b128 v[48:51], v217 offset:30592
	ds_read_b32 v92, v218 offset:29568
	v_pk_mul_f32 v[206:207], v[24:25], v[122:123]
	v_pk_mul_f32 v[208:209], v[24:25], v[204:205]
	v_pk_fma_f32 v[206:207], v[22:23], v[120:121], v[206:207]
	v_pk_fma_f32 v[208:209], v[22:23], v[202:203], v[208:209]
	v_pk_mul_f32 v[210:211], v[132:133], v[28:29] op_sel_hi:[1,0]
	v_add_f32_e32 v214, v206, v207
	v_add_f32_e32 v216, v208, v209
	v_pk_mul_f32 v[212:213], v[134:135], v[28:29] op_sel_hi:[1,0]
	v_add_f32_dpp v214, v214, v214 quad_perm:[1,0,3,2] row_mask:0xf bank_mask:0xf bound_ctrl:1
	v_add_f32_dpp v216, v216, v216 quad_perm:[1,0,3,2] row_mask:0xf bank_mask:0xf bound_ctrl:1
	v_pk_fma_f32 v[210:211], v[22:23], v[124:125], v[210:211]
	v_add_f32_dpp v214, v214, v214 quad_perm:[2,3,0,1] row_mask:0xf bank_mask:0xf bound_ctrl:1
	v_add_f32_dpp v216, v216, v216 quad_perm:[2,3,0,1] row_mask:0xf bank_mask:0xf bound_ctrl:1
	v_pk_fma_f32 v[212:213], v[24:25], v[126:127], v[212:213]
	v_add_f32_dpp v214, v214, v214 row_half_mirror row_mask:0xf bank_mask:0xf bound_ctrl:1
	v_add_f32_dpp v216, v216, v216 row_half_mirror row_mask:0xf bank_mask:0xf bound_ctrl:1
	v_cmp_eq_u32_e32 vcc, 3, v106
	v_add_f32_dpp v214, v214, v214 row_mirror row_mask:0xf bank_mask:0xf bound_ctrl:1
	v_add_f32_dpp v216, v216, v216 row_mirror row_mask:0xf bank_mask:0xf bound_ctrl:1
	v_pk_fma_f32 v[22:23], v[128:129], v[214:215], v[210:211] op_sel_hi:[1,0,1]
	v_pk_fma_f32 v[24:25], v[130:131], v[214:215], v[212:213] op_sel_hi:[1,0,1]
	v_cndmask_b32_e32 v26, v26, v216, vcc
	s_waitcnt lgkmcnt(6)
; __device__ void phase_scan(int l, unsigned char* lds) {
;     ...
;             for (int t8 = 16; t8 < (jb.nsteps < 32 ? jb.nsteps : 32); t8 += 4) {
; #pragma unroll
;                 for (int u = 0; u < 4; ++u) {
;                     const int tt = t8 + u;
;                     const unsigned char* tb = buf + tt * SC_TOKB + c0 * 4;
;                     const f32x4 a = *(const f32x4*)(tb), w = *(const f32x4*)(tb + 256), b = *(const f32x4*)(tb + 512), k = *(const f32x4*)(tb + 768), r = *(const f32x4*)(tb + 1024);
;                     const float v = *(const float*)(buf + tt * SC_TOKB + 1280 + rl * 4);
;                     const f32x2 a01 = (f32x2){a[0], a[1]}, a23 = (f32x2){a[2], a[3]}, w01 = (f32x2){w[0], w[1]}, w23 = (f32x2){w[2], w[3]}, b01 = (f32x2){b[0], b[1]}, b23 = (f32x2){b[2], b[3]};
;                     const f32x2 k01 = (f32x2){k[0], k[1]}, k23 = (f32x2){k[2], k[3]}, r01 = (f32x2){r[0], r[1]}, r23 = (f32x2){r[2], r[3]};
;                     const f32x2 pa = s01 * a01 + s23 * a23;
;                     const float sa = allsum16(pa.x + pa.y);
;                     const f32x2 kv01 = k01 * v, kv23 = k23 * v;
;                     s01 = s01 * w01 + (b01 * sa + kv01); s23 = s23 * w23 + (b23 * sa + kv23);
;                     const f32x2 py = s01 * r01 + s23 * r23;
;                     const float y = allsum16(py.x + py.y);
;                     if ((lane & 15) == (tt & 15)) yreg1 = y;
;                 }
;             }
	ds_read_b128 v[186:189], v217 offset:30912
	ds_read_b128 v[190:193], v217 offset:31168
	ds_read_b128 v[194:197], v217 offset:31424
	ds_read_b128 v[198:201], v217 offset:31680
	ds_read_b128 v[202:205], v217 offset:31936
	ds_read_b32 v52, v218 offset:30912
	v_pk_mul_f32 v[206:207], v[24:25], v[148:149]
	v_pk_mul_f32 v[208:209], v[24:25], v[138:139]
	v_pk_fma_f32 v[206:207], v[22:23], v[146:147], v[206:207]
	v_pk_fma_f32 v[208:209], v[22:23], v[136:137], v[208:209]
	v_pk_mul_f32 v[210:211], v[158:159], v[30:31] op_sel_hi:[1,0]
	v_add_f32_e32 v214, v206, v207
	v_add_f32_e32 v216, v208, v209
	v_pk_mul_f32 v[212:213], v[160:161], v[30:31] op_sel_hi:[1,0]
	v_add_f32_dpp v214, v214, v214 quad_perm:[1,0,3,2] row_mask:0xf bank_mask:0xf bound_ctrl:1
	v_add_f32_dpp v216, v216, v216 quad_perm:[1,0,3,2] row_mask:0xf bank_mask:0xf bound_ctrl:1
	v_pk_fma_f32 v[210:211], v[22:23], v[150:151], v[210:211]
	v_add_f32_dpp v214, v214, v214 quad_perm:[2,3,0,1] row_mask:0xf bank_mask:0xf bound_ctrl:1
	v_add_f32_dpp v216, v216, v216 quad_perm:[2,3,0,1] row_mask:0xf bank_mask:0xf bound_ctrl:1
	v_pk_fma_f32 v[212:213], v[24:25], v[152:153], v[212:213]
	v_add_f32_dpp v214, v214, v214 row_half_mirror row_mask:0xf bank_mask:0xf bound_ctrl:1
	v_add_f32_dpp v216, v216, v216 row_half_mirror row_mask:0xf bank_mask:0xf bound_ctrl:1
	v_cmp_eq_u32_e32 vcc, 4, v106
	v_add_f32_dpp v214, v214, v214 row_mirror row_mask:0xf bank_mask:0xf bound_ctrl:1
	v_add_f32_dpp v216, v216, v216 row_mirror row_mask:0xf bank_mask:0xf bound_ctrl:1
	v_pk_fma_f32 v[22:23], v[154:155], v[214:215], v[210:211] op_sel_hi:[1,0,1]
	v_pk_fma_f32 v[24:25], v[156:157], v[214:215], v[212:213] op_sel_hi:[1,0,1]
	v_cndmask_b32_e32 v26, v26, v216, vcc
	s_waitcnt lgkmcnt(6)
	ds_read_b128 v[120:123], v217 offset:32256
	ds_read_b128 v[124:127], v217 offset:32512
	ds_read_b128 v[128:131], v217 offset:32768
	ds_read_b128 v[132:135], v217 offset:33024
	ds_read_b128 v[136:139], v217 offset:33280
	ds_read_b32 v28, v218 offset:32256
	v_pk_mul_f32 v[206:207], v[24:25], v[34:35]
	v_pk_mul_f32 v[208:209], v[24:25], v[164:165]
	v_pk_fma_f32 v[206:207], v[22:23], v[32:33], v[206:207]
	v_pk_fma_f32 v[208:209], v[22:23], v[162:163], v[208:209]
	v_pk_mul_f32 v[210:211], v[44:45], v[92:93] op_sel_hi:[1,0]
	v_add_f32_e32 v214, v206, v207
	v_add_f32_e32 v216, v208, v209
	v_pk_mul_f32 v[212:213], v[46:47], v[92:93] op_sel_hi:[1,0]
	v_add_f32_dpp v214, v214, v214 quad_perm:[1,0,3,2] row_mask:0xf bank_mask:0xf bound_ctrl:1
	v_add_f32_dpp v216, v216, v216 quad_perm:[1,0,3,2] row_mask:0xf bank_mask:0xf bound_ctrl:1
	v_pk_fma_f32 v[210:211], v[22:23], v[36:37], v[210:211]
	v_add_f32_dpp v214, v214, v214 quad_perm:[2,3,0,1] row_mask:0xf bank_mask:0xf bound_ctrl:1
	v_add_f32_dpp v216, v216, v216 quad_perm:[2,3,0,1] row_mask:0xf bank_mask:0xf bound_ctrl:1
	v_pk_fma_f32 v[212:213], v[24:25], v[38:39], v[212:213]
	v_add_f32_dpp v214, v214, v214 row_half_mirror row_mask:0xf bank_mask:0xf bound_ctrl:1
	v_add_f32_dpp v216, v216, v216 row_half_mirror row_mask:0xf bank_mask:0xf bound_ctrl:1
	v_cmp_eq_u32_e32 vcc, 5, v106
	v_add_f32_dpp v214, v214, v214 row_mirror row_mask:0xf bank_mask:0xf bound_ctrl:1
	v_add_f32_dpp v216, v216, v216 row_mirror row_mask:0xf bank_mask:0xf bound_ctrl:1
	v_pk_fma_f32 v[22:23], v[40:41], v[214:215], v[210:211] op_sel_hi:[1,0,1]
	v_pk_fma_f32 v[24:25], v[42:43], v[214:215], v[212:213] op_sel_hi:[1,0,1]
	v_cndmask_b32_e32 v26, v26, v216, vcc
	s_waitcnt lgkmcnt(6)
	ds_read_b128 v[146:149], v217 offset:33600
	ds_read_b128 v[150:153], v217 offset:33856
	ds_read_b128 v[154:157], v217 offset:34112
	ds_read_b128 v[158:161], v217 offset:34368
	ds_read_b128 v[162:165], v217 offset:34624
	ds_read_b32 v30, v218 offset:33600
	v_pk_mul_f32 v[206:207], v[24:25], v[188:189]
	v_pk_mul_f32 v[208:209], v[24:25], v[50:51]
	v_pk_fma_f32 v[206:207], v[22:23], v[186:187], v[206:207]
	v_pk_fma_f32 v[208:209], v[22:23], v[48:49], v[208:209]
	v_pk_mul_f32 v[210:211], v[198:199], v[52:53] op_sel_hi:[1,0]
	v_add_f32_e32 v214, v206, v207
	v_add_f32_e32 v216, v208, v209
	v_pk_mul_f32 v[212:213], v[200:201], v[52:53] op_sel_hi:[1,0]
	v_add_f32_dpp v214, v214, v214 quad_perm:[1,0,3,2] row_mask:0xf bank_mask:0xf bound_ctrl:1
	v_add_f32_dpp v216, v216, v216 quad_perm:[1,0,3,2] row_mask:0xf bank_mask:0xf bound_ctrl:1
	v_pk_fma_f32 v[210:211], v[22:23], v[190:191], v[210:211]
	v_add_f32_dpp v214, v214, v214 quad_perm:[2,3,0,1] row_mask:0xf bank_mask:0xf bound_ctrl:1
	v_add_f32_dpp v216, v216, v216 quad_perm:[2,3,0,1] row_mask:0xf bank_mask:0xf bound_ctrl:1
	v_pk_fma_f32 v[212:213], v[24:25], v[192:193], v[212:213]
	v_add_f32_dpp v214, v214, v214 row_half_mirror row_mask:0xf bank_mask:0xf bound_ctrl:1
	v_add_f32_dpp v216, v216, v216 row_half_mirror row_mask:0xf bank_mask:0xf bound_ctrl:1
	v_cmp_eq_u32_e32 vcc, 6, v106
	v_add_f32_dpp v214, v214, v214 row_mirror row_mask:0xf bank_mask:0xf bound_ctrl:1
	v_add_f32_dpp v216, v216, v216 row_mirror row_mask:0xf bank_mask:0xf bound_ctrl:1
	v_pk_fma_f32 v[22:23], v[194:195], v[214:215], v[210:211] op_sel_hi:[1,0,1]
	v_pk_fma_f32 v[24:25], v[196:197], v[214:215], v[212:213] op_sel_hi:[1,0,1]
	v_cndmask_b32_e32 v26, v26, v216, vcc
	s_waitcnt lgkmcnt(6)
; __device__ void phase_scan(int l, unsigned char* lds) {
;     ...
;             for (int t8 = 16; t8 < (jb.nsteps < 32 ? jb.nsteps : 32); t8 += 4) {
; #pragma unroll
;                 for (int u = 0; u < 4; ++u) {
;                     const int tt = t8 + u;
;                     const unsigned char* tb = buf + tt * SC_TOKB + c0 * 4;
;                     const f32x4 a = *(const f32x4*)(tb), w = *(const f32x4*)(tb + 256), b = *(const f32x4*)(tb + 512), k = *(const f32x4*)(tb + 768), r = *(const f32x4*)(tb + 1024);
;                     const float v = *(const float*)(buf + tt * SC_TOKB + 1280 + rl * 4);
;                     const f32x2 a01 = (f32x2){a[0], a[1]}, a23 = (f32x2){a[2], a[3]}, w01 = (f32x2){w[0], w[1]}, w23 = (f32x2){w[2], w[3]}, b01 = (f32x2){b[0], b[1]}, b23 = (f32x2){b[2], b[3]};
;                     const f32x2 k01 = (f32x2){k[0], k[1]}, k23 = (f32x2){k[2], k[3]}, r01 = (f32x2){r[0], r[1]}, r23 = (f32x2){r[2], r[3]};
;                     const f32x2 pa = s01 * a01 + s23 * a23;
;                     const float sa = allsum16(pa.x + pa.y);
;                     const f32x2 kv01 = k01 * v, kv23 = k23 * v;
;                     s01 = s01 * w01 + (b01 * sa + kv01); s23 = s23 * w23 + (b23 * sa + kv23);
;                     const f32x2 py = s01 * r01 + s23 * r23;
;                     const float y = allsum16(py.x + py.y);
;                     if ((lane & 15) == (tt & 15)) yreg1 = y;
;                 }
;             }
	ds_read_b128 v[32:35], v217 offset:34944
	ds_read_b128 v[36:39], v217 offset:35200
	ds_read_b128 v[40:43], v217 offset:35456
	ds_read_b128 v[44:47], v217 offset:35712
	ds_read_b128 v[48:51], v217 offset:35968
	ds_read_b32 v92, v218 offset:34944
	v_pk_mul_f32 v[206:207], v[24:25], v[122:123]
	v_pk_mul_f32 v[208:209], v[24:25], v[204:205]
	v_pk_fma_f32 v[206:207], v[22:23], v[120:121], v[206:207]
	v_pk_fma_f32 v[208:209], v[22:23], v[202:203], v[208:209]
	v_pk_mul_f32 v[210:211], v[132:133], v[28:29] op_sel_hi:[1,0]
	v_add_f32_e32 v214, v206, v207
	v_add_f32_e32 v216, v208, v209
	v_pk_mul_f32 v[212:213], v[134:135], v[28:29] op_sel_hi:[1,0]
	v_add_f32_dpp v214, v214, v214 quad_perm:[1,0,3,2] row_mask:0xf bank_mask:0xf bound_ctrl:1
	v_add_f32_dpp v216, v216, v216 quad_perm:[1,0,3,2] row_mask:0xf bank_mask:0xf bound_ctrl:1
	v_pk_fma_f32 v[210:211], v[22:23], v[124:125], v[210:211]
	v_add_f32_dpp v214, v214, v214 quad_perm:[2,3,0,1] row_mask:0xf bank_mask:0xf bound_ctrl:1
	v_add_f32_dpp v216, v216, v216 quad_perm:[2,3,0,1] row_mask:0xf bank_mask:0xf bound_ctrl:1
	v_pk_fma_f32 v[212:213], v[24:25], v[126:127], v[212:213]
	v_add_f32_dpp v214, v214, v214 row_half_mirror row_mask:0xf bank_mask:0xf bound_ctrl:1
	v_add_f32_dpp v216, v216, v216 row_half_mirror row_mask:0xf bank_mask:0xf bound_ctrl:1
	v_cmp_eq_u32_e32 vcc, 7, v106
	v_add_f32_dpp v214, v214, v214 row_mirror row_mask:0xf bank_mask:0xf bound_ctrl:1
	v_add_f32_dpp v216, v216, v216 row_mirror row_mask:0xf bank_mask:0xf bound_ctrl:1
	v_pk_fma_f32 v[22:23], v[128:129], v[214:215], v[210:211] op_sel_hi:[1,0,1]
	v_pk_fma_f32 v[24:25], v[130:131], v[214:215], v[212:213] op_sel_hi:[1,0,1]
	v_cndmask_b32_e32 v26, v26, v216, vcc
	s_waitcnt lgkmcnt(6)
	ds_read_b128 v[186:189], v217 offset:36288
	ds_read_b128 v[190:193], v217 offset:36544
	ds_read_b128 v[194:197], v217 offset:36800
	ds_read_b128 v[198:201], v217 offset:37056
	ds_read_b128 v[202:205], v217 offset:37312
	ds_read_b32 v52, v218 offset:36288
	v_pk_mul_f32 v[206:207], v[24:25], v[148:149]
	v_pk_mul_f32 v[208:209], v[24:25], v[138:139]
	v_pk_fma_f32 v[206:207], v[22:23], v[146:147], v[206:207]
	v_pk_fma_f32 v[208:209], v[22:23], v[136:137], v[208:209]
	v_pk_mul_f32 v[210:211], v[158:159], v[30:31] op_sel_hi:[1,0]
	v_add_f32_e32 v214, v206, v207
	v_add_f32_e32 v216, v208, v209
	v_pk_mul_f32 v[212:213], v[160:161], v[30:31] op_sel_hi:[1,0]
	v_add_f32_dpp v214, v214, v214 quad_perm:[1,0,3,2] row_mask:0xf bank_mask:0xf bound_ctrl:1
	v_add_f32_dpp v216, v216, v216 quad_perm:[1,0,3,2] row_mask:0xf bank_mask:0xf bound_ctrl:1
	v_pk_fma_f32 v[210:211], v[22:23], v[150:151], v[210:211]
	v_add_f32_dpp v214, v214, v214 quad_perm:[2,3,0,1] row_mask:0xf bank_mask:0xf bound_ctrl:1
	v_add_f32_dpp v216, v216, v216 quad_perm:[2,3,0,1] row_mask:0xf bank_mask:0xf bound_ctrl:1
	v_pk_fma_f32 v[212:213], v[24:25], v[152:153], v[212:213]
	v_add_f32_dpp v214, v214, v214 row_half_mirror row_mask:0xf bank_mask:0xf bound_ctrl:1
	v_add_f32_dpp v216, v216, v216 row_half_mirror row_mask:0xf bank_mask:0xf bound_ctrl:1
	v_cmp_eq_u32_e32 vcc, 8, v106
	v_add_f32_dpp v214, v214, v214 row_mirror row_mask:0xf bank_mask:0xf bound_ctrl:1
	v_add_f32_dpp v216, v216, v216 row_mirror row_mask:0xf bank_mask:0xf bound_ctrl:1
	v_pk_fma_f32 v[22:23], v[154:155], v[214:215], v[210:211] op_sel_hi:[1,0,1]
	v_pk_fma_f32 v[24:25], v[156:157], v[214:215], v[212:213] op_sel_hi:[1,0,1]
	v_cndmask_b32_e32 v26, v26, v216, vcc
	s_waitcnt lgkmcnt(6)
	ds_read_b128 v[120:123], v217 offset:37632
	ds_read_b128 v[124:127], v217 offset:37888
	ds_read_b128 v[128:131], v217 offset:38144
	ds_read_b128 v[132:135], v217 offset:38400
	ds_read_b128 v[136:139], v217 offset:38656
	ds_read_b32 v28, v218 offset:37632
	v_pk_mul_f32 v[206:207], v[24:25], v[34:35]
	v_pk_mul_f32 v[208:209], v[24:25], v[164:165]
	v_pk_fma_f32 v[206:207], v[22:23], v[32:33], v[206:207]
	v_pk_fma_f32 v[208:209], v[22:23], v[162:163], v[208:209]
	v_pk_mul_f32 v[210:211], v[44:45], v[92:93] op_sel_hi:[1,0]
	v_add_f32_e32 v214, v206, v207
	v_add_f32_e32 v216, v208, v209
	v_pk_mul_f32 v[212:213], v[46:47], v[92:93] op_sel_hi:[1,0]
	v_add_f32_dpp v214, v214, v214 quad_perm:[1,0,3,2] row_mask:0xf bank_mask:0xf bound_ctrl:1
	v_add_f32_dpp v216, v216, v216 quad_perm:[1,0,3,2] row_mask:0xf bank_mask:0xf bound_ctrl:1
	v_pk_fma_f32 v[210:211], v[22:23], v[36:37], v[210:211]
	v_add_f32_dpp v214, v214, v214 quad_perm:[2,3,0,1] row_mask:0xf bank_mask:0xf bound_ctrl:1
	v_add_f32_dpp v216, v216, v216 quad_perm:[2,3,0,1] row_mask:0xf bank_mask:0xf bound_ctrl:1
	v_pk_fma_f32 v[212:213], v[24:25], v[38:39], v[212:213]
	v_add_f32_dpp v214, v214, v214 row_half_mirror row_mask:0xf bank_mask:0xf bound_ctrl:1
	v_add_f32_dpp v216, v216, v216 row_half_mirror row_mask:0xf bank_mask:0xf bound_ctrl:1
	v_cmp_eq_u32_e32 vcc, 9, v106
	v_add_f32_dpp v214, v214, v214 row_mirror row_mask:0xf bank_mask:0xf bound_ctrl:1
	v_add_f32_dpp v216, v216, v216 row_mirror row_mask:0xf bank_mask:0xf bound_ctrl:1
	v_pk_fma_f32 v[22:23], v[40:41], v[214:215], v[210:211] op_sel_hi:[1,0,1]
	v_pk_fma_f32 v[24:25], v[42:43], v[214:215], v[212:213] op_sel_hi:[1,0,1]
	v_cndmask_b32_e32 v26, v26, v216, vcc
	s_waitcnt lgkmcnt(6)
; __device__ void phase_scan(int l, unsigned char* lds) {
;     ...
;             for (int t8 = 16; t8 < (jb.nsteps < 32 ? jb.nsteps : 32); t8 += 4) {
; #pragma unroll
;                 for (int u = 0; u < 4; ++u) {
;                     const int tt = t8 + u;
;                     const unsigned char* tb = buf + tt * SC_TOKB + c0 * 4;
;                     const f32x4 a = *(const f32x4*)(tb), w = *(const f32x4*)(tb + 256), b = *(const f32x4*)(tb + 512), k = *(const f32x4*)(tb + 768), r = *(const f32x4*)(tb + 1024);
;                     const float v = *(const float*)(buf + tt * SC_TOKB + 1280 + rl * 4);
;                     const f32x2 a01 = (f32x2){a[0], a[1]}, a23 = (f32x2){a[2], a[3]}, w01 = (f32x2){w[0], w[1]}, w23 = (f32x2){w[2], w[3]}, b01 = (f32x2){b[0], b[1]}, b23 = (f32x2){b[2], b[3]};
;                     const f32x2 k01 = (f32x2){k[0], k[1]}, k23 = (f32x2){k[2], k[3]}, r01 = (f32x2){r[0], r[1]}, r23 = (f32x2){r[2], r[3]};
;                     const f32x2 pa = s01 * a01 + s23 * a23;
;                     const float sa = allsum16(pa.x + pa.y);
;                     const f32x2 kv01 = k01 * v, kv23 = k23 * v;
;                     s01 = s01 * w01 + (b01 * sa + kv01); s23 = s23 * w23 + (b23 * sa + kv23);
;                     const f32x2 py = s01 * r01 + s23 * r23;
;                     const float y = allsum16(py.x + py.y);
;                     if ((lane & 15) == (tt & 15)) yreg1 = y;
;                 }
;             }
	ds_read_b128 v[146:149], v217 offset:38976
	ds_read_b128 v[150:153], v217 offset:39232
	ds_read_b128 v[154:157], v217 offset:39488
	ds_read_b128 v[158:161], v217 offset:39744
	ds_read_b128 v[162:165], v217 offset:40000
	ds_read_b32 v30, v218 offset:38976
	v_pk_mul_f32 v[206:207], v[24:25], v[188:189]
	v_pk_mul_f32 v[208:209], v[24:25], v[50:51]
	v_pk_fma_f32 v[206:207], v[22:23], v[186:187], v[206:207]
	v_pk_fma_f32 v[208:209], v[22:23], v[48:49], v[208:209]
	v_pk_mul_f32 v[210:211], v[198:199], v[52:53] op_sel_hi:[1,0]
	v_add_f32_e32 v214, v206, v207
	v_add_f32_e32 v216, v208, v209
	v_pk_mul_f32 v[212:213], v[200:201], v[52:53] op_sel_hi:[1,0]
	v_add_f32_dpp v214, v214, v214 quad_perm:[1,0,3,2] row_mask:0xf bank_mask:0xf bound_ctrl:1
	v_add_f32_dpp v216, v216, v216 quad_perm:[1,0,3,2] row_mask:0xf bank_mask:0xf bound_ctrl:1
	v_pk_fma_f32 v[210:211], v[22:23], v[190:191], v[210:211]
	v_add_f32_dpp v214, v214, v214 quad_perm:[2,3,0,1] row_mask:0xf bank_mask:0xf bound_ctrl:1
	v_add_f32_dpp v216, v216, v216 quad_perm:[2,3,0,1] row_mask:0xf bank_mask:0xf bound_ctrl:1
	v_pk_fma_f32 v[212:213], v[24:25], v[192:193], v[212:213]
	v_add_f32_dpp v214, v214, v214 row_half_mirror row_mask:0xf bank_mask:0xf bound_ctrl:1
	v_add_f32_dpp v216, v216, v216 row_half_mirror row_mask:0xf bank_mask:0xf bound_ctrl:1
	v_cmp_eq_u32_e32 vcc, 10, v106
	v_add_f32_dpp v214, v214, v214 row_mirror row_mask:0xf bank_mask:0xf bound_ctrl:1
	v_add_f32_dpp v216, v216, v216 row_mirror row_mask:0xf bank_mask:0xf bound_ctrl:1
	v_pk_fma_f32 v[22:23], v[194:195], v[214:215], v[210:211] op_sel_hi:[1,0,1]
	v_pk_fma_f32 v[24:25], v[196:197], v[214:215], v[212:213] op_sel_hi:[1,0,1]
	v_cndmask_b32_e32 v26, v26, v216, vcc
	s_waitcnt lgkmcnt(6)
	ds_read_b128 v[32:35], v217 offset:40320
	ds_read_b128 v[36:39], v217 offset:40576
	ds_read_b128 v[40:43], v217 offset:40832
	ds_read_b128 v[44:47], v217 offset:41088
	ds_read_b128 v[48:51], v217 offset:41344
	ds_read_b32 v92, v218 offset:40320
	v_pk_mul_f32 v[206:207], v[24:25], v[122:123]
	v_pk_mul_f32 v[208:209], v[24:25], v[204:205]
	v_pk_fma_f32 v[206:207], v[22:23], v[120:121], v[206:207]
	v_pk_fma_f32 v[208:209], v[22:23], v[202:203], v[208:209]
	v_pk_mul_f32 v[210:211], v[132:133], v[28:29] op_sel_hi:[1,0]
	v_add_f32_e32 v214, v206, v207
	v_add_f32_e32 v216, v208, v209
	v_pk_mul_f32 v[212:213], v[134:135], v[28:29] op_sel_hi:[1,0]
	v_add_f32_dpp v214, v214, v214 quad_perm:[1,0,3,2] row_mask:0xf bank_mask:0xf bound_ctrl:1
	v_add_f32_dpp v216, v216, v216 quad_perm:[1,0,3,2] row_mask:0xf bank_mask:0xf bound_ctrl:1
	v_pk_fma_f32 v[210:211], v[22:23], v[124:125], v[210:211]
	v_add_f32_dpp v214, v214, v214 quad_perm:[2,3,0,1] row_mask:0xf bank_mask:0xf bound_ctrl:1
	v_add_f32_dpp v216, v216, v216 quad_perm:[2,3,0,1] row_mask:0xf bank_mask:0xf bound_ctrl:1
	v_pk_fma_f32 v[212:213], v[24:25], v[126:127], v[212:213]
	v_add_f32_dpp v214, v214, v214 row_half_mirror row_mask:0xf bank_mask:0xf bound_ctrl:1
	v_add_f32_dpp v216, v216, v216 row_half_mirror row_mask:0xf bank_mask:0xf bound_ctrl:1
	v_cmp_eq_u32_e32 vcc, 11, v106
	v_add_f32_dpp v214, v214, v214 row_mirror row_mask:0xf bank_mask:0xf bound_ctrl:1
	v_add_f32_dpp v216, v216, v216 row_mirror row_mask:0xf bank_mask:0xf bound_ctrl:1
	v_pk_fma_f32 v[22:23], v[128:129], v[214:215], v[210:211] op_sel_hi:[1,0,1]
	v_pk_fma_f32 v[24:25], v[130:131], v[214:215], v[212:213] op_sel_hi:[1,0,1]
	v_cndmask_b32_e32 v26, v26, v216, vcc
	s_waitcnt lgkmcnt(6)
	ds_read_b128 v[186:189], v217 offset:41664
	ds_read_b128 v[190:193], v217 offset:41920
	ds_read_b128 v[194:197], v217 offset:42176
	ds_read_b128 v[198:201], v217 offset:42432
	ds_read_b128 v[202:205], v217 offset:42688
	ds_read_b32 v52, v218 offset:41664
	v_pk_mul_f32 v[206:207], v[24:25], v[148:149]
	v_pk_mul_f32 v[208:209], v[24:25], v[138:139]
	v_pk_fma_f32 v[206:207], v[22:23], v[146:147], v[206:207]
	v_pk_fma_f32 v[208:209], v[22:23], v[136:137], v[208:209]
	v_pk_mul_f32 v[210:211], v[158:159], v[30:31] op_sel_hi:[1,0]
	v_add_f32_e32 v214, v206, v207
	v_add_f32_e32 v216, v208, v209
	v_pk_mul_f32 v[212:213], v[160:161], v[30:31] op_sel_hi:[1,0]
	v_add_f32_dpp v214, v214, v214 quad_perm:[1,0,3,2] row_mask:0xf bank_mask:0xf bound_ctrl:1
	v_add_f32_dpp v216, v216, v216 quad_perm:[1,0,3,2] row_mask:0xf bank_mask:0xf bound_ctrl:1
	v_pk_fma_f32 v[210:211], v[22:23], v[150:151], v[210:211]
	v_add_f32_dpp v214, v214, v214 quad_perm:[2,3,0,1] row_mask:0xf bank_mask:0xf bound_ctrl:1
	v_add_f32_dpp v216, v216, v216 quad_perm:[2,3,0,1] row_mask:0xf bank_mask:0xf bound_ctrl:1
	v_pk_fma_f32 v[212:213], v[24:25], v[152:153], v[212:213]
	v_add_f32_dpp v214, v214, v214 row_half_mirror row_mask:0xf bank_mask:0xf bound_ctrl:1
	v_add_f32_dpp v216, v216, v216 row_half_mirror row_mask:0xf bank_mask:0xf bound_ctrl:1
	v_cmp_eq_u32_e32 vcc, 12, v106
	v_add_f32_dpp v214, v214, v214 row_mirror row_mask:0xf bank_mask:0xf bound_ctrl:1
	v_add_f32_dpp v216, v216, v216 row_mirror row_mask:0xf bank_mask:0xf bound_ctrl:1
	v_pk_fma_f32 v[22:23], v[154:155], v[214:215], v[210:211] op_sel_hi:[1,0,1]
	v_pk_fma_f32 v[24:25], v[156:157], v[214:215], v[212:213] op_sel_hi:[1,0,1]
	v_cndmask_b32_e32 v26, v26, v216, vcc
	s_waitcnt lgkmcnt(6)
; __device__ void phase_scan(int l, unsigned char* lds) {
;     ...
;             for (int t8 = 0; t8 < (jb.nsteps < 16 ? jb.nsteps : 16); t8 += 4) {
; #pragma unroll
;                 for (int u = 0; u < 4; ++u) {
;                     const int tt = t8 + u;
;                     const unsigned char* tb = buf + tt * SC_TOKB + c0 * 4;
;                     const f32x4 a = *(const f32x4*)(tb), w = *(const f32x4*)(tb + 256), b = *(const f32x4*)(tb + 512), k = *(const f32x4*)(tb + 768), r = *(const f32x4*)(tb + 1024);
;                     const float v = *(const float*)(buf + tt * SC_TOKB + 1280 + rl * 4);
;                     const f32x2 a01 = (f32x2){a[0], a[1]}, a23 = (f32x2){a[2], a[3]}, w01 = (f32x2){w[0], w[1]}, w23 = (f32x2){w[2], w[3]}, b01 = (f32x2){b[0], b[1]}, b23 = (f32x2){b[2], b[3]};
;                     const f32x2 k01 = (f32x2){k[0], k[1]}, k23 = (f32x2){k[2], k[3]}, r01 = (f32x2){r[0], r[1]}, r23 = (f32x2){r[2], r[3]};
;                     const f32x2 pa = s01 * a01 + s23 * a23;
;                     const float sa = allsum16(pa.x + pa.y);
;                     const f32x2 kv01 = k01 * v, kv23 = k23 * v;
;                     s01 = s01 * w01 + (b01 * sa + kv01); s23 = s23 * w23 + (b23 * sa + kv23);
;                     const f32x2 py = s01 * r01 + s23 * r23;
;                     const float y = allsum16(py.x + py.y);
;                     if ((lane & 15) == (tt & 15)) yreg0 = y;
;                 }
;             }
;             for (int t8 = 16; t8 < (jb.nsteps < 32 ? jb.nsteps : 32); t8 += 4) {
; #pragma unroll
;                 for (int u = 0; u < 4; ++u) {
;                     const int tt = t8 + u;
;                     const unsigned char* tb = buf + tt * SC_TOKB + c0 * 4;
;                     const f32x4 a = *(const f32x4*)(tb), w = *(const f32x4*)(tb + 256), b = *(const f32x4*)(tb + 512), k = *(const f32x4*)(tb + 768), r = *(const f32x4*)(tb + 1024);
;                     const float v = *(const float*)(buf + tt * SC_TOKB + 1280 + rl * 4);
;                     const f32x2 a01 = (f32x2){a[0], a[1]}, a23 = (f32x2){a[2], a[3]}, w01 = (f32x2){w[0], w[1]}, w23 = (f32x2){w[2], w[3]}, b01 = (f32x2){b[0], b[1]}, b23 = (f32x2){b[2], b[3]};
;                     const f32x2 k01 = (f32x2){k[0], k[1]}, k23 = (f32x2){k[2], k[3]}, r01 = (f32x2){r[0], r[1]}, r23 = (f32x2){r[2], r[3]};
;                     const f32x2 pa = s01 * a01 + s23 * a23;
	v_pk_mul_f32 v[206:207], v[24:25], v[34:35]
	v_pk_mul_f32 v[208:209], v[24:25], v[164:165]
	v_pk_fma_f32 v[206:207], v[22:23], v[32:33], v[206:207]
	v_pk_fma_f32 v[208:209], v[22:23], v[162:163], v[208:209]
	v_pk_mul_f32 v[210:211], v[44:45], v[92:93] op_sel_hi:[1,0]
	v_add_f32_e32 v214, v206, v207
	v_add_f32_e32 v216, v208, v209
	v_pk_mul_f32 v[212:213], v[46:47], v[92:93] op_sel_hi:[1,0]
	v_add_f32_dpp v214, v214, v214 quad_perm:[1,0,3,2] row_mask:0xf bank_mask:0xf bound_ctrl:1
	v_add_f32_dpp v216, v216, v216 quad_perm:[1,0,3,2] row_mask:0xf bank_mask:0xf bound_ctrl:1
	v_pk_fma_f32 v[210:211], v[22:23], v[36:37], v[210:211]
	v_add_f32_dpp v214, v214, v214 quad_perm:[2,3,0,1] row_mask:0xf bank_mask:0xf bound_ctrl:1
	v_add_f32_dpp v216, v216, v216 quad_perm:[2,3,0,1] row_mask:0xf bank_mask:0xf bound_ctrl:1
	v_pk_fma_f32 v[212:213], v[24:25], v[38:39], v[212:213]
	v_add_f32_dpp v214, v214, v214 row_half_mirror row_mask:0xf bank_mask:0xf bound_ctrl:1
	v_add_f32_dpp v216, v216, v216 row_half_mirror row_mask:0xf bank_mask:0xf bound_ctrl:1
	v_cmp_eq_u32_e32 vcc, 13, v106
	v_add_f32_dpp v214, v214, v214 row_mirror row_mask:0xf bank_mask:0xf bound_ctrl:1
	v_add_f32_dpp v216, v216, v216 row_mirror row_mask:0xf bank_mask:0xf bound_ctrl:1
	v_pk_fma_f32 v[22:23], v[40:41], v[214:215], v[210:211] op_sel_hi:[1,0,1]
	v_pk_fma_f32 v[24:25], v[42:43], v[214:215], v[212:213] op_sel_hi:[1,0,1]
	v_cndmask_b32_e32 v26, v26, v216, vcc
	s_waitcnt lgkmcnt(0)
	v_pk_mul_f32 v[206:207], v[24:25], v[188:189]
	v_pk_mul_f32 v[208:209], v[24:25], v[50:51]
	v_pk_fma_f32 v[206:207], v[22:23], v[186:187], v[206:207]
	v_pk_fma_f32 v[208:209], v[22:23], v[48:49], v[208:209]
	v_pk_mul_f32 v[210:211], v[198:199], v[52:53] op_sel_hi:[1,0]
	v_add_f32_e32 v214, v206, v207
	v_add_f32_e32 v216, v208, v209
	v_pk_mul_f32 v[212:213], v[200:201], v[52:53] op_sel_hi:[1,0]
	v_add_f32_dpp v214, v214, v214 quad_perm:[1,0,3,2] row_mask:0xf bank_mask:0xf bound_ctrl:1
	v_add_f32_dpp v216, v216, v216 quad_perm:[1,0,3,2] row_mask:0xf bank_mask:0xf bound_ctrl:1
	v_pk_fma_f32 v[210:211], v[22:23], v[190:191], v[210:211]
	v_add_f32_dpp v214, v214, v214 quad_perm:[2,3,0,1] row_mask:0xf bank_mask:0xf bound_ctrl:1
	v_add_f32_dpp v216, v216, v216 quad_perm:[2,3,0,1] row_mask:0xf bank_mask:0xf bound_ctrl:1
	v_pk_fma_f32 v[212:213], v[24:25], v[192:193], v[212:213]
	v_add_f32_dpp v214, v214, v214 row_half_mirror row_mask:0xf bank_mask:0xf bound_ctrl:1
	v_add_f32_dpp v216, v216, v216 row_half_mirror row_mask:0xf bank_mask:0xf bound_ctrl:1
	v_cmp_eq_u32_e32 vcc, 14, v106
	v_add_f32_dpp v214, v214, v214 row_mirror row_mask:0xf bank_mask:0xf bound_ctrl:1
	v_add_f32_dpp v216, v216, v216 row_mirror row_mask:0xf bank_mask:0xf bound_ctrl:1
	v_pk_fma_f32 v[22:23], v[194:195], v[214:215], v[210:211] op_sel_hi:[1,0,1]
	v_pk_fma_f32 v[24:25], v[196:197], v[214:215], v[212:213] op_sel_hi:[1,0,1]
	v_cndmask_b32_e32 v26, v26, v216, vcc
	v_pk_mul_f32 v[208:209], v[24:25], v[204:205]
	v_pk_fma_f32 v[208:209], v[22:23], v[202:203], v[208:209]
	v_cmp_eq_u32_e32 vcc, 15, v106
	v_add_f32_e32 v216, v208, v209
	s_nop 1
	v_add_f32_dpp v216, v216, v216 quad_perm:[1,0,3,2] row_mask:0xf bank_mask:0xf bound_ctrl:1
	s_nop 1
	v_add_f32_dpp v216, v216, v216 quad_perm:[2,3,0,1] row_mask:0xf bank_mask:0xf bound_ctrl:1
	s_nop 1
	v_add_f32_dpp v216, v216, v216 row_half_mirror row_mask:0xf bank_mask:0xf bound_ctrl:1
	s_nop 1
	v_add_f32_dpp v216, v216, v216 row_mirror row_mask:0xf bank_mask:0xf bound_ctrl:1
	v_cndmask_b32_e32 v26, v26, v216, vcc
	s_branch .LBB0_537
.Lscan0_n8:
	ds_read_b128 v[120:123], v217 offset:0
	ds_read_b128 v[124:127], v217 offset:256
	ds_read_b128 v[128:131], v217 offset:512
	ds_read_b128 v[132:135], v217 offset:768
	ds_read_b128 v[136:139], v217 offset:1024
	ds_read_b32 v28, v218 offset:0
	ds_read_b128 v[146:149], v217 offset:1344
	ds_read_b128 v[150:153], v217 offset:1600
	ds_read_b128 v[154:157], v217 offset:1856
	ds_read_b128 v[158:161], v217 offset:2112
	ds_read_b128 v[162:165], v217 offset:2368
	ds_read_b32 v30, v218 offset:1344
	s_waitcnt lgkmcnt(6)
	ds_read_b128 v[32:35], v217 offset:2688
	ds_read_b128 v[36:39], v217 offset:2944
	ds_read_b128 v[40:43], v217 offset:3200
	ds_read_b128 v[44:47], v217 offset:3456
	ds_read_b128 v[48:51], v217 offset:3712
	ds_read_b32 v92, v218 offset:2688
	v_pk_mul_f32 v[206:207], v[24:25], v[122:123]
	v_pk_mul_f32 v[210:211], v[132:133], v[28:29] op_sel_hi:[1,0]
	v_pk_fma_f32 v[206:207], v[22:23], v[120:121], v[206:207]
	v_pk_mul_f32 v[212:213], v[134:135], v[28:29] op_sel_hi:[1,0]
	v_pk_fma_f32 v[210:211], v[22:23], v[124:125], v[210:211]
	v_add_f32_e32 v214, v206, v207
	v_pk_fma_f32 v[212:213], v[24:25], v[126:127], v[212:213]
	s_nop 0
	v_add_f32_dpp v214, v214, v214 quad_perm:[1,0,3,2] row_mask:0xf bank_mask:0xf bound_ctrl:1
	s_nop 1
	v_add_f32_dpp v214, v214, v214 quad_perm:[2,3,0,1] row_mask:0xf bank_mask:0xf bound_ctrl:1
	s_nop 1
	v_add_f32_dpp v214, v214, v214 row_half_mirror row_mask:0xf bank_mask:0xf bound_ctrl:1
	s_nop 1
	v_add_f32_dpp v214, v214, v214 row_mirror row_mask:0xf bank_mask:0xf bound_ctrl:1
	v_pk_fma_f32 v[22:23], v[128:129], v[214:215], v[210:211] op_sel_hi:[1,0,1]
	v_pk_fma_f32 v[24:25], v[130:131], v[214:215], v[212:213] op_sel_hi:[1,0,1]
	s_waitcnt lgkmcnt(6)
; __device__ void phase_scan(int l, unsigned char* lds) {
;     ...
;             for (int t8 = 0; t8 < (jb.nsteps < 16 ? jb.nsteps : 16); t8 += 4) {
; #pragma unroll
;                 for (int u = 0; u < 4; ++u) {
;                     const int tt = t8 + u;
;                     const unsigned char* tb = buf + tt * SC_TOKB + c0 * 4;
;                     const f32x4 a = *(const f32x4*)(tb), w = *(const f32x4*)(tb + 256), b = *(const f32x4*)(tb + 512), k = *(const f32x4*)(tb + 768), r = *(const f32x4*)(tb + 1024);
;                     const float v = *(const float*)(buf + tt * SC_TOKB + 1280 + rl * 4);
;                     const f32x2 a01 = (f32x2){a[0], a[1]}, a23 = (f32x2){a[2], a[3]}, w01 = (f32x2){w[0], w[1]}, w23 = (f32x2){w[2], w[3]}, b01 = (f32x2){b[0], b[1]}, b23 = (f32x2){b[2], b[3]};
;                     const f32x2 k01 = (f32x2){k[0], k[1]}, k23 = (f32x2){k[2], k[3]}, r01 = (f32x2){r[0], r[1]}, r23 = (f32x2){r[2], r[3]};
;                     const f32x2 pa = s01 * a01 + s23 * a23;
;                     const float sa = allsum16(pa.x + pa.y);
;                     const f32x2 kv01 = k01 * v, kv23 = k23 * v;
;                     s01 = s01 * w01 + (b01 * sa + kv01); s23 = s23 * w23 + (b23 * sa + kv23);
;                     const f32x2 py = s01 * r01 + s23 * r23;
;                     const float y = allsum16(py.x + py.y);
;                     if ((lane & 15) == (tt & 15)) yreg0 = y;
;                 }
;             }
	ds_read_b128 v[186:189], v217 offset:4032
	ds_read_b128 v[190:193], v217 offset:4288
	ds_read_b128 v[194:197], v217 offset:4544
	ds_read_b128 v[198:201], v217 offset:4800
	ds_read_b128 v[202:205], v217 offset:5056
	ds_read_b32 v52, v218 offset:4032
	v_pk_mul_f32 v[206:207], v[24:25], v[148:149]
	v_pk_mul_f32 v[208:209], v[24:25], v[138:139]
	v_pk_fma_f32 v[206:207], v[22:23], v[146:147], v[206:207]
	v_pk_fma_f32 v[208:209], v[22:23], v[136:137], v[208:209]
	v_pk_mul_f32 v[210:211], v[158:159], v[30:31] op_sel_hi:[1,0]
	v_add_f32_e32 v214, v206, v207
	v_add_f32_e32 v216, v208, v209
	v_pk_mul_f32 v[212:213], v[160:161], v[30:31] op_sel_hi:[1,0]
	v_add_f32_dpp v214, v214, v214 quad_perm:[1,0,3,2] row_mask:0xf bank_mask:0xf bound_ctrl:1
	v_add_f32_dpp v216, v216, v216 quad_perm:[1,0,3,2] row_mask:0xf bank_mask:0xf bound_ctrl:1
	v_pk_fma_f32 v[210:211], v[22:23], v[150:151], v[210:211]
	v_add_f32_dpp v214, v214, v214 quad_perm:[2,3,0,1] row_mask:0xf bank_mask:0xf bound_ctrl:1
	v_add_f32_dpp v216, v216, v216 quad_perm:[2,3,0,1] row_mask:0xf bank_mask:0xf bound_ctrl:1
	v_pk_fma_f32 v[212:213], v[24:25], v[152:153], v[212:213]
	v_add_f32_dpp v214, v214, v214 row_half_mirror row_mask:0xf bank_mask:0xf bound_ctrl:1
	v_add_f32_dpp v216, v216, v216 row_half_mirror row_mask:0xf bank_mask:0xf bound_ctrl:1
	v_cmp_eq_u32_e32 vcc, 0, v106
	v_add_f32_dpp v214, v214, v214 row_mirror row_mask:0xf bank_mask:0xf bound_ctrl:1
	v_add_f32_dpp v216, v216, v216 row_mirror row_mask:0xf bank_mask:0xf bound_ctrl:1
	v_pk_fma_f32 v[22:23], v[154:155], v[214:215], v[210:211] op_sel_hi:[1,0,1]
	v_pk_fma_f32 v[24:25], v[156:157], v[214:215], v[212:213] op_sel_hi:[1,0,1]
	v_cndmask_b32_e32 v18, v18, v216, vcc
	s_waitcnt lgkmcnt(6)
	ds_read_b128 v[120:123], v217 offset:5376
	ds_read_b128 v[124:127], v217 offset:5632
	ds_read_b128 v[128:131], v217 offset:5888
	ds_read_b128 v[132:135], v217 offset:6144
	ds_read_b128 v[136:139], v217 offset:6400
	ds_read_b32 v28, v218 offset:5376
	v_pk_mul_f32 v[206:207], v[24:25], v[34:35]
	v_pk_mul_f32 v[208:209], v[24:25], v[164:165]
	v_pk_fma_f32 v[206:207], v[22:23], v[32:33], v[206:207]
	v_pk_fma_f32 v[208:209], v[22:23], v[162:163], v[208:209]
	v_pk_mul_f32 v[210:211], v[44:45], v[92:93] op_sel_hi:[1,0]
	v_add_f32_e32 v214, v206, v207
	v_add_f32_e32 v216, v208, v209
	v_pk_mul_f32 v[212:213], v[46:47], v[92:93] op_sel_hi:[1,0]
	v_add_f32_dpp v214, v214, v214 quad_perm:[1,0,3,2] row_mask:0xf bank_mask:0xf bound_ctrl:1
	v_add_f32_dpp v216, v216, v216 quad_perm:[1,0,3,2] row_mask:0xf bank_mask:0xf bound_ctrl:1
	v_pk_fma_f32 v[210:211], v[22:23], v[36:37], v[210:211]
	v_add_f32_dpp v214, v214, v214 quad_perm:[2,3,0,1] row_mask:0xf bank_mask:0xf bound_ctrl:1
	v_add_f32_dpp v216, v216, v216 quad_perm:[2,3,0,1] row_mask:0xf bank_mask:0xf bound_ctrl:1
	v_pk_fma_f32 v[212:213], v[24:25], v[38:39], v[212:213]
	v_add_f32_dpp v214, v214, v214 row_half_mirror row_mask:0xf bank_mask:0xf bound_ctrl:1
	v_add_f32_dpp v216, v216, v216 row_half_mirror row_mask:0xf bank_mask:0xf bound_ctrl:1
	v_cmp_eq_u32_e32 vcc, 1, v106
	v_add_f32_dpp v214, v214, v214 row_mirror row_mask:0xf bank_mask:0xf bound_ctrl:1
	v_add_f32_dpp v216, v216, v216 row_mirror row_mask:0xf bank_mask:0xf bound_ctrl:1
	v_pk_fma_f32 v[22:23], v[40:41], v[214:215], v[210:211] op_sel_hi:[1,0,1]
	v_pk_fma_f32 v[24:25], v[42:43], v[214:215], v[212:213] op_sel_hi:[1,0,1]
	v_cndmask_b32_e32 v18, v18, v216, vcc
	s_waitcnt lgkmcnt(6)
	ds_read_b128 v[146:149], v217 offset:6720
	ds_read_b128 v[150:153], v217 offset:6976
	ds_read_b128 v[154:157], v217 offset:7232
	ds_read_b128 v[158:161], v217 offset:7488
	ds_read_b128 v[162:165], v217 offset:7744
	ds_read_b32 v30, v218 offset:6720
	v_pk_mul_f32 v[206:207], v[24:25], v[188:189]
	v_pk_mul_f32 v[208:209], v[24:25], v[50:51]
	v_pk_fma_f32 v[206:207], v[22:23], v[186:187], v[206:207]
	v_pk_fma_f32 v[208:209], v[22:23], v[48:49], v[208:209]
	v_pk_mul_f32 v[210:211], v[198:199], v[52:53] op_sel_hi:[1,0]
	v_add_f32_e32 v214, v206, v207
	v_add_f32_e32 v216, v208, v209
	v_pk_mul_f32 v[212:213], v[200:201], v[52:53] op_sel_hi:[1,0]
	v_add_f32_dpp v214, v214, v214 quad_perm:[1,0,3,2] row_mask:0xf bank_mask:0xf bound_ctrl:1
	v_add_f32_dpp v216, v216, v216 quad_perm:[1,0,3,2] row_mask:0xf bank_mask:0xf bound_ctrl:1
	v_pk_fma_f32 v[210:211], v[22:23], v[190:191], v[210:211]
	v_add_f32_dpp v214, v214, v214 quad_perm:[2,3,0,1] row_mask:0xf bank_mask:0xf bound_ctrl:1
	v_add_f32_dpp v216, v216, v216 quad_perm:[2,3,0,1] row_mask:0xf bank_mask:0xf bound_ctrl:1
	v_pk_fma_f32 v[212:213], v[24:25], v[192:193], v[212:213]
	v_add_f32_dpp v214, v214, v214 row_half_mirror row_mask:0xf bank_mask:0xf bound_ctrl:1
	v_add_f32_dpp v216, v216, v216 row_half_mirror row_mask:0xf bank_mask:0xf bound_ctrl:1
	v_cmp_eq_u32_e32 vcc, 2, v106
	v_add_f32_dpp v214, v214, v214 row_mirror row_mask:0xf bank_mask:0xf bound_ctrl:1
	v_add_f32_dpp v216, v216, v216 row_mirror row_mask:0xf bank_mask:0xf bound_ctrl:1
	v_pk_fma_f32 v[22:23], v[194:195], v[214:215], v[210:211] op_sel_hi:[1,0,1]
	v_pk_fma_f32 v[24:25], v[196:197], v[214:215], v[212:213] op_sel_hi:[1,0,1]
	v_cndmask_b32_e32 v18, v18, v216, vcc
	s_waitcnt lgkmcnt(6)
; __device__ void phase_scan(int l, unsigned char* lds) {
;     ...
;             for (int t8 = 0; t8 < (jb.nsteps < 16 ? jb.nsteps : 16); t8 += 4) {
; #pragma unroll
;                 for (int u = 0; u < 4; ++u) {
;                     const int tt = t8 + u;
;                     const unsigned char* tb = buf + tt * SC_TOKB + c0 * 4;
;                     const f32x4 a = *(const f32x4*)(tb), w = *(const f32x4*)(tb + 256), b = *(const f32x4*)(tb + 512), k = *(const f32x4*)(tb + 768), r = *(const f32x4*)(tb + 1024);
;                     const float v = *(const float*)(buf + tt * SC_TOKB + 1280 + rl * 4);
;                     const f32x2 a01 = (f32x2){a[0], a[1]}, a23 = (f32x2){a[2], a[3]}, w01 = (f32x2){w[0], w[1]}, w23 = (f32x2){w[2], w[3]}, b01 = (f32x2){b[0], b[1]}, b23 = (f32x2){b[2], b[3]};
;                     const f32x2 k01 = (f32x2){k[0], k[1]}, k23 = (f32x2){k[2], k[3]}, r01 = (f32x2){r[0], r[1]}, r23 = (f32x2){r[2], r[3]};
;                     const f32x2 pa = s01 * a01 + s23 * a23;
;                     const float sa = allsum16(pa.x + pa.y);
;                     const f32x2 kv01 = k01 * v, kv23 = k23 * v;
;                     s01 = s01 * w01 + (b01 * sa + kv01); s23 = s23 * w23 + (b23 * sa + kv23);
;                     const f32x2 py = s01 * r01 + s23 * r23;
;                     const float y = allsum16(py.x + py.y);
;                     if ((lane & 15) == (tt & 15)) yreg0 = y;
;                 }
;             }
	ds_read_b128 v[32:35], v217 offset:8064
	ds_read_b128 v[36:39], v217 offset:8320
	ds_read_b128 v[40:43], v217 offset:8576
	ds_read_b128 v[44:47], v217 offset:8832
	ds_read_b128 v[48:51], v217 offset:9088
	ds_read_b32 v92, v218 offset:8064
	v_pk_mul_f32 v[206:207], v[24:25], v[122:123]
	v_pk_mul_f32 v[208:209], v[24:25], v[204:205]
	v_pk_fma_f32 v[206:207], v[22:23], v[120:121], v[206:207]
	v_pk_fma_f32 v[208:209], v[22:23], v[202:203], v[208:209]
	v_pk_mul_f32 v[210:211], v[132:133], v[28:29] op_sel_hi:[1,0]
	v_add_f32_e32 v214, v206, v207
	v_add_f32_e32 v216, v208, v209
	v_pk_mul_f32 v[212:213], v[134:135], v[28:29] op_sel_hi:[1,0]
	v_add_f32_dpp v214, v214, v214 quad_perm:[1,0,3,2] row_mask:0xf bank_mask:0xf bound_ctrl:1
	v_add_f32_dpp v216, v216, v216 quad_perm:[1,0,3,2] row_mask:0xf bank_mask:0xf bound_ctrl:1
	v_pk_fma_f32 v[210:211], v[22:23], v[124:125], v[210:211]
	v_add_f32_dpp v214, v214, v214 quad_perm:[2,3,0,1] row_mask:0xf bank_mask:0xf bound_ctrl:1
	v_add_f32_dpp v216, v216, v216 quad_perm:[2,3,0,1] row_mask:0xf bank_mask:0xf bound_ctrl:1
	v_pk_fma_f32 v[212:213], v[24:25], v[126:127], v[212:213]
	v_add_f32_dpp v214, v214, v214 row_half_mirror row_mask:0xf bank_mask:0xf bound_ctrl:1
	v_add_f32_dpp v216, v216, v216 row_half_mirror row_mask:0xf bank_mask:0xf bound_ctrl:1
	v_cmp_eq_u32_e32 vcc, 3, v106
	v_add_f32_dpp v214, v214, v214 row_mirror row_mask:0xf bank_mask:0xf bound_ctrl:1
	v_add_f32_dpp v216, v216, v216 row_mirror row_mask:0xf bank_mask:0xf bound_ctrl:1
	v_pk_fma_f32 v[22:23], v[128:129], v[214:215], v[210:211] op_sel_hi:[1,0,1]
	v_pk_fma_f32 v[24:25], v[130:131], v[214:215], v[212:213] op_sel_hi:[1,0,1]
	v_cndmask_b32_e32 v18, v18, v216, vcc
	s_waitcnt lgkmcnt(6)
	ds_read_b128 v[186:189], v217 offset:9408
	ds_read_b128 v[190:193], v217 offset:9664
	ds_read_b128 v[194:197], v217 offset:9920
	ds_read_b128 v[198:201], v217 offset:10176
	ds_read_b128 v[202:205], v217 offset:10432
	ds_read_b32 v52, v218 offset:9408
	v_pk_mul_f32 v[206:207], v[24:25], v[148:149]
	v_pk_mul_f32 v[208:209], v[24:25], v[138:139]
	v_pk_fma_f32 v[206:207], v[22:23], v[146:147], v[206:207]
	v_pk_fma_f32 v[208:209], v[22:23], v[136:137], v[208:209]
	v_pk_mul_f32 v[210:211], v[158:159], v[30:31] op_sel_hi:[1,0]
	v_add_f32_e32 v214, v206, v207
	v_add_f32_e32 v216, v208, v209
	v_pk_mul_f32 v[212:213], v[160:161], v[30:31] op_sel_hi:[1,0]
	v_add_f32_dpp v214, v214, v214 quad_perm:[1,0,3,2] row_mask:0xf bank_mask:0xf bound_ctrl:1
	v_add_f32_dpp v216, v216, v216 quad_perm:[1,0,3,2] row_mask:0xf bank_mask:0xf bound_ctrl:1
	v_pk_fma_f32 v[210:211], v[22:23], v[150:151], v[210:211]
	v_add_f32_dpp v214, v214, v214 quad_perm:[2,3,0,1] row_mask:0xf bank_mask:0xf bound_ctrl:1
	v_add_f32_dpp v216, v216, v216 quad_perm:[2,3,0,1] row_mask:0xf bank_mask:0xf bound_ctrl:1
	v_pk_fma_f32 v[212:213], v[24:25], v[152:153], v[212:213]
	v_add_f32_dpp v214, v214, v214 row_half_mirror row_mask:0xf bank_mask:0xf bound_ctrl:1
	v_add_f32_dpp v216, v216, v216 row_half_mirror row_mask:0xf bank_mask:0xf bound_ctrl:1
	v_cmp_eq_u32_e32 vcc, 4, v106
	v_add_f32_dpp v214, v214, v214 row_mirror row_mask:0xf bank_mask:0xf bound_ctrl:1
	v_add_f32_dpp v216, v216, v216 row_mirror row_mask:0xf bank_mask:0xf bound_ctrl:1
	v_pk_fma_f32 v[22:23], v[154:155], v[214:215], v[210:211] op_sel_hi:[1,0,1]
	v_pk_fma_f32 v[24:25], v[156:157], v[214:215], v[212:213] op_sel_hi:[1,0,1]
	v_cndmask_b32_e32 v18, v18, v216, vcc
	s_waitcnt lgkmcnt(6)
	v_pk_mul_f32 v[206:207], v[24:25], v[34:35]
	v_pk_mul_f32 v[208:209], v[24:25], v[164:165]
	v_pk_fma_f32 v[206:207], v[22:23], v[32:33], v[206:207]
	v_pk_fma_f32 v[208:209], v[22:23], v[162:163], v[208:209]
	v_pk_mul_f32 v[210:211], v[44:45], v[92:93] op_sel_hi:[1,0]
	v_add_f32_e32 v214, v206, v207
	v_add_f32_e32 v216, v208, v209
	v_pk_mul_f32 v[212:213], v[46:47], v[92:93] op_sel_hi:[1,0]
	v_add_f32_dpp v214, v214, v214 quad_perm:[1,0,3,2] row_mask:0xf bank_mask:0xf bound_ctrl:1
	v_add_f32_dpp v216, v216, v216 quad_perm:[1,0,3,2] row_mask:0xf bank_mask:0xf bound_ctrl:1
	v_pk_fma_f32 v[210:211], v[22:23], v[36:37], v[210:211]
	v_add_f32_dpp v214, v214, v214 quad_perm:[2,3,0,1] row_mask:0xf bank_mask:0xf bound_ctrl:1
	v_add_f32_dpp v216, v216, v216 quad_perm:[2,3,0,1] row_mask:0xf bank_mask:0xf bound_ctrl:1
	v_pk_fma_f32 v[212:213], v[24:25], v[38:39], v[212:213]
	v_add_f32_dpp v214, v214, v214 row_half_mirror row_mask:0xf bank_mask:0xf bound_ctrl:1
	v_add_f32_dpp v216, v216, v216 row_half_mirror row_mask:0xf bank_mask:0xf bound_ctrl:1
	v_cmp_eq_u32_e32 vcc, 5, v106
	v_add_f32_dpp v214, v214, v214 row_mirror row_mask:0xf bank_mask:0xf bound_ctrl:1
	v_add_f32_dpp v216, v216, v216 row_mirror row_mask:0xf bank_mask:0xf bound_ctrl:1
	v_pk_fma_f32 v[22:23], v[40:41], v[214:215], v[210:211] op_sel_hi:[1,0,1]
	v_pk_fma_f32 v[24:25], v[42:43], v[214:215], v[212:213] op_sel_hi:[1,0,1]
	v_cndmask_b32_e32 v18, v18, v216, vcc
	s_waitcnt lgkmcnt(0)
	v_pk_mul_f32 v[206:207], v[24:25], v[188:189]
	v_pk_mul_f32 v[208:209], v[24:25], v[50:51]
	v_pk_fma_f32 v[206:207], v[22:23], v[186:187], v[206:207]
	v_pk_fma_f32 v[208:209], v[22:23], v[48:49], v[208:209]
	v_pk_mul_f32 v[210:211], v[198:199], v[52:53] op_sel_hi:[1,0]
	v_add_f32_e32 v214, v206, v207
	v_add_f32_e32 v216, v208, v209
	v_pk_mul_f32 v[212:213], v[200:201], v[52:53] op_sel_hi:[1,0]
	v_add_f32_dpp v214, v214, v214 quad_perm:[1,0,3,2] row_mask:0xf bank_mask:0xf bound_ctrl:1
	v_add_f32_dpp v216, v216, v216 quad_perm:[1,0,3,2] row_mask:0xf bank_mask:0xf bound_ctrl:1
	v_pk_fma_f32 v[210:211], v[22:23], v[190:191], v[210:211]
	v_add_f32_dpp v214, v214, v214 quad_perm:[2,3,0,1] row_mask:0xf bank_mask:0xf bound_ctrl:1
	v_add_f32_dpp v216, v216, v216 quad_perm:[2,3,0,1] row_mask:0xf bank_mask:0xf bound_ctrl:1
	v_pk_fma_f32 v[212:213], v[24:25], v[192:193], v[212:213]
	v_add_f32_dpp v214, v214, v214 row_half_mirror row_mask:0xf bank_mask:0xf bound_ctrl:1
	v_add_f32_dpp v216, v216, v216 row_half_mirror row_mask:0xf bank_mask:0xf bound_ctrl:1
	v_cmp_eq_u32_e32 vcc, 6, v106
	v_add_f32_dpp v214, v214, v214 row_mirror row_mask:0xf bank_mask:0xf bound_ctrl:1
	v_add_f32_dpp v216, v216, v216 row_mirror row_mask:0xf bank_mask:0xf bound_ctrl:1
	v_pk_fma_f32 v[22:23], v[194:195], v[214:215], v[210:211] op_sel_hi:[1,0,1]
	v_pk_fma_f32 v[24:25], v[196:197], v[214:215], v[212:213] op_sel_hi:[1,0,1]
	v_cndmask_b32_e32 v18, v18, v216, vcc
	v_pk_mul_f32 v[208:209], v[24:25], v[204:205]
	v_pk_fma_f32 v[208:209], v[22:23], v[202:203], v[208:209]
	v_cmp_eq_u32_e32 vcc, 7, v106
	v_add_f32_e32 v216, v208, v209
	s_nop 1
	v_add_f32_dpp v216, v216, v216 quad_perm:[1,0,3,2] row_mask:0xf bank_mask:0xf bound_ctrl:1
	s_nop 1
	v_add_f32_dpp v216, v216, v216 quad_perm:[2,3,0,1] row_mask:0xf bank_mask:0xf bound_ctrl:1
	s_nop 1
	v_add_f32_dpp v216, v216, v216 row_half_mirror row_mask:0xf bank_mask:0xf bound_ctrl:1
	s_nop 1
	v_add_f32_dpp v216, v216, v216 row_mirror row_mask:0xf bank_mask:0xf bound_ctrl:1
	v_cndmask_b32_e32 v18, v18, v216, vcc

; __device__ void phase_scan(int l, unsigned char* lds) {
;     ...
;             const Job jb = job_decode(J, ci);
;             const int rl = wid * 4 + (lane >> 4), row = jb.rs * 16 + rl, c0 = (lane & 15) * 4;
;             const size_t sidx = ((((size_t)l * (jb.is_s ? NSB : NB) + jb.seq) * 8 + jb.h) * 64 + row) * 64 + c0;
;             if (jb.first) { s01 = (f32x2){0.f, 0.f}; s23 = s01;
;                 if (jb.is_s) { asm volatile("" ::: "memory");
;                     s01 = (f32x2){s_pref[0], s_pref[1]}; s23 = (f32x2){s_pref[2], s_pref[3]}; } }
;             if (Jn < NJOBS && Jn >= 256 && cn == 0 && Jn != J) { const Job jn = job_decode(Jn, 0);
;                 s_pref = *(const f32x4*)(st_wkv + (((((size_t)l * NSB + jn.seq) * 8 + jn.h) * 64 + jn.rs * 16 + rl) * 64 + c0)); }
;             float yreg0 = 0.f, yreg1 = 0.f;
;             for (int t8 = 0; t8 < (jb.nsteps < 16 ? jb.nsteps : 16); t8 += 4) {
; #pragma unroll
;                 for (int u = 0; u < 4; ++u) {
;                     const int tt = t8 + u;
;                     const unsigned char* tb = buf + tt * SC_TOKB + c0 * 4;
;                     const f32x4 a = *(const f32x4*)(tb), w = *(const f32x4*)(tb + 256), b = *(const f32x4*)(tb + 512), k = *(const f32x4*)(tb + 768), r = *(const f32x4*)(tb + 1024);
;                     const float v = *(const float*)(buf + tt * SC_TOKB + 1280 + rl * 4);
;                     const f32x2 a01 = (f32x2){a[0], a[1]}, a23 = (f32x2){a[2], a[3]}, w01 = (f32x2){w[0], w[1]}, w23 = (f32x2){w[2], w[3]}, b01 = (f32x2){b[0], b[1]}, b23 = (f32x2){b[2], b[3]};
;                     const f32x2 k01 = (f32x2){k[0], k[1]}, k23 = (f32x2){k[2], k[3]}, r01 = (f32x2){r[0], r[1]}, r23 = (f32x2){r[2], r[3]};
;                     const f32x2 pa = s01 * a01 + s23 * a23;
;                     const float sa = allsum16(pa.x + pa.y);
;                     const f32x2 kv01 = k01 * v, kv23 = k23 * v;
;                     s01 = s01 * w01 + (b01 * sa + kv01); s23 = s23 * w23 + (b23 * sa + kv23);
;                     const f32x2 py = s01 * r01 + s23 * r23;
;                     const float y = allsum16(py.x + py.y);
;                     if ((lane & 15) == (tt & 15)) yreg0 = y;
;                 }
;             }
.LBB0_1673:
	s_mul_hi_u32 s17, s84, 0xaaaaaaab
	s_lshr_b32 s17, s17, 1
	s_mul_i32 s17, s17, 0xfffe0800
	s_xor_b64 s[18:19], s[18:19], -1
	v_add_u32_e32 v217, s17, v110
	v_add_u32_e32 v218, s17, v111
	v_mov_b32_e32 v18, 0
	v_mov_b32_e32 v26, 0
	s_cmp_eq_u32 s44, 32
	s_cbranch_scc0 .Lscan1_n8
	ds_read_b128 v[120:123], v217 offset:0
	ds_read_b128 v[124:127], v217 offset:256
	ds_read_b128 v[128:131], v217 offset:512
	ds_read_b128 v[132:135], v217 offset:768
	ds_read_b128 v[136:139], v217 offset:1024
	ds_read_b32 v28, v218 offset:0
	ds_read_b128 v[146:149], v217 offset:1344
	ds_read_b128 v[150:153], v217 offset:1600
	ds_read_b128 v[154:157], v217 offset:1856
	ds_read_b128 v[158:161], v217 offset:2112
	ds_read_b128 v[162:165], v217 offset:2368
	ds_read_b32 v30, v218 offset:1344
	s_waitcnt lgkmcnt(6)
	ds_read_b128 v[32:35], v217 offset:2688
	ds_read_b128 v[36:39], v217 offset:2944
	ds_read_b128 v[40:43], v217 offset:3200
	ds_read_b128 v[44:47], v217 offset:3456
	ds_read_b128 v[48:51], v217 offset:3712
	ds_read_b32 v92, v218 offset:2688
	v_pk_mul_f32 v[206:207], v[24:25], v[122:123]
	v_pk_mul_f32 v[210:211], v[132:133], v[28:29] op_sel_hi:[1,0]
	v_pk_fma_f32 v[206:207], v[22:23], v[120:121], v[206:207]
	v_pk_mul_f32 v[212:213], v[134:135], v[28:29] op_sel_hi:[1,0]
	v_pk_fma_f32 v[210:211], v[22:23], v[124:125], v[210:211]
	v_add_f32_e32 v214, v206, v207
	v_pk_fma_f32 v[212:213], v[24:25], v[126:127], v[212:213]
	s_nop 0
	v_add_f32_dpp v214, v214, v214 quad_perm:[1,0,3,2] row_mask:0xf bank_mask:0xf bound_ctrl:1
	s_nop 1
	v_add_f32_dpp v214, v214, v214 quad_perm:[2,3,0,1] row_mask:0xf bank_mask:0xf bound_ctrl:1
	s_nop 1
	v_add_f32_dpp v214, v214, v214 row_half_mirror row_mask:0xf bank_mask:0xf bound_ctrl:1
	s_nop 1
	v_add_f32_dpp v214, v214, v214 row_mirror row_mask:0xf bank_mask:0xf bound_ctrl:1
	v_pk_fma_f32 v[22:23], v[128:129], v[214:215], v[210:211] op_sel_hi:[1,0,1]
	v_pk_fma_f32 v[24:25], v[130:131], v[214:215], v[212:213] op_sel_hi:[1,0,1]
	s_waitcnt lgkmcnt(6)
	ds_read_b128 v[186:189], v217 offset:4032
	ds_read_b128 v[190:193], v217 offset:4288
	ds_read_b128 v[194:197], v217 offset:4544
	ds_read_b128 v[198:201], v217 offset:4800
	ds_read_b128 v[202:205], v217 offset:5056
	ds_read_b32 v52, v218 offset:4032
	v_pk_mul_f32 v[206:207], v[24:25], v[148:149]
	v_pk_mul_f32 v[208:209], v[24:25], v[138:139]
	v_pk_fma_f32 v[206:207], v[22:23], v[146:147], v[206:207]
	v_pk_fma_f32 v[208:209], v[22:23], v[136:137], v[208:209]
	v_pk_mul_f32 v[210:211], v[158:159], v[30:31] op_sel_hi:[1,0]
	v_add_f32_e32 v214, v206, v207
	v_add_f32_e32 v216, v208, v209
	v_pk_mul_f32 v[212:213], v[160:161], v[30:31] op_sel_hi:[1,0]
	v_add_f32_dpp v214, v214, v214 quad_perm:[1,0,3,2] row_mask:0xf bank_mask:0xf bound_ctrl:1
	v_add_f32_dpp v216, v216, v216 quad_perm:[1,0,3,2] row_mask:0xf bank_mask:0xf bound_ctrl:1
	v_pk_fma_f32 v[210:211], v[22:23], v[150:151], v[210:211]
	v_add_f32_dpp v214, v214, v214 quad_perm:[2,3,0,1] row_mask:0xf bank_mask:0xf bound_ctrl:1
	v_add_f32_dpp v216, v216, v216 quad_perm:[2,3,0,1] row_mask:0xf bank_mask:0xf bound_ctrl:1
	v_pk_fma_f32 v[212:213], v[24:25], v[152:153], v[212:213]
	v_add_f32_dpp v214, v214, v214 row_half_mirror row_mask:0xf bank_mask:0xf bound_ctrl:1
	v_add_f32_dpp v216, v216, v216 row_half_mirror row_mask:0xf bank_mask:0xf bound_ctrl:1
	v_cmp_eq_u32_e32 vcc, 0, v106
	v_add_f32_dpp v214, v214, v214 row_mirror row_mask:0xf bank_mask:0xf bound_ctrl:1
	v_add_f32_dpp v216, v216, v216 row_mirror row_mask:0xf bank_mask:0xf bound_ctrl:1
	v_pk_fma_f32 v[22:23], v[154:155], v[214:215], v[210:211] op_sel_hi:[1,0,1]
	v_pk_fma_f32 v[24:25], v[156:157], v[214:215], v[212:213] op_sel_hi:[1,0,1]
	v_cndmask_b32_e32 v18, v18, v216, vcc
	s_waitcnt lgkmcnt(6)
	ds_read_b128 v[120:123], v217 offset:5376
	ds_read_b128 v[124:127], v217 offset:5632
	ds_read_b128 v[128:131], v217 offset:5888
	ds_read_b128 v[132:135], v217 offset:6144
	ds_read_b128 v[136:139], v217 offset:6400
	ds_read_b32 v28, v218 offset:5376
	v_pk_mul_f32 v[206:207], v[24:25], v[34:35]
	v_pk_mul_f32 v[208:209], v[24:25], v[164:165]
	v_pk_fma_f32 v[206:207], v[22:23], v[32:33], v[206:207]
	v_pk_fma_f32 v[208:209], v[22:23], v[162:163], v[208:209]
	v_pk_mul_f32 v[210:211], v[44:45], v[92:93] op_sel_hi:[1,0]
	v_add_f32_e32 v214, v206, v207
	v_add_f32_e32 v216, v208, v209
	v_pk_mul_f32 v[212:213], v[46:47], v[92:93] op_sel_hi:[1,0]
	v_add_f32_dpp v214, v214, v214 quad_perm:[1,0,3,2] row_mask:0xf bank_mask:0xf bound_ctrl:1
	v_add_f32_dpp v216, v216, v216 quad_perm:[1,0,3,2] row_mask:0xf bank_mask:0xf bound_ctrl:1
	v_pk_fma_f32 v[210:211], v[22:23], v[36:37], v[210:211]
	v_add_f32_dpp v214, v214, v214 quad_perm:[2,3,0,1] row_mask:0xf bank_mask:0xf bound_ctrl:1
	v_add_f32_dpp v216, v216, v216 quad_perm:[2,3,0,1] row_mask:0xf bank_mask:0xf bound_ctrl:1
	v_pk_fma_f32 v[212:213], v[24:25], v[38:39], v[212:213]
	v_add_f32_dpp v214, v214, v214 row_half_mirror row_mask:0xf bank_mask:0xf bound_ctrl:1
	v_add_f32_dpp v216, v216, v216 row_half_mirror row_mask:0xf bank_mask:0xf bound_ctrl:1
	v_cmp_eq_u32_e32 vcc, 1, v106
	v_add_f32_dpp v214, v214, v214 row_mirror row_mask:0xf bank_mask:0xf bound_ctrl:1
	v_add_f32_dpp v216, v216, v216 row_mirror row_mask:0xf bank_mask:0xf bound_ctrl:1
	v_pk_fma_f32 v[22:23], v[40:41], v[214:215], v[210:211] op_sel_hi:[1,0,1]
	v_pk_fma_f32 v[24:25], v[42:43], v[214:215], v[212:213] op_sel_hi:[1,0,1]
	v_cndmask_b32_e32 v18, v18, v216, vcc
	s_waitcnt lgkmcnt(6)
; __device__ void phase_scan(int l, unsigned char* lds) {
;     ...
;             for (int t8 = 0; t8 < (jb.nsteps < 16 ? jb.nsteps : 16); t8 += 4) {
; #pragma unroll
;                 for (int u = 0; u < 4; ++u) {
;                     const int tt = t8 + u;
;                     const unsigned char* tb = buf + tt * SC_TOKB + c0 * 4;
;                     const f32x4 a = *(const f32x4*)(tb), w = *(const f32x4*)(tb + 256), b = *(const f32x4*)(tb + 512), k = *(const f32x4*)(tb + 768), r = *(const f32x4*)(tb + 1024);
;                     const float v = *(const float*)(buf + tt * SC_TOKB + 1280 + rl * 4);
;                     const f32x2 a01 = (f32x2){a[0], a[1]}, a23 = (f32x2){a[2], a[3]}, w01 = (f32x2){w[0], w[1]}, w23 = (f32x2){w[2], w[3]}, b01 = (f32x2){b[0], b[1]}, b23 = (f32x2){b[2], b[3]};
;                     const f32x2 k01 = (f32x2){k[0], k[1]}, k23 = (f32x2){k[2], k[3]}, r01 = (f32x2){r[0], r[1]}, r23 = (f32x2){r[2], r[3]};
;                     const f32x2 pa = s01 * a01 + s23 * a23;
;                     const float sa = allsum16(pa.x + pa.y);
;                     const f32x2 kv01 = k01 * v, kv23 = k23 * v;
;                     s01 = s01 * w01 + (b01 * sa + kv01); s23 = s23 * w23 + (b23 * sa + kv23);
;                     const f32x2 py = s01 * r01 + s23 * r23;
;                     const float y = allsum16(py.x + py.y);
;                     if ((lane & 15) == (tt & 15)) yreg0 = y;
;                 }
;             }
	ds_read_b128 v[146:149], v217 offset:6720
	ds_read_b128 v[150:153], v217 offset:6976
	ds_read_b128 v[154:157], v217 offset:7232
	ds_read_b128 v[158:161], v217 offset:7488
	ds_read_b128 v[162:165], v217 offset:7744
	ds_read_b32 v30, v218 offset:6720
	v_pk_mul_f32 v[206:207], v[24:25], v[188:189]
	v_pk_mul_f32 v[208:209], v[24:25], v[50:51]
	v_pk_fma_f32 v[206:207], v[22:23], v[186:187], v[206:207]
	v_pk_fma_f32 v[208:209], v[22:23], v[48:49], v[208:209]
	v_pk_mul_f32 v[210:211], v[198:199], v[52:53] op_sel_hi:[1,0]
	v_add_f32_e32 v214, v206, v207
	v_add_f32_e32 v216, v208, v209
	v_pk_mul_f32 v[212:213], v[200:201], v[52:53] op_sel_hi:[1,0]
	v_add_f32_dpp v214, v214, v214 quad_perm:[1,0,3,2] row_mask:0xf bank_mask:0xf bound_ctrl:1
	v_add_f32_dpp v216, v216, v216 quad_perm:[1,0,3,2] row_mask:0xf bank_mask:0xf bound_ctrl:1
	v_pk_fma_f32 v[210:211], v[22:23], v[190:191], v[210:211]
	v_add_f32_dpp v214, v214, v214 quad_perm:[2,3,0,1] row_mask:0xf bank_mask:0xf bound_ctrl:1
	v_add_f32_dpp v216, v216, v216 quad_perm:[2,3,0,1] row_mask:0xf bank_mask:0xf bound_ctrl:1
	v_pk_fma_f32 v[212:213], v[24:25], v[192:193], v[212:213]
	v_add_f32_dpp v214, v214, v214 row_half_mirror row_mask:0xf bank_mask:0xf bound_ctrl:1
	v_add_f32_dpp v216, v216, v216 row_half_mirror row_mask:0xf bank_mask:0xf bound_ctrl:1
	v_cmp_eq_u32_e32 vcc, 2, v106
	v_add_f32_dpp v214, v214, v214 row_mirror row_mask:0xf bank_mask:0xf bound_ctrl:1
	v_add_f32_dpp v216, v216, v216 row_mirror row_mask:0xf bank_mask:0xf bound_ctrl:1
	v_pk_fma_f32 v[22:23], v[194:195], v[214:215], v[210:211] op_sel_hi:[1,0,1]
	v_pk_fma_f32 v[24:25], v[196:197], v[214:215], v[212:213] op_sel_hi:[1,0,1]
	v_cndmask_b32_e32 v18, v18, v216, vcc
	s_waitcnt lgkmcnt(6)
	ds_read_b128 v[32:35], v217 offset:8064
	ds_read_b128 v[36:39], v217 offset:8320
	ds_read_b128 v[40:43], v217 offset:8576
	ds_read_b128 v[44:47], v217 offset:8832
	ds_read_b128 v[48:51], v217 offset:9088
	ds_read_b32 v92, v218 offset:8064
	v_pk_mul_f32 v[206:207], v[24:25], v[122:123]
	v_pk_mul_f32 v[208:209], v[24:25], v[204:205]
	v_pk_fma_f32 v[206:207], v[22:23], v[120:121], v[206:207]
	v_pk_fma_f32 v[208:209], v[22:23], v[202:203], v[208:209]
	v_pk_mul_f32 v[210:211], v[132:133], v[28:29] op_sel_hi:[1,0]
	v_add_f32_e32 v214, v206, v207
	v_add_f32_e32 v216, v208, v209
	v_pk_mul_f32 v[212:213], v[134:135], v[28:29] op_sel_hi:[1,0]
	v_add_f32_dpp v214, v214, v214 quad_perm:[1,0,3,2] row_mask:0xf bank_mask:0xf bound_ctrl:1
	v_add_f32_dpp v216, v216, v216 quad_perm:[1,0,3,2] row_mask:0xf bank_mask:0xf bound_ctrl:1
	v_pk_fma_f32 v[210:211], v[22:23], v[124:125], v[210:211]
	v_add_f32_dpp v214, v214, v214 quad_perm:[2,3,0,1] row_mask:0xf bank_mask:0xf bound_ctrl:1
	v_add_f32_dpp v216, v216, v216 quad_perm:[2,3,0,1] row_mask:0xf bank_mask:0xf bound_ctrl:1
	v_pk_fma_f32 v[212:213], v[24:25], v[126:127], v[212:213]
	v_add_f32_dpp v214, v214, v214 row_half_mirror row_mask:0xf bank_mask:0xf bound_ctrl:1
	v_add_f32_dpp v216, v216, v216 row_half_mirror row_mask:0xf bank_mask:0xf bound_ctrl:1
	v_cmp_eq_u32_e32 vcc, 3, v106
	v_add_f32_dpp v214, v214, v214 row_mirror row_mask:0xf bank_mask:0xf bound_ctrl:1
	v_add_f32_dpp v216, v216, v216 row_mirror row_mask:0xf bank_mask:0xf bound_ctrl:1
	v_pk_fma_f32 v[22:23], v[128:129], v[214:215], v[210:211] op_sel_hi:[1,0,1]
	v_pk_fma_f32 v[24:25], v[130:131], v[214:215], v[212:213] op_sel_hi:[1,0,1]
	v_cndmask_b32_e32 v18, v18, v216, vcc
	s_waitcnt lgkmcnt(6)
	ds_read_b128 v[186:189], v217 offset:9408
	ds_read_b128 v[190:193], v217 offset:9664
	ds_read_b128 v[194:197], v217 offset:9920
	ds_read_b128 v[198:201], v217 offset:10176
	ds_read_b128 v[202:205], v217 offset:10432
	ds_read_b32 v52, v218 offset:9408
	v_pk_mul_f32 v[206:207], v[24:25], v[148:149]
	v_pk_mul_f32 v[208:209], v[24:25], v[138:139]
	v_pk_fma_f32 v[206:207], v[22:23], v[146:147], v[206:207]
	v_pk_fma_f32 v[208:209], v[22:23], v[136:137], v[208:209]
	v_pk_mul_f32 v[210:211], v[158:159], v[30:31] op_sel_hi:[1,0]
	v_add_f32_e32 v214, v206, v207
	v_add_f32_e32 v216, v208, v209
	v_pk_mul_f32 v[212:213], v[160:161], v[30:31] op_sel_hi:[1,0]
	v_add_f32_dpp v214, v214, v214 quad_perm:[1,0,3,2] row_mask:0xf bank_mask:0xf bound_ctrl:1
	v_add_f32_dpp v216, v216, v216 quad_perm:[1,0,3,2] row_mask:0xf bank_mask:0xf bound_ctrl:1
	v_pk_fma_f32 v[210:211], v[22:23], v[150:151], v[210:211]
	v_add_f32_dpp v214, v214, v214 quad_perm:[2,3,0,1] row_mask:0xf bank_mask:0xf bound_ctrl:1
	v_add_f32_dpp v216, v216, v216 quad_perm:[2,3,0,1] row_mask:0xf bank_mask:0xf bound_ctrl:1
	v_pk_fma_f32 v[212:213], v[24:25], v[152:153], v[212:213]
	v_add_f32_dpp v214, v214, v214 row_half_mirror row_mask:0xf bank_mask:0xf bound_ctrl:1
	v_add_f32_dpp v216, v216, v216 row_half_mirror row_mask:0xf bank_mask:0xf bound_ctrl:1
	v_cmp_eq_u32_e32 vcc, 4, v106
	v_add_f32_dpp v214, v214, v214 row_mirror row_mask:0xf bank_mask:0xf bound_ctrl:1
	v_add_f32_dpp v216, v216, v216 row_mirror row_mask:0xf bank_mask:0xf bound_ctrl:1
	v_pk_fma_f32 v[22:23], v[154:155], v[214:215], v[210:211] op_sel_hi:[1,0,1]
	v_pk_fma_f32 v[24:25], v[156:157], v[214:215], v[212:213] op_sel_hi:[1,0,1]
	v_cndmask_b32_e32 v18, v18, v216, vcc
	s_waitcnt lgkmcnt(6)
; __device__ void phase_scan(int l, unsigned char* lds) {
;     ...
;             for (int t8 = 0; t8 < (jb.nsteps < 16 ? jb.nsteps : 16); t8 += 4) {
; #pragma unroll
;                 for (int u = 0; u < 4; ++u) {
;                     const int tt = t8 + u;
;                     const unsigned char* tb = buf + tt * SC_TOKB + c0 * 4;
;                     const f32x4 a = *(const f32x4*)(tb), w = *(const f32x4*)(tb + 256), b = *(const f32x4*)(tb + 512), k = *(const f32x4*)(tb + 768), r = *(const f32x4*)(tb + 1024);
;                     const float v = *(const float*)(buf + tt * SC_TOKB + 1280 + rl * 4);
;                     const f32x2 a01 = (f32x2){a[0], a[1]}, a23 = (f32x2){a[2], a[3]}, w01 = (f32x2){w[0], w[1]}, w23 = (f32x2){w[2], w[3]}, b01 = (f32x2){b[0], b[1]}, b23 = (f32x2){b[2], b[3]};
;                     const f32x2 k01 = (f32x2){k[0], k[1]}, k23 = (f32x2){k[2], k[3]}, r01 = (f32x2){r[0], r[1]}, r23 = (f32x2){r[2], r[3]};
;                     const f32x2 pa = s01 * a01 + s23 * a23;
;                     const float sa = allsum16(pa.x + pa.y);
;                     const f32x2 kv01 = k01 * v, kv23 = k23 * v;
;                     s01 = s01 * w01 + (b01 * sa + kv01); s23 = s23 * w23 + (b23 * sa + kv23);
;                     const f32x2 py = s01 * r01 + s23 * r23;
;                     const float y = allsum16(py.x + py.y);
;                     if ((lane & 15) == (tt & 15)) yreg0 = y;
;                 }
;             }
	ds_read_b128 v[120:123], v217 offset:10752
	ds_read_b128 v[124:127], v217 offset:11008
	ds_read_b128 v[128:131], v217 offset:11264
	ds_read_b128 v[132:135], v217 offset:11520
	ds_read_b128 v[136:139], v217 offset:11776
	ds_read_b32 v28, v218 offset:10752
	v_pk_mul_f32 v[206:207], v[24:25], v[34:35]
	v_pk_mul_f32 v[208:209], v[24:25], v[164:165]
	v_pk_fma_f32 v[206:207], v[22:23], v[32:33], v[206:207]
	v_pk_fma_f32 v[208:209], v[22:23], v[162:163], v[208:209]
	v_pk_mul_f32 v[210:211], v[44:45], v[92:93] op_sel_hi:[1,0]
	v_add_f32_e32 v214, v206, v207
	v_add_f32_e32 v216, v208, v209
	v_pk_mul_f32 v[212:213], v[46:47], v[92:93] op_sel_hi:[1,0]
	v_add_f32_dpp v214, v214, v214 quad_perm:[1,0,3,2] row_mask:0xf bank_mask:0xf bound_ctrl:1
	v_add_f32_dpp v216, v216, v216 quad_perm:[1,0,3,2] row_mask:0xf bank_mask:0xf bound_ctrl:1
	v_pk_fma_f32 v[210:211], v[22:23], v[36:37], v[210:211]
	v_add_f32_dpp v214, v214, v214 quad_perm:[2,3,0,1] row_mask:0xf bank_mask:0xf bound_ctrl:1
	v_add_f32_dpp v216, v216, v216 quad_perm:[2,3,0,1] row_mask:0xf bank_mask:0xf bound_ctrl:1
	v_pk_fma_f32 v[212:213], v[24:25], v[38:39], v[212:213]
	v_add_f32_dpp v214, v214, v214 row_half_mirror row_mask:0xf bank_mask:0xf bound_ctrl:1
	v_add_f32_dpp v216, v216, v216 row_half_mirror row_mask:0xf bank_mask:0xf bound_ctrl:1
	v_cmp_eq_u32_e32 vcc, 5, v106
	v_add_f32_dpp v214, v214, v214 row_mirror row_mask:0xf bank_mask:0xf bound_ctrl:1
	v_add_f32_dpp v216, v216, v216 row_mirror row_mask:0xf bank_mask:0xf bound_ctrl:1
	v_pk_fma_f32 v[22:23], v[40:41], v[214:215], v[210:211] op_sel_hi:[1,0,1]
	v_pk_fma_f32 v[24:25], v[42:43], v[214:215], v[212:213] op_sel_hi:[1,0,1]
	v_cndmask_b32_e32 v18, v18, v216, vcc
	s_waitcnt lgkmcnt(6)
	ds_read_b128 v[146:149], v217 offset:12096
	ds_read_b128 v[150:153], v217 offset:12352
	ds_read_b128 v[154:157], v217 offset:12608
	ds_read_b128 v[158:161], v217 offset:12864
	ds_read_b128 v[162:165], v217 offset:13120
	ds_read_b32 v30, v218 offset:12096
	v_pk_mul_f32 v[206:207], v[24:25], v[188:189]
	v_pk_mul_f32 v[208:209], v[24:25], v[50:51]
	v_pk_fma_f32 v[206:207], v[22:23], v[186:187], v[206:207]
	v_pk_fma_f32 v[208:209], v[22:23], v[48:49], v[208:209]
	v_pk_mul_f32 v[210:211], v[198:199], v[52:53] op_sel_hi:[1,0]
	v_add_f32_e32 v214, v206, v207
	v_add_f32_e32 v216, v208, v209
	v_pk_mul_f32 v[212:213], v[200:201], v[52:53] op_sel_hi:[1,0]
	v_add_f32_dpp v214, v214, v214 quad_perm:[1,0,3,2] row_mask:0xf bank_mask:0xf bound_ctrl:1
	v_add_f32_dpp v216, v216, v216 quad_perm:[1,0,3,2] row_mask:0xf bank_mask:0xf bound_ctrl:1
	v_pk_fma_f32 v[210:211], v[22:23], v[190:191], v[210:211]
	v_add_f32_dpp v214, v214, v214 quad_perm:[2,3,0,1] row_mask:0xf bank_mask:0xf bound_ctrl:1
	v_add_f32_dpp v216, v216, v216 quad_perm:[2,3,0,1] row_mask:0xf bank_mask:0xf bound_ctrl:1
	v_pk_fma_f32 v[212:213], v[24:25], v[192:193], v[212:213]
	v_add_f32_dpp v214, v214, v214 row_half_mirror row_mask:0xf bank_mask:0xf bound_ctrl:1
	v_add_f32_dpp v216, v216, v216 row_half_mirror row_mask:0xf bank_mask:0xf bound_ctrl:1
	v_cmp_eq_u32_e32 vcc, 6, v106
	v_add_f32_dpp v214, v214, v214 row_mirror row_mask:0xf bank_mask:0xf bound_ctrl:1
	v_add_f32_dpp v216, v216, v216 row_mirror row_mask:0xf bank_mask:0xf bound_ctrl:1
	v_pk_fma_f32 v[22:23], v[194:195], v[214:215], v[210:211] op_sel_hi:[1,0,1]
	v_pk_fma_f32 v[24:25], v[196:197], v[214:215], v[212:213] op_sel_hi:[1,0,1]
	v_cndmask_b32_e32 v18, v18, v216, vcc
	s_waitcnt lgkmcnt(6)
	ds_read_b128 v[32:35], v217 offset:13440
	ds_read_b128 v[36:39], v217 offset:13696
	ds_read_b128 v[40:43], v217 offset:13952
	ds_read_b128 v[44:47], v217 offset:14208
	ds_read_b128 v[48:51], v217 offset:14464
	ds_read_b32 v92, v218 offset:13440
	v_pk_mul_f32 v[206:207], v[24:25], v[122:123]
	v_pk_mul_f32 v[208:209], v[24:25], v[204:205]
	v_pk_fma_f32 v[206:207], v[22:23], v[120:121], v[206:207]
	v_pk_fma_f32 v[208:209], v[22:23], v[202:203], v[208:209]
	v_pk_mul_f32 v[210:211], v[132:133], v[28:29] op_sel_hi:[1,0]
	v_add_f32_e32 v214, v206, v207
	v_add_f32_e32 v216, v208, v209
	v_pk_mul_f32 v[212:213], v[134:135], v[28:29] op_sel_hi:[1,0]
	v_add_f32_dpp v214, v214, v214 quad_perm:[1,0,3,2] row_mask:0xf bank_mask:0xf bound_ctrl:1
	v_add_f32_dpp v216, v216, v216 quad_perm:[1,0,3,2] row_mask:0xf bank_mask:0xf bound_ctrl:1
	v_pk_fma_f32 v[210:211], v[22:23], v[124:125], v[210:211]
	v_add_f32_dpp v214, v214, v214 quad_perm:[2,3,0,1] row_mask:0xf bank_mask:0xf bound_ctrl:1
	v_add_f32_dpp v216, v216, v216 quad_perm:[2,3,0,1] row_mask:0xf bank_mask:0xf bound_ctrl:1
	v_pk_fma_f32 v[212:213], v[24:25], v[126:127], v[212:213]
	v_add_f32_dpp v214, v214, v214 row_half_mirror row_mask:0xf bank_mask:0xf bound_ctrl:1
	v_add_f32_dpp v216, v216, v216 row_half_mirror row_mask:0xf bank_mask:0xf bound_ctrl:1
	v_cmp_eq_u32_e32 vcc, 7, v106
	v_add_f32_dpp v214, v214, v214 row_mirror row_mask:0xf bank_mask:0xf bound_ctrl:1
	v_add_f32_dpp v216, v216, v216 row_mirror row_mask:0xf bank_mask:0xf bound_ctrl:1
	v_pk_fma_f32 v[22:23], v[128:129], v[214:215], v[210:211] op_sel_hi:[1,0,1]
	v_pk_fma_f32 v[24:25], v[130:131], v[214:215], v[212:213] op_sel_hi:[1,0,1]
	v_cndmask_b32_e32 v18, v18, v216, vcc
	s_waitcnt lgkmcnt(6)
; __device__ void phase_scan(int l, unsigned char* lds) {
;     ...
;             for (int t8 = 0; t8 < (jb.nsteps < 16 ? jb.nsteps : 16); t8 += 4) {
; #pragma unroll
;                 for (int u = 0; u < 4; ++u) {
;                     const int tt = t8 + u;
;                     const unsigned char* tb = buf + tt * SC_TOKB + c0 * 4;
;                     const f32x4 a = *(const f32x4*)(tb), w = *(const f32x4*)(tb + 256), b = *(const f32x4*)(tb + 512), k = *(const f32x4*)(tb + 768), r = *(const f32x4*)(tb + 1024);
;                     const float v = *(const float*)(buf + tt * SC_TOKB + 1280 + rl * 4);
;                     const f32x2 a01 = (f32x2){a[0], a[1]}, a23 = (f32x2){a[2], a[3]}, w01 = (f32x2){w[0], w[1]}, w23 = (f32x2){w[2], w[3]}, b01 = (f32x2){b[0], b[1]}, b23 = (f32x2){b[2], b[3]};
;                     const f32x2 k01 = (f32x2){k[0], k[1]}, k23 = (f32x2){k[2], k[3]}, r01 = (f32x2){r[0], r[1]}, r23 = (f32x2){r[2], r[3]};
;                     const f32x2 pa = s01 * a01 + s23 * a23;
;                     const float sa = allsum16(pa.x + pa.y);
;                     const f32x2 kv01 = k01 * v, kv23 = k23 * v;
;                     s01 = s01 * w01 + (b01 * sa + kv01); s23 = s23 * w23 + (b23 * sa + kv23);
;                     const f32x2 py = s01 * r01 + s23 * r23;
;                     const float y = allsum16(py.x + py.y);
;                     if ((lane & 15) == (tt & 15)) yreg0 = y;
;                 }
;             }
	ds_read_b128 v[186:189], v217 offset:14784
	ds_read_b128 v[190:193], v217 offset:15040
	ds_read_b128 v[194:197], v217 offset:15296
	ds_read_b128 v[198:201], v217 offset:15552
	ds_read_b128 v[202:205], v217 offset:15808
	ds_read_b32 v52, v218 offset:14784
	v_pk_mul_f32 v[206:207], v[24:25], v[148:149]
	v_pk_mul_f32 v[208:209], v[24:25], v[138:139]
	v_pk_fma_f32 v[206:207], v[22:23], v[146:147], v[206:207]
	v_pk_fma_f32 v[208:209], v[22:23], v[136:137], v[208:209]
	v_pk_mul_f32 v[210:211], v[158:159], v[30:31] op_sel_hi:[1,0]
	v_add_f32_e32 v214, v206, v207
	v_add_f32_e32 v216, v208, v209
	v_pk_mul_f32 v[212:213], v[160:161], v[30:31] op_sel_hi:[1,0]
	v_add_f32_dpp v214, v214, v214 quad_perm:[1,0,3,2] row_mask:0xf bank_mask:0xf bound_ctrl:1
	v_add_f32_dpp v216, v216, v216 quad_perm:[1,0,3,2] row_mask:0xf bank_mask:0xf bound_ctrl:1
	v_pk_fma_f32 v[210:211], v[22:23], v[150:151], v[210:211]
	v_add_f32_dpp v214, v214, v214 quad_perm:[2,3,0,1] row_mask:0xf bank_mask:0xf bound_ctrl:1
	v_add_f32_dpp v216, v216, v216 quad_perm:[2,3,0,1] row_mask:0xf bank_mask:0xf bound_ctrl:1
	v_pk_fma_f32 v[212:213], v[24:25], v[152:153], v[212:213]
	v_add_f32_dpp v214, v214, v214 row_half_mirror row_mask:0xf bank_mask:0xf bound_ctrl:1
	v_add_f32_dpp v216, v216, v216 row_half_mirror row_mask:0xf bank_mask:0xf bound_ctrl:1
	v_cmp_eq_u32_e32 vcc, 8, v106
	v_add_f32_dpp v214, v214, v214 row_mirror row_mask:0xf bank_mask:0xf bound_ctrl:1
	v_add_f32_dpp v216, v216, v216 row_mirror row_mask:0xf bank_mask:0xf bound_ctrl:1
	v_pk_fma_f32 v[22:23], v[154:155], v[214:215], v[210:211] op_sel_hi:[1,0,1]
	v_pk_fma_f32 v[24:25], v[156:157], v[214:215], v[212:213] op_sel_hi:[1,0,1]
	v_cndmask_b32_e32 v18, v18, v216, vcc
	s_waitcnt lgkmcnt(6)
	ds_read_b128 v[120:123], v217 offset:16128
	ds_read_b128 v[124:127], v217 offset:16384
	ds_read_b128 v[128:131], v217 offset:16640
	ds_read_b128 v[132:135], v217 offset:16896
	ds_read_b128 v[136:139], v217 offset:17152
	ds_read_b32 v28, v218 offset:16128
	v_pk_mul_f32 v[206:207], v[24:25], v[34:35]
	v_pk_mul_f32 v[208:209], v[24:25], v[164:165]
	v_pk_fma_f32 v[206:207], v[22:23], v[32:33], v[206:207]
	v_pk_fma_f32 v[208:209], v[22:23], v[162:163], v[208:209]
	v_pk_mul_f32 v[210:211], v[44:45], v[92:93] op_sel_hi:[1,0]
	v_add_f32_e32 v214, v206, v207
	v_add_f32_e32 v216, v208, v209
	v_pk_mul_f32 v[212:213], v[46:47], v[92:93] op_sel_hi:[1,0]
	v_add_f32_dpp v214, v214, v214 quad_perm:[1,0,3,2] row_mask:0xf bank_mask:0xf bound_ctrl:1
	v_add_f32_dpp v216, v216, v216 quad_perm:[1,0,3,2] row_mask:0xf bank_mask:0xf bound_ctrl:1
	v_pk_fma_f32 v[210:211], v[22:23], v[36:37], v[210:211]
	v_add_f32_dpp v214, v214, v214 quad_perm:[2,3,0,1] row_mask:0xf bank_mask:0xf bound_ctrl:1
	v_add_f32_dpp v216, v216, v216 quad_perm:[2,3,0,1] row_mask:0xf bank_mask:0xf bound_ctrl:1
	v_pk_fma_f32 v[212:213], v[24:25], v[38:39], v[212:213]
	v_add_f32_dpp v214, v214, v214 row_half_mirror row_mask:0xf bank_mask:0xf bound_ctrl:1
	v_add_f32_dpp v216, v216, v216 row_half_mirror row_mask:0xf bank_mask:0xf bound_ctrl:1
	v_cmp_eq_u32_e32 vcc, 9, v106
	v_add_f32_dpp v214, v214, v214 row_mirror row_mask:0xf bank_mask:0xf bound_ctrl:1
	v_add_f32_dpp v216, v216, v216 row_mirror row_mask:0xf bank_mask:0xf bound_ctrl:1
	v_pk_fma_f32 v[22:23], v[40:41], v[214:215], v[210:211] op_sel_hi:[1,0,1]
	v_pk_fma_f32 v[24:25], v[42:43], v[214:215], v[212:213] op_sel_hi:[1,0,1]
	v_cndmask_b32_e32 v18, v18, v216, vcc
	s_waitcnt lgkmcnt(6)
	ds_read_b128 v[146:149], v217 offset:17472
	ds_read_b128 v[150:153], v217 offset:17728
	ds_read_b128 v[154:157], v217 offset:17984
	ds_read_b128 v[158:161], v217 offset:18240
	ds_read_b128 v[162:165], v217 offset:18496
	ds_read_b32 v30, v218 offset:17472
	v_pk_mul_f32 v[206:207], v[24:25], v[188:189]
	v_pk_mul_f32 v[208:209], v[24:25], v[50:51]
	v_pk_fma_f32 v[206:207], v[22:23], v[186:187], v[206:207]
	v_pk_fma_f32 v[208:209], v[22:23], v[48:49], v[208:209]
	v_pk_mul_f32 v[210:211], v[198:199], v[52:53] op_sel_hi:[1,0]
	v_add_f32_e32 v214, v206, v207
	v_add_f32_e32 v216, v208, v209
	v_pk_mul_f32 v[212:213], v[200:201], v[52:53] op_sel_hi:[1,0]
	v_add_f32_dpp v214, v214, v214 quad_perm:[1,0,3,2] row_mask:0xf bank_mask:0xf bound_ctrl:1
	v_add_f32_dpp v216, v216, v216 quad_perm:[1,0,3,2] row_mask:0xf bank_mask:0xf bound_ctrl:1
	v_pk_fma_f32 v[210:211], v[22:23], v[190:191], v[210:211]
	v_add_f32_dpp v214, v214, v214 quad_perm:[2,3,0,1] row_mask:0xf bank_mask:0xf bound_ctrl:1
	v_add_f32_dpp v216, v216, v216 quad_perm:[2,3,0,1] row_mask:0xf bank_mask:0xf bound_ctrl:1
	v_pk_fma_f32 v[212:213], v[24:25], v[192:193], v[212:213]
	v_add_f32_dpp v214, v214, v214 row_half_mirror row_mask:0xf bank_mask:0xf bound_ctrl:1
	v_add_f32_dpp v216, v216, v216 row_half_mirror row_mask:0xf bank_mask:0xf bound_ctrl:1
	v_cmp_eq_u32_e32 vcc, 10, v106
	v_add_f32_dpp v214, v214, v214 row_mirror row_mask:0xf bank_mask:0xf bound_ctrl:1
	v_add_f32_dpp v216, v216, v216 row_mirror row_mask:0xf bank_mask:0xf bound_ctrl:1
	v_pk_fma_f32 v[22:23], v[194:195], v[214:215], v[210:211] op_sel_hi:[1,0,1]
	v_pk_fma_f32 v[24:25], v[196:197], v[214:215], v[212:213] op_sel_hi:[1,0,1]
	v_cndmask_b32_e32 v18, v18, v216, vcc
	s_waitcnt lgkmcnt(6)
; __device__ void phase_scan(int l, unsigned char* lds) {
;     ...
;             for (int t8 = 0; t8 < (jb.nsteps < 16 ? jb.nsteps : 16); t8 += 4) {
; #pragma unroll
;                 for (int u = 0; u < 4; ++u) {
;                     const int tt = t8 + u;
;                     const unsigned char* tb = buf + tt * SC_TOKB + c0 * 4;
;                     const f32x4 a = *(const f32x4*)(tb), w = *(const f32x4*)(tb + 256), b = *(const f32x4*)(tb + 512), k = *(const f32x4*)(tb + 768), r = *(const f32x4*)(tb + 1024);
;                     const float v = *(const float*)(buf + tt * SC_TOKB + 1280 + rl * 4);
;                     const f32x2 a01 = (f32x2){a[0], a[1]}, a23 = (f32x2){a[2], a[3]}, w01 = (f32x2){w[0], w[1]}, w23 = (f32x2){w[2], w[3]}, b01 = (f32x2){b[0], b[1]}, b23 = (f32x2){b[2], b[3]};
;                     const f32x2 k01 = (f32x2){k[0], k[1]}, k23 = (f32x2){k[2], k[3]}, r01 = (f32x2){r[0], r[1]}, r23 = (f32x2){r[2], r[3]};
;                     const f32x2 pa = s01 * a01 + s23 * a23;
;                     const float sa = allsum16(pa.x + pa.y);
;                     const f32x2 kv01 = k01 * v, kv23 = k23 * v;
;                     s01 = s01 * w01 + (b01 * sa + kv01); s23 = s23 * w23 + (b23 * sa + kv23);
;                     const f32x2 py = s01 * r01 + s23 * r23;
;                     const float y = allsum16(py.x + py.y);
;                     if ((lane & 15) == (tt & 15)) yreg0 = y;
;                 }
;             }
	ds_read_b128 v[32:35], v217 offset:18816
	ds_read_b128 v[36:39], v217 offset:19072
	ds_read_b128 v[40:43], v217 offset:19328
	ds_read_b128 v[44:47], v217 offset:19584
	ds_read_b128 v[48:51], v217 offset:19840
	ds_read_b32 v92, v218 offset:18816
	v_pk_mul_f32 v[206:207], v[24:25], v[122:123]
	v_pk_mul_f32 v[208:209], v[24:25], v[204:205]
	v_pk_fma_f32 v[206:207], v[22:23], v[120:121], v[206:207]
	v_pk_fma_f32 v[208:209], v[22:23], v[202:203], v[208:209]
	v_pk_mul_f32 v[210:211], v[132:133], v[28:29] op_sel_hi:[1,0]
	v_add_f32_e32 v214, v206, v207
	v_add_f32_e32 v216, v208, v209
	v_pk_mul_f32 v[212:213], v[134:135], v[28:29] op_sel_hi:[1,0]
	v_add_f32_dpp v214, v214, v214 quad_perm:[1,0,3,2] row_mask:0xf bank_mask:0xf bound_ctrl:1
	v_add_f32_dpp v216, v216, v216 quad_perm:[1,0,3,2] row_mask:0xf bank_mask:0xf bound_ctrl:1
	v_pk_fma_f32 v[210:211], v[22:23], v[124:125], v[210:211]
	v_add_f32_dpp v214, v214, v214 quad_perm:[2,3,0,1] row_mask:0xf bank_mask:0xf bound_ctrl:1
	v_add_f32_dpp v216, v216, v216 quad_perm:[2,3,0,1] row_mask:0xf bank_mask:0xf bound_ctrl:1
	v_pk_fma_f32 v[212:213], v[24:25], v[126:127], v[212:213]
	v_add_f32_dpp v214, v214, v214 row_half_mirror row_mask:0xf bank_mask:0xf bound_ctrl:1
	v_add_f32_dpp v216, v216, v216 row_half_mirror row_mask:0xf bank_mask:0xf bound_ctrl:1
	v_cmp_eq_u32_e32 vcc, 11, v106
	v_add_f32_dpp v214, v214, v214 row_mirror row_mask:0xf bank_mask:0xf bound_ctrl:1
	v_add_f32_dpp v216, v216, v216 row_mirror row_mask:0xf bank_mask:0xf bound_ctrl:1
	v_pk_fma_f32 v[22:23], v[128:129], v[214:215], v[210:211] op_sel_hi:[1,0,1]
	v_pk_fma_f32 v[24:25], v[130:131], v[214:215], v[212:213] op_sel_hi:[1,0,1]
	v_cndmask_b32_e32 v18, v18, v216, vcc
	s_waitcnt lgkmcnt(6)
	ds_read_b128 v[186:189], v217 offset:20160
	ds_read_b128 v[190:193], v217 offset:20416
	ds_read_b128 v[194:197], v217 offset:20672
	ds_read_b128 v[198:201], v217 offset:20928
	ds_read_b128 v[202:205], v217 offset:21184
	ds_read_b32 v52, v218 offset:20160
	v_pk_mul_f32 v[206:207], v[24:25], v[148:149]
	v_pk_mul_f32 v[208:209], v[24:25], v[138:139]
	v_pk_fma_f32 v[206:207], v[22:23], v[146:147], v[206:207]
	v_pk_fma_f32 v[208:209], v[22:23], v[136:137], v[208:209]
	v_pk_mul_f32 v[210:211], v[158:159], v[30:31] op_sel_hi:[1,0]
	v_add_f32_e32 v214, v206, v207
	v_add_f32_e32 v216, v208, v209
	v_pk_mul_f32 v[212:213], v[160:161], v[30:31] op_sel_hi:[1,0]
	v_add_f32_dpp v214, v214, v214 quad_perm:[1,0,3,2] row_mask:0xf bank_mask:0xf bound_ctrl:1
	v_add_f32_dpp v216, v216, v216 quad_perm:[1,0,3,2] row_mask:0xf bank_mask:0xf bound_ctrl:1
	v_pk_fma_f32 v[210:211], v[22:23], v[150:151], v[210:211]
	v_add_f32_dpp v214, v214, v214 quad_perm:[2,3,0,1] row_mask:0xf bank_mask:0xf bound_ctrl:1
	v_add_f32_dpp v216, v216, v216 quad_perm:[2,3,0,1] row_mask:0xf bank_mask:0xf bound_ctrl:1
	v_pk_fma_f32 v[212:213], v[24:25], v[152:153], v[212:213]
	v_add_f32_dpp v214, v214, v214 row_half_mirror row_mask:0xf bank_mask:0xf bound_ctrl:1
	v_add_f32_dpp v216, v216, v216 row_half_mirror row_mask:0xf bank_mask:0xf bound_ctrl:1
	v_cmp_eq_u32_e32 vcc, 12, v106
	v_add_f32_dpp v214, v214, v214 row_mirror row_mask:0xf bank_mask:0xf bound_ctrl:1
	v_add_f32_dpp v216, v216, v216 row_mirror row_mask:0xf bank_mask:0xf bound_ctrl:1
	v_pk_fma_f32 v[22:23], v[154:155], v[214:215], v[210:211] op_sel_hi:[1,0,1]
	v_pk_fma_f32 v[24:25], v[156:157], v[214:215], v[212:213] op_sel_hi:[1,0,1]
	v_cndmask_b32_e32 v18, v18, v216, vcc
	s_waitcnt lgkmcnt(6)
	ds_read_b128 v[120:123], v217 offset:21504
	ds_read_b128 v[124:127], v217 offset:21760
	ds_read_b128 v[128:131], v217 offset:22016
	ds_read_b128 v[132:135], v217 offset:22272
	ds_read_b128 v[136:139], v217 offset:22528
	ds_read_b32 v28, v218 offset:21504
	v_pk_mul_f32 v[206:207], v[24:25], v[34:35]
	v_pk_mul_f32 v[208:209], v[24:25], v[164:165]
	v_pk_fma_f32 v[206:207], v[22:23], v[32:33], v[206:207]
	v_pk_fma_f32 v[208:209], v[22:23], v[162:163], v[208:209]
	v_pk_mul_f32 v[210:211], v[44:45], v[92:93] op_sel_hi:[1,0]
	v_add_f32_e32 v214, v206, v207
	v_add_f32_e32 v216, v208, v209
	v_pk_mul_f32 v[212:213], v[46:47], v[92:93] op_sel_hi:[1,0]
	v_add_f32_dpp v214, v214, v214 quad_perm:[1,0,3,2] row_mask:0xf bank_mask:0xf bound_ctrl:1
	v_add_f32_dpp v216, v216, v216 quad_perm:[1,0,3,2] row_mask:0xf bank_mask:0xf bound_ctrl:1
	v_pk_fma_f32 v[210:211], v[22:23], v[36:37], v[210:211]
	v_add_f32_dpp v214, v214, v214 quad_perm:[2,3,0,1] row_mask:0xf bank_mask:0xf bound_ctrl:1
	v_add_f32_dpp v216, v216, v216 quad_perm:[2,3,0,1] row_mask:0xf bank_mask:0xf bound_ctrl:1
	v_pk_fma_f32 v[212:213], v[24:25], v[38:39], v[212:213]
	v_add_f32_dpp v214, v214, v214 row_half_mirror row_mask:0xf bank_mask:0xf bound_ctrl:1
	v_add_f32_dpp v216, v216, v216 row_half_mirror row_mask:0xf bank_mask:0xf bound_ctrl:1
	v_cmp_eq_u32_e32 vcc, 13, v106
	v_add_f32_dpp v214, v214, v214 row_mirror row_mask:0xf bank_mask:0xf bound_ctrl:1
	v_add_f32_dpp v216, v216, v216 row_mirror row_mask:0xf bank_mask:0xf bound_ctrl:1
	v_pk_fma_f32 v[22:23], v[40:41], v[214:215], v[210:211] op_sel_hi:[1,0,1]
	v_pk_fma_f32 v[24:25], v[42:43], v[214:215], v[212:213] op_sel_hi:[1,0,1]
	v_cndmask_b32_e32 v18, v18, v216, vcc
	s_waitcnt lgkmcnt(6)
; __device__ void phase_scan(int l, unsigned char* lds) {
;     ...
;             for (int t8 = 0; t8 < (jb.nsteps < 16 ? jb.nsteps : 16); t8 += 4) {
; #pragma unroll
;                 for (int u = 0; u < 4; ++u) {
;                     const int tt = t8 + u;
;                     const unsigned char* tb = buf + tt * SC_TOKB + c0 * 4;
;                     const f32x4 a = *(const f32x4*)(tb), w = *(const f32x4*)(tb + 256), b = *(const f32x4*)(tb + 512), k = *(const f32x4*)(tb + 768), r = *(const f32x4*)(tb + 1024);
;                     const float v = *(const float*)(buf + tt * SC_TOKB + 1280 + rl * 4);
;                     const f32x2 a01 = (f32x2){a[0], a[1]}, a23 = (f32x2){a[2], a[3]}, w01 = (f32x2){w[0], w[1]}, w23 = (f32x2){w[2], w[3]}, b01 = (f32x2){b[0], b[1]}, b23 = (f32x2){b[2], b[3]};
;                     const f32x2 k01 = (f32x2){k[0], k[1]}, k23 = (f32x2){k[2], k[3]}, r01 = (f32x2){r[0], r[1]}, r23 = (f32x2){r[2], r[3]};
;                     const f32x2 pa = s01 * a01 + s23 * a23;
;                     const float sa = allsum16(pa.x + pa.y);
;                     const f32x2 kv01 = k01 * v, kv23 = k23 * v;
;                     s01 = s01 * w01 + (b01 * sa + kv01); s23 = s23 * w23 + (b23 * sa + kv23);
;                     const f32x2 py = s01 * r01 + s23 * r23;
;                     const float y = allsum16(py.x + py.y);
;                     if ((lane & 15) == (tt & 15)) yreg0 = y;
;                 }
;             }
;             for (int t8 = 16; t8 < (jb.nsteps < 32 ? jb.nsteps : 32); t8 += 4) {
; #pragma unroll
;                 for (int u = 0; u < 4; ++u) {
;                     const int tt = t8 + u;
;                     const unsigned char* tb = buf + tt * SC_TOKB + c0 * 4;
;                     const f32x4 a = *(const f32x4*)(tb), w = *(const f32x4*)(tb + 256), b = *(const f32x4*)(tb + 512), k = *(const f32x4*)(tb + 768), r = *(const f32x4*)(tb + 1024);
;                     const float v = *(const float*)(buf + tt * SC_TOKB + 1280 + rl * 4);
;                     const f32x2 a01 = (f32x2){a[0], a[1]}, a23 = (f32x2){a[2], a[3]}, w01 = (f32x2){w[0], w[1]}, w23 = (f32x2){w[2], w[3]}, b01 = (f32x2){b[0], b[1]}, b23 = (f32x2){b[2], b[3]};
;                     const f32x2 k01 = (f32x2){k[0], k[1]}, k23 = (f32x2){k[2], k[3]}, r01 = (f32x2){r[0], r[1]}, r23 = (f32x2){r[2], r[3]};
;                     const f32x2 pa = s01 * a01 + s23 * a23;
	ds_read_b128 v[146:149], v217 offset:22848
	ds_read_b128 v[150:153], v217 offset:23104
	ds_read_b128 v[154:157], v217 offset:23360
	ds_read_b128 v[158:161], v217 offset:23616
	ds_read_b128 v[162:165], v217 offset:23872
	ds_read_b32 v30, v218 offset:22848
	v_pk_mul_f32 v[206:207], v[24:25], v[188:189]
	v_pk_mul_f32 v[208:209], v[24:25], v[50:51]
	v_pk_fma_f32 v[206:207], v[22:23], v[186:187], v[206:207]
	v_pk_fma_f32 v[208:209], v[22:23], v[48:49], v[208:209]
	v_pk_mul_f32 v[210:211], v[198:199], v[52:53] op_sel_hi:[1,0]
	v_add_f32_e32 v214, v206, v207
	v_add_f32_e32 v216, v208, v209
	v_pk_mul_f32 v[212:213], v[200:201], v[52:53] op_sel_hi:[1,0]
	v_add_f32_dpp v214, v214, v214 quad_perm:[1,0,3,2] row_mask:0xf bank_mask:0xf bound_ctrl:1
	v_add_f32_dpp v216, v216, v216 quad_perm:[1,0,3,2] row_mask:0xf bank_mask:0xf bound_ctrl:1
	v_pk_fma_f32 v[210:211], v[22:23], v[190:191], v[210:211]
	v_add_f32_dpp v214, v214, v214 quad_perm:[2,3,0,1] row_mask:0xf bank_mask:0xf bound_ctrl:1
	v_add_f32_dpp v216, v216, v216 quad_perm:[2,3,0,1] row_mask:0xf bank_mask:0xf bound_ctrl:1
	v_pk_fma_f32 v[212:213], v[24:25], v[192:193], v[212:213]
	v_add_f32_dpp v214, v214, v214 row_half_mirror row_mask:0xf bank_mask:0xf bound_ctrl:1
	v_add_f32_dpp v216, v216, v216 row_half_mirror row_mask:0xf bank_mask:0xf bound_ctrl:1
	v_cmp_eq_u32_e32 vcc, 14, v106
	v_add_f32_dpp v214, v214, v214 row_mirror row_mask:0xf bank_mask:0xf bound_ctrl:1
	v_add_f32_dpp v216, v216, v216 row_mirror row_mask:0xf bank_mask:0xf bound_ctrl:1
	v_pk_fma_f32 v[22:23], v[194:195], v[214:215], v[210:211] op_sel_hi:[1,0,1]
	v_pk_fma_f32 v[24:25], v[196:197], v[214:215], v[212:213] op_sel_hi:[1,0,1]
	v_cndmask_b32_e32 v18, v18, v216, vcc
	s_waitcnt lgkmcnt(6)
	ds_read_b128 v[32:35], v217 offset:24192
	ds_read_b128 v[36:39], v217 offset:24448
	ds_read_b128 v[40:43], v217 offset:24704
	ds_read_b128 v[44:47], v217 offset:24960
	ds_read_b128 v[48:51], v217 offset:25216
	ds_read_b32 v92, v218 offset:24192
	v_pk_mul_f32 v[206:207], v[24:25], v[122:123]
	v_pk_mul_f32 v[208:209], v[24:25], v[204:205]
	v_pk_fma_f32 v[206:207], v[22:23], v[120:121], v[206:207]
	v_pk_fma_f32 v[208:209], v[22:23], v[202:203], v[208:209]
	v_pk_mul_f32 v[210:211], v[132:133], v[28:29] op_sel_hi:[1,0]
	v_add_f32_e32 v214, v206, v207
	v_add_f32_e32 v216, v208, v209
	v_pk_mul_f32 v[212:213], v[134:135], v[28:29] op_sel_hi:[1,0]
	v_add_f32_dpp v214, v214, v214 quad_perm:[1,0,3,2] row_mask:0xf bank_mask:0xf bound_ctrl:1
	v_add_f32_dpp v216, v216, v216 quad_perm:[1,0,3,2] row_mask:0xf bank_mask:0xf bound_ctrl:1
	v_pk_fma_f32 v[210:211], v[22:23], v[124:125], v[210:211]
	v_add_f32_dpp v214, v214, v214 quad_perm:[2,3,0,1] row_mask:0xf bank_mask:0xf bound_ctrl:1
	v_add_f32_dpp v216, v216, v216 quad_perm:[2,3,0,1] row_mask:0xf bank_mask:0xf bound_ctrl:1
	v_pk_fma_f32 v[212:213], v[24:25], v[126:127], v[212:213]
	v_add_f32_dpp v214, v214, v214 row_half_mirror row_mask:0xf bank_mask:0xf bound_ctrl:1
	v_add_f32_dpp v216, v216, v216 row_half_mirror row_mask:0xf bank_mask:0xf bound_ctrl:1
	v_cmp_eq_u32_e32 vcc, 15, v106
	v_add_f32_dpp v214, v214, v214 row_mirror row_mask:0xf bank_mask:0xf bound_ctrl:1
	v_add_f32_dpp v216, v216, v216 row_mirror row_mask:0xf bank_mask:0xf bound_ctrl:1
	v_pk_fma_f32 v[22:23], v[128:129], v[214:215], v[210:211] op_sel_hi:[1,0,1]
	v_pk_fma_f32 v[24:25], v[130:131], v[214:215], v[212:213] op_sel_hi:[1,0,1]
	v_cndmask_b32_e32 v18, v18, v216, vcc
	s_waitcnt lgkmcnt(6)
	ds_read_b128 v[186:189], v217 offset:25536
	ds_read_b128 v[190:193], v217 offset:25792
	ds_read_b128 v[194:197], v217 offset:26048
	ds_read_b128 v[198:201], v217 offset:26304
	ds_read_b128 v[202:205], v217 offset:26560
	ds_read_b32 v52, v218 offset:25536
	v_pk_mul_f32 v[206:207], v[24:25], v[148:149]
	v_pk_mul_f32 v[208:209], v[24:25], v[138:139]
	v_pk_fma_f32 v[206:207], v[22:23], v[146:147], v[206:207]
	v_pk_fma_f32 v[208:209], v[22:23], v[136:137], v[208:209]
	v_pk_mul_f32 v[210:211], v[158:159], v[30:31] op_sel_hi:[1,0]
	v_add_f32_e32 v214, v206, v207
	v_add_f32_e32 v216, v208, v209
	v_pk_mul_f32 v[212:213], v[160:161], v[30:31] op_sel_hi:[1,0]
	v_add_f32_dpp v214, v214, v214 quad_perm:[1,0,3,2] row_mask:0xf bank_mask:0xf bound_ctrl:1
	v_add_f32_dpp v216, v216, v216 quad_perm:[1,0,3,2] row_mask:0xf bank_mask:0xf bound_ctrl:1
	v_pk_fma_f32 v[210:211], v[22:23], v[150:151], v[210:211]
	v_add_f32_dpp v214, v214, v214 quad_perm:[2,3,0,1] row_mask:0xf bank_mask:0xf bound_ctrl:1
	v_add_f32_dpp v216, v216, v216 quad_perm:[2,3,0,1] row_mask:0xf bank_mask:0xf bound_ctrl:1
	v_pk_fma_f32 v[212:213], v[24:25], v[152:153], v[212:213]
	v_add_f32_dpp v214, v214, v214 row_half_mirror row_mask:0xf bank_mask:0xf bound_ctrl:1
	v_add_f32_dpp v216, v216, v216 row_half_mirror row_mask:0xf bank_mask:0xf bound_ctrl:1
	v_cmp_eq_u32_e32 vcc, 0, v106
	v_add_f32_dpp v214, v214, v214 row_mirror row_mask:0xf bank_mask:0xf bound_ctrl:1
	v_add_f32_dpp v216, v216, v216 row_mirror row_mask:0xf bank_mask:0xf bound_ctrl:1
	v_pk_fma_f32 v[22:23], v[154:155], v[214:215], v[210:211] op_sel_hi:[1,0,1]
	v_pk_fma_f32 v[24:25], v[156:157], v[214:215], v[212:213] op_sel_hi:[1,0,1]
	v_cndmask_b32_e32 v26, v26, v216, vcc
	s_waitcnt lgkmcnt(6)
; __device__ void phase_scan(int l, unsigned char* lds) {
;     ...
;             for (int t8 = 16; t8 < (jb.nsteps < 32 ? jb.nsteps : 32); t8 += 4) {
; #pragma unroll
;                 for (int u = 0; u < 4; ++u) {
;                     const int tt = t8 + u;
;                     const unsigned char* tb = buf + tt * SC_TOKB + c0 * 4;
;                     const f32x4 a = *(const f32x4*)(tb), w = *(const f32x4*)(tb + 256), b = *(const f32x4*)(tb + 512), k = *(const f32x4*)(tb + 768), r = *(const f32x4*)(tb + 1024);
;                     const float v = *(const float*)(buf + tt * SC_TOKB + 1280 + rl * 4);
;                     const f32x2 a01 = (f32x2){a[0], a[1]}, a23 = (f32x2){a[2], a[3]}, w01 = (f32x2){w[0], w[1]}, w23 = (f32x2){w[2], w[3]}, b01 = (f32x2){b[0], b[1]}, b23 = (f32x2){b[2], b[3]};
;                     const f32x2 k01 = (f32x2){k[0], k[1]}, k23 = (f32x2){k[2], k[3]}, r01 = (f32x2){r[0], r[1]}, r23 = (f32x2){r[2], r[3]};
;                     const f32x2 pa = s01 * a01 + s23 * a23;
;                     const float sa = allsum16(pa.x + pa.y);
;                     const f32x2 kv01 = k01 * v, kv23 = k23 * v;
;                     s01 = s01 * w01 + (b01 * sa + kv01); s23 = s23 * w23 + (b23 * sa + kv23);
;                     const f32x2 py = s01 * r01 + s23 * r23;
;                     const float y = allsum16(py.x + py.y);
;                     if ((lane & 15) == (tt & 15)) yreg1 = y;
;                 }
;             }
	ds_read_b128 v[120:123], v217 offset:26880
	ds_read_b128 v[124:127], v217 offset:27136
	ds_read_b128 v[128:131], v217 offset:27392
	ds_read_b128 v[132:135], v217 offset:27648
	ds_read_b128 v[136:139], v217 offset:27904
	ds_read_b32 v28, v218 offset:26880
	v_pk_mul_f32 v[206:207], v[24:25], v[34:35]
	v_pk_mul_f32 v[208:209], v[24:25], v[164:165]
	v_pk_fma_f32 v[206:207], v[22:23], v[32:33], v[206:207]
	v_pk_fma_f32 v[208:209], v[22:23], v[162:163], v[208:209]
	v_pk_mul_f32 v[210:211], v[44:45], v[92:93] op_sel_hi:[1,0]
	v_add_f32_e32 v214, v206, v207
	v_add_f32_e32 v216, v208, v209
	v_pk_mul_f32 v[212:213], v[46:47], v[92:93] op_sel_hi:[1,0]
	v_add_f32_dpp v214, v214, v214 quad_perm:[1,0,3,2] row_mask:0xf bank_mask:0xf bound_ctrl:1
	v_add_f32_dpp v216, v216, v216 quad_perm:[1,0,3,2] row_mask:0xf bank_mask:0xf bound_ctrl:1
	v_pk_fma_f32 v[210:211], v[22:23], v[36:37], v[210:211]
	v_add_f32_dpp v214, v214, v214 quad_perm:[2,3,0,1] row_mask:0xf bank_mask:0xf bound_ctrl:1
	v_add_f32_dpp v216, v216, v216 quad_perm:[2,3,0,1] row_mask:0xf bank_mask:0xf bound_ctrl:1
	v_pk_fma_f32 v[212:213], v[24:25], v[38:39], v[212:213]
	v_add_f32_dpp v214, v214, v214 row_half_mirror row_mask:0xf bank_mask:0xf bound_ctrl:1
	v_add_f32_dpp v216, v216, v216 row_half_mirror row_mask:0xf bank_mask:0xf bound_ctrl:1
	v_cmp_eq_u32_e32 vcc, 1, v106
	v_add_f32_dpp v214, v214, v214 row_mirror row_mask:0xf bank_mask:0xf bound_ctrl:1
	v_add_f32_dpp v216, v216, v216 row_mirror row_mask:0xf bank_mask:0xf bound_ctrl:1
	v_pk_fma_f32 v[22:23], v[40:41], v[214:215], v[210:211] op_sel_hi:[1,0,1]
	v_pk_fma_f32 v[24:25], v[42:43], v[214:215], v[212:213] op_sel_hi:[1,0,1]
	v_cndmask_b32_e32 v26, v26, v216, vcc
	s_waitcnt lgkmcnt(6)
	ds_read_b128 v[146:149], v217 offset:28224
	ds_read_b128 v[150:153], v217 offset:28480
	ds_read_b128 v[154:157], v217 offset:28736
	ds_read_b128 v[158:161], v217 offset:28992
	ds_read_b128 v[162:165], v217 offset:29248
	ds_read_b32 v30, v218 offset:28224
	v_pk_mul_f32 v[206:207], v[24:25], v[188:189]
	v_pk_mul_f32 v[208:209], v[24:25], v[50:51]
	v_pk_fma_f32 v[206:207], v[22:23], v[186:187], v[206:207]
	v_pk_fma_f32 v[208:209], v[22:23], v[48:49], v[208:209]
	v_pk_mul_f32 v[210:211], v[198:199], v[52:53] op_sel_hi:[1,0]
	v_add_f32_e32 v214, v206, v207
	v_add_f32_e32 v216, v208, v209
	v_pk_mul_f32 v[212:213], v[200:201], v[52:53] op_sel_hi:[1,0]
	v_add_f32_dpp v214, v214, v214 quad_perm:[1,0,3,2] row_mask:0xf bank_mask:0xf bound_ctrl:1
	v_add_f32_dpp v216, v216, v216 quad_perm:[1,0,3,2] row_mask:0xf bank_mask:0xf bound_ctrl:1
	v_pk_fma_f32 v[210:211], v[22:23], v[190:191], v[210:211]
	v_add_f32_dpp v214, v214, v214 quad_perm:[2,3,0,1] row_mask:0xf bank_mask:0xf bound_ctrl:1
	v_add_f32_dpp v216, v216, v216 quad_perm:[2,3,0,1] row_mask:0xf bank_mask:0xf bound_ctrl:1
	v_pk_fma_f32 v[212:213], v[24:25], v[192:193], v[212:213]
	v_add_f32_dpp v214, v214, v214 row_half_mirror row_mask:0xf bank_mask:0xf bound_ctrl:1
	v_add_f32_dpp v216, v216, v216 row_half_mirror row_mask:0xf bank_mask:0xf bound_ctrl:1
	v_cmp_eq_u32_e32 vcc, 2, v106
	v_add_f32_dpp v214, v214, v214 row_mirror row_mask:0xf bank_mask:0xf bound_ctrl:1
	v_add_f32_dpp v216, v216, v216 row_mirror row_mask:0xf bank_mask:0xf bound_ctrl:1
	v_pk_fma_f32 v[22:23], v[194:195], v[214:215], v[210:211] op_sel_hi:[1,0,1]
	v_pk_fma_f32 v[24:25], v[196:197], v[214:215], v[212:213] op_sel_hi:[1,0,1]
	v_cndmask_b32_e32 v26, v26, v216, vcc
	s_waitcnt lgkmcnt(6)
	ds_read_b128 v[32:35], v217 offset:29568
	ds_read_b128 v[36:39], v217 offset:29824
	ds_read_b128 v[40:43], v217 offset:30080
	ds_read_b128 v[44:47], v217 offset:30336
	ds_read_b128 v[48:51], v217 offset:30592
	ds_read_b32 v92, v218 offset:29568
	v_pk_mul_f32 v[206:207], v[24:25], v[122:123]
	v_pk_mul_f32 v[208:209], v[24:25], v[204:205]
	v_pk_fma_f32 v[206:207], v[22:23], v[120:121], v[206:207]
	v_pk_fma_f32 v[208:209], v[22:23], v[202:203], v[208:209]
	v_pk_mul_f32 v[210:211], v[132:133], v[28:29] op_sel_hi:[1,0]
	v_add_f32_e32 v214, v206, v207
	v_add_f32_e32 v216, v208, v209
	v_pk_mul_f32 v[212:213], v[134:135], v[28:29] op_sel_hi:[1,0]
	v_add_f32_dpp v214, v214, v214 quad_perm:[1,0,3,2] row_mask:0xf bank_mask:0xf bound_ctrl:1
	v_add_f32_dpp v216, v216, v216 quad_perm:[1,0,3,2] row_mask:0xf bank_mask:0xf bound_ctrl:1
	v_pk_fma_f32 v[210:211], v[22:23], v[124:125], v[210:211]
	v_add_f32_dpp v214, v214, v214 quad_perm:[2,3,0,1] row_mask:0xf bank_mask:0xf bound_ctrl:1
	v_add_f32_dpp v216, v216, v216 quad_perm:[2,3,0,1] row_mask:0xf bank_mask:0xf bound_ctrl:1
	v_pk_fma_f32 v[212:213], v[24:25], v[126:127], v[212:213]
	v_add_f32_dpp v214, v214, v214 row_half_mirror row_mask:0xf bank_mask:0xf bound_ctrl:1
	v_add_f32_dpp v216, v216, v216 row_half_mirror row_mask:0xf bank_mask:0xf bound_ctrl:1
	v_cmp_eq_u32_e32 vcc, 3, v106
	v_add_f32_dpp v214, v214, v214 row_mirror row_mask:0xf bank_mask:0xf bound_ctrl:1
	v_add_f32_dpp v216, v216, v216 row_mirror row_mask:0xf bank_mask:0xf bound_ctrl:1
	v_pk_fma_f32 v[22:23], v[128:129], v[214:215], v[210:211] op_sel_hi:[1,0,1]
	v_pk_fma_f32 v[24:25], v[130:131], v[214:215], v[212:213] op_sel_hi:[1,0,1]
	v_cndmask_b32_e32 v26, v26, v216, vcc
	s_waitcnt lgkmcnt(6)
; __device__ void phase_scan(int l, unsigned char* lds) {
;     ...
;             for (int t8 = 16; t8 < (jb.nsteps < 32 ? jb.nsteps : 32); t8 += 4) {
; #pragma unroll
;                 for (int u = 0; u < 4; ++u) {
;                     const int tt = t8 + u;
;                     const unsigned char* tb = buf + tt * SC_TOKB + c0 * 4;
;                     const f32x4 a = *(const f32x4*)(tb), w = *(const f32x4*)(tb + 256), b = *(const f32x4*)(tb + 512), k = *(const f32x4*)(tb + 768), r = *(const f32x4*)(tb + 1024);
;                     const float v = *(const float*)(buf + tt * SC_TOKB + 1280 + rl * 4);
;                     const f32x2 a01 = (f32x2){a[0], a[1]}, a23 = (f32x2){a[2], a[3]}, w01 = (f32x2){w[0], w[1]}, w23 = (f32x2){w[2], w[3]}, b01 = (f32x2){b[0], b[1]}, b23 = (f32x2){b[2], b[3]};
;                     const f32x2 k01 = (f32x2){k[0], k[1]}, k23 = (f32x2){k[2], k[3]}, r01 = (f32x2){r[0], r[1]}, r23 = (f32x2){r[2], r[3]};
;                     const f32x2 pa = s01 * a01 + s23 * a23;
;                     const float sa = allsum16(pa.x + pa.y);
;                     const f32x2 kv01 = k01 * v, kv23 = k23 * v;
;                     s01 = s01 * w01 + (b01 * sa + kv01); s23 = s23 * w23 + (b23 * sa + kv23);
;                     const f32x2 py = s01 * r01 + s23 * r23;
;                     const float y = allsum16(py.x + py.y);
;                     if ((lane & 15) == (tt & 15)) yreg1 = y;
;                 }
;             }
	ds_read_b128 v[186:189], v217 offset:30912
	ds_read_b128 v[190:193], v217 offset:31168
	ds_read_b128 v[194:197], v217 offset:31424
	ds_read_b128 v[198:201], v217 offset:31680
	ds_read_b128 v[202:205], v217 offset:31936
	ds_read_b32 v52, v218 offset:30912
	v_pk_mul_f32 v[206:207], v[24:25], v[148:149]
	v_pk_mul_f32 v[208:209], v[24:25], v[138:139]
	v_pk_fma_f32 v[206:207], v[22:23], v[146:147], v[206:207]
	v_pk_fma_f32 v[208:209], v[22:23], v[136:137], v[208:209]
	v_pk_mul_f32 v[210:211], v[158:159], v[30:31] op_sel_hi:[1,0]
	v_add_f32_e32 v214, v206, v207
	v_add_f32_e32 v216, v208, v209
	v_pk_mul_f32 v[212:213], v[160:161], v[30:31] op_sel_hi:[1,0]
	v_add_f32_dpp v214, v214, v214 quad_perm:[1,0,3,2] row_mask:0xf bank_mask:0xf bound_ctrl:1
	v_add_f32_dpp v216, v216, v216 quad_perm:[1,0,3,2] row_mask:0xf bank_mask:0xf bound_ctrl:1
	v_pk_fma_f32 v[210:211], v[22:23], v[150:151], v[210:211]
	v_add_f32_dpp v214, v214, v214 quad_perm:[2,3,0,1] row_mask:0xf bank_mask:0xf bound_ctrl:1
	v_add_f32_dpp v216, v216, v216 quad_perm:[2,3,0,1] row_mask:0xf bank_mask:0xf bound_ctrl:1
	v_pk_fma_f32 v[212:213], v[24:25], v[152:153], v[212:213]
	v_add_f32_dpp v214, v214, v214 row_half_mirror row_mask:0xf bank_mask:0xf bound_ctrl:1
	v_add_f32_dpp v216, v216, v216 row_half_mirror row_mask:0xf bank_mask:0xf bound_ctrl:1
	v_cmp_eq_u32_e32 vcc, 4, v106
	v_add_f32_dpp v214, v214, v214 row_mirror row_mask:0xf bank_mask:0xf bound_ctrl:1
	v_add_f32_dpp v216, v216, v216 row_mirror row_mask:0xf bank_mask:0xf bound_ctrl:1
	v_pk_fma_f32 v[22:23], v[154:155], v[214:215], v[210:211] op_sel_hi:[1,0,1]
	v_pk_fma_f32 v[24:25], v[156:157], v[214:215], v[212:213] op_sel_hi:[1,0,1]
	v_cndmask_b32_e32 v26, v26, v216, vcc
	s_waitcnt lgkmcnt(6)
	ds_read_b128 v[120:123], v217 offset:32256
	ds_read_b128 v[124:127], v217 offset:32512
	ds_read_b128 v[128:131], v217 offset:32768
	ds_read_b128 v[132:135], v217 offset:33024
	ds_read_b128 v[136:139], v217 offset:33280
	ds_read_b32 v28, v218 offset:32256
	v_pk_mul_f32 v[206:207], v[24:25], v[34:35]
	v_pk_mul_f32 v[208:209], v[24:25], v[164:165]
	v_pk_fma_f32 v[206:207], v[22:23], v[32:33], v[206:207]
	v_pk_fma_f32 v[208:209], v[22:23], v[162:163], v[208:209]
	v_pk_mul_f32 v[210:211], v[44:45], v[92:93] op_sel_hi:[1,0]
	v_add_f32_e32 v214, v206, v207
	v_add_f32_e32 v216, v208, v209
	v_pk_mul_f32 v[212:213], v[46:47], v[92:93] op_sel_hi:[1,0]
	v_add_f32_dpp v214, v214, v214 quad_perm:[1,0,3,2] row_mask:0xf bank_mask:0xf bound_ctrl:1
	v_add_f32_dpp v216, v216, v216 quad_perm:[1,0,3,2] row_mask:0xf bank_mask:0xf bound_ctrl:1
	v_pk_fma_f32 v[210:211], v[22:23], v[36:37], v[210:211]
	v_add_f32_dpp v214, v214, v214 quad_perm:[2,3,0,1] row_mask:0xf bank_mask:0xf bound_ctrl:1
	v_add_f32_dpp v216, v216, v216 quad_perm:[2,3,0,1] row_mask:0xf bank_mask:0xf bound_ctrl:1
	v_pk_fma_f32 v[212:213], v[24:25], v[38:39], v[212:213]
	v_add_f32_dpp v214, v214, v214 row_half_mirror row_mask:0xf bank_mask:0xf bound_ctrl:1
	v_add_f32_dpp v216, v216, v216 row_half_mirror row_mask:0xf bank_mask:0xf bound_ctrl:1
	v_cmp_eq_u32_e32 vcc, 5, v106
	v_add_f32_dpp v214, v214, v214 row_mirror row_mask:0xf bank_mask:0xf bound_ctrl:1
	v_add_f32_dpp v216, v216, v216 row_mirror row_mask:0xf bank_mask:0xf bound_ctrl:1
	v_pk_fma_f32 v[22:23], v[40:41], v[214:215], v[210:211] op_sel_hi:[1,0,1]
	v_pk_fma_f32 v[24:25], v[42:43], v[214:215], v[212:213] op_sel_hi:[1,0,1]
	v_cndmask_b32_e32 v26, v26, v216, vcc
	s_waitcnt lgkmcnt(6)
	ds_read_b128 v[146:149], v217 offset:33600
	ds_read_b128 v[150:153], v217 offset:33856
	ds_read_b128 v[154:157], v217 offset:34112
	ds_read_b128 v[158:161], v217 offset:34368
	ds_read_b128 v[162:165], v217 offset:34624
	ds_read_b32 v30, v218 offset:33600
	v_pk_mul_f32 v[206:207], v[24:25], v[188:189]
	v_pk_mul_f32 v[208:209], v[24:25], v[50:51]
	v_pk_fma_f32 v[206:207], v[22:23], v[186:187], v[206:207]
	v_pk_fma_f32 v[208:209], v[22:23], v[48:49], v[208:209]
	v_pk_mul_f32 v[210:211], v[198:199], v[52:53] op_sel_hi:[1,0]
	v_add_f32_e32 v214, v206, v207
	v_add_f32_e32 v216, v208, v209
	v_pk_mul_f32 v[212:213], v[200:201], v[52:53] op_sel_hi:[1,0]
	v_add_f32_dpp v214, v214, v214 quad_perm:[1,0,3,2] row_mask:0xf bank_mask:0xf bound_ctrl:1
	v_add_f32_dpp v216, v216, v216 quad_perm:[1,0,3,2] row_mask:0xf bank_mask:0xf bound_ctrl:1
	v_pk_fma_f32 v[210:211], v[22:23], v[190:191], v[210:211]
	v_add_f32_dpp v214, v214, v214 quad_perm:[2,3,0,1] row_mask:0xf bank_mask:0xf bound_ctrl:1
	v_add_f32_dpp v216, v216, v216 quad_perm:[2,3,0,1] row_mask:0xf bank_mask:0xf bound_ctrl:1
	v_pk_fma_f32 v[212:213], v[24:25], v[192:193], v[212:213]
	v_add_f32_dpp v214, v214, v214 row_half_mirror row_mask:0xf bank_mask:0xf bound_ctrl:1
	v_add_f32_dpp v216, v216, v216 row_half_mirror row_mask:0xf bank_mask:0xf bound_ctrl:1
	v_cmp_eq_u32_e32 vcc, 6, v106
	v_add_f32_dpp v214, v214, v214 row_mirror row_mask:0xf bank_mask:0xf bound_ctrl:1
	v_add_f32_dpp v216, v216, v216 row_mirror row_mask:0xf bank_mask:0xf bound_ctrl:1
	v_pk_fma_f32 v[22:23], v[194:195], v[214:215], v[210:211] op_sel_hi:[1,0,1]
	v_pk_fma_f32 v[24:25], v[196:197], v[214:215], v[212:213] op_sel_hi:[1,0,1]
	v_cndmask_b32_e32 v26, v26, v216, vcc
	s_waitcnt lgkmcnt(6)
; __device__ void phase_scan(int l, unsigned char* lds) {
;     ...
;             for (int t8 = 16; t8 < (jb.nsteps < 32 ? jb.nsteps : 32); t8 += 4) {
; #pragma unroll
;                 for (int u = 0; u < 4; ++u) {
;                     const int tt = t8 + u;
;                     const unsigned char* tb = buf + tt * SC_TOKB + c0 * 4;
;                     const f32x4 a = *(const f32x4*)(tb), w = *(const f32x4*)(tb + 256), b = *(const f32x4*)(tb + 512), k = *(const f32x4*)(tb + 768), r = *(const f32x4*)(tb + 1024);
;                     const float v = *(const float*)(buf + tt * SC_TOKB + 1280 + rl * 4);
;                     const f32x2 a01 = (f32x2){a[0], a[1]}, a23 = (f32x2){a[2], a[3]}, w01 = (f32x2){w[0], w[1]}, w23 = (f32x2){w[2], w[3]}, b01 = (f32x2){b[0], b[1]}, b23 = (f32x2){b[2], b[3]};
;                     const f32x2 k01 = (f32x2){k[0], k[1]}, k23 = (f32x2){k[2], k[3]}, r01 = (f32x2){r[0], r[1]}, r23 = (f32x2){r[2], r[3]};
;                     const f32x2 pa = s01 * a01 + s23 * a23;
;                     const float sa = allsum16(pa.x + pa.y);
;                     const f32x2 kv01 = k01 * v, kv23 = k23 * v;
;                     s01 = s01 * w01 + (b01 * sa + kv01); s23 = s23 * w23 + (b23 * sa + kv23);
;                     const f32x2 py = s01 * r01 + s23 * r23;
;                     const float y = allsum16(py.x + py.y);
;                     if ((lane & 15) == (tt & 15)) yreg1 = y;
;                 }
;             }
	ds_read_b128 v[32:35], v217 offset:34944
	ds_read_b128 v[36:39], v217 offset:35200
	ds_read_b128 v[40:43], v217 offset:35456
	ds_read_b128 v[44:47], v217 offset:35712
	ds_read_b128 v[48:51], v217 offset:35968
	ds_read_b32 v92, v218 offset:34944
	v_pk_mul_f32 v[206:207], v[24:25], v[122:123]
	v_pk_mul_f32 v[208:209], v[24:25], v[204:205]
	v_pk_fma_f32 v[206:207], v[22:23], v[120:121], v[206:207]
	v_pk_fma_f32 v[208:209], v[22:23], v[202:203], v[208:209]
	v_pk_mul_f32 v[210:211], v[132:133], v[28:29] op_sel_hi:[1,0]
	v_add_f32_e32 v214, v206, v207
	v_add_f32_e32 v216, v208, v209
	v_pk_mul_f32 v[212:213], v[134:135], v[28:29] op_sel_hi:[1,0]
	v_add_f32_dpp v214, v214, v214 quad_perm:[1,0,3,2] row_mask:0xf bank_mask:0xf bound_ctrl:1
	v_add_f32_dpp v216, v216, v216 quad_perm:[1,0,3,2] row_mask:0xf bank_mask:0xf bound_ctrl:1
	v_pk_fma_f32 v[210:211], v[22:23], v[124:125], v[210:211]
	v_add_f32_dpp v214, v214, v214 quad_perm:[2,3,0,1] row_mask:0xf bank_mask:0xf bound_ctrl:1
	v_add_f32_dpp v216, v216, v216 quad_perm:[2,3,0,1] row_mask:0xf bank_mask:0xf bound_ctrl:1
	v_pk_fma_f32 v[212:213], v[24:25], v[126:127], v[212:213]
	v_add_f32_dpp v214, v214, v214 row_half_mirror row_mask:0xf bank_mask:0xf bound_ctrl:1
	v_add_f32_dpp v216, v216, v216 row_half_mirror row_mask:0xf bank_mask:0xf bound_ctrl:1
	v_cmp_eq_u32_e32 vcc, 7, v106
	v_add_f32_dpp v214, v214, v214 row_mirror row_mask:0xf bank_mask:0xf bound_ctrl:1
	v_add_f32_dpp v216, v216, v216 row_mirror row_mask:0xf bank_mask:0xf bound_ctrl:1
	v_pk_fma_f32 v[22:23], v[128:129], v[214:215], v[210:211] op_sel_hi:[1,0,1]
	v_pk_fma_f32 v[24:25], v[130:131], v[214:215], v[212:213] op_sel_hi:[1,0,1]
	v_cndmask_b32_e32 v26, v26, v216, vcc
	s_waitcnt lgkmcnt(6)
	ds_read_b128 v[186:189], v217 offset:36288
	ds_read_b128 v[190:193], v217 offset:36544
	ds_read_b128 v[194:197], v217 offset:36800
	ds_read_b128 v[198:201], v217 offset:37056
	ds_read_b128 v[202:205], v217 offset:37312
	ds_read_b32 v52, v218 offset:36288
	v_pk_mul_f32 v[206:207], v[24:25], v[148:149]
	v_pk_mul_f32 v[208:209], v[24:25], v[138:139]
	v_pk_fma_f32 v[206:207], v[22:23], v[146:147], v[206:207]
	v_pk_fma_f32 v[208:209], v[22:23], v[136:137], v[208:209]
	v_pk_mul_f32 v[210:211], v[158:159], v[30:31] op_sel_hi:[1,0]
	v_add_f32_e32 v214, v206, v207
	v_add_f32_e32 v216, v208, v209
	v_pk_mul_f32 v[212:213], v[160:161], v[30:31] op_sel_hi:[1,0]
	v_add_f32_dpp v214, v214, v214 quad_perm:[1,0,3,2] row_mask:0xf bank_mask:0xf bound_ctrl:1
	v_add_f32_dpp v216, v216, v216 quad_perm:[1,0,3,2] row_mask:0xf bank_mask:0xf bound_ctrl:1
	v_pk_fma_f32 v[210:211], v[22:23], v[150:151], v[210:211]
	v_add_f32_dpp v214, v214, v214 quad_perm:[2,3,0,1] row_mask:0xf bank_mask:0xf bound_ctrl:1
	v_add_f32_dpp v216, v216, v216 quad_perm:[2,3,0,1] row_mask:0xf bank_mask:0xf bound_ctrl:1
	v_pk_fma_f32 v[212:213], v[24:25], v[152:153], v[212:213]
	v_add_f32_dpp v214, v214, v214 row_half_mirror row_mask:0xf bank_mask:0xf bound_ctrl:1
	v_add_f32_dpp v216, v216, v216 row_half_mirror row_mask:0xf bank_mask:0xf bound_ctrl:1
	v_cmp_eq_u32_e32 vcc, 8, v106
	v_add_f32_dpp v214, v214, v214 row_mirror row_mask:0xf bank_mask:0xf bound_ctrl:1
	v_add_f32_dpp v216, v216, v216 row_mirror row_mask:0xf bank_mask:0xf bound_ctrl:1
	v_pk_fma_f32 v[22:23], v[154:155], v[214:215], v[210:211] op_sel_hi:[1,0,1]
	v_pk_fma_f32 v[24:25], v[156:157], v[214:215], v[212:213] op_sel_hi:[1,0,1]
	v_cndmask_b32_e32 v26, v26, v216, vcc
	s_waitcnt lgkmcnt(6)
	ds_read_b128 v[120:123], v217 offset:37632
	ds_read_b128 v[124:127], v217 offset:37888
	ds_read_b128 v[128:131], v217 offset:38144
	ds_read_b128 v[132:135], v217 offset:38400
	ds_read_b128 v[136:139], v217 offset:38656
	ds_read_b32 v28, v218 offset:37632
	v_pk_mul_f32 v[206:207], v[24:25], v[34:35]
	v_pk_mul_f32 v[208:209], v[24:25], v[164:165]
	v_pk_fma_f32 v[206:207], v[22:23], v[32:33], v[206:207]
	v_pk_fma_f32 v[208:209], v[22:23], v[162:163], v[208:209]
	v_pk_mul_f32 v[210:211], v[44:45], v[92:93] op_sel_hi:[1,0]
	v_add_f32_e32 v214, v206, v207
	v_add_f32_e32 v216, v208, v209
	v_pk_mul_f32 v[212:213], v[46:47], v[92:93] op_sel_hi:[1,0]
	v_add_f32_dpp v214, v214, v214 quad_perm:[1,0,3,2] row_mask:0xf bank_mask:0xf bound_ctrl:1
	v_add_f32_dpp v216, v216, v216 quad_perm:[1,0,3,2] row_mask:0xf bank_mask:0xf bound_ctrl:1
	v_pk_fma_f32 v[210:211], v[22:23], v[36:37], v[210:211]
	v_add_f32_dpp v214, v214, v214 quad_perm:[2,3,0,1] row_mask:0xf bank_mask:0xf bound_ctrl:1
	v_add_f32_dpp v216, v216, v216 quad_perm:[2,3,0,1] row_mask:0xf bank_mask:0xf bound_ctrl:1
	v_pk_fma_f32 v[212:213], v[24:25], v[38:39], v[212:213]
	v_add_f32_dpp v214, v214, v214 row_half_mirror row_mask:0xf bank_mask:0xf bound_ctrl:1
	v_add_f32_dpp v216, v216, v216 row_half_mirror row_mask:0xf bank_mask:0xf bound_ctrl:1
	v_cmp_eq_u32_e32 vcc, 9, v106
	v_add_f32_dpp v214, v214, v214 row_mirror row_mask:0xf bank_mask:0xf bound_ctrl:1
	v_add_f32_dpp v216, v216, v216 row_mirror row_mask:0xf bank_mask:0xf bound_ctrl:1
	v_pk_fma_f32 v[22:23], v[40:41], v[214:215], v[210:211] op_sel_hi:[1,0,1]
	v_pk_fma_f32 v[24:25], v[42:43], v[214:215], v[212:213] op_sel_hi:[1,0,1]
	v_cndmask_b32_e32 v26, v26, v216, vcc
	s_waitcnt lgkmcnt(6)
; __device__ void phase_scan(int l, unsigned char* lds) {
;     ...
;             for (int t8 = 16; t8 < (jb.nsteps < 32 ? jb.nsteps : 32); t8 += 4) {
; #pragma unroll
;                 for (int u = 0; u < 4; ++u) {
;                     const int tt = t8 + u;
;                     const unsigned char* tb = buf + tt * SC_TOKB + c0 * 4;
;                     const f32x4 a = *(const f32x4*)(tb), w = *(const f32x4*)(tb + 256), b = *(const f32x4*)(tb + 512), k = *(const f32x4*)(tb + 768), r = *(const f32x4*)(tb + 1024);
;                     const float v = *(const float*)(buf + tt * SC_TOKB + 1280 + rl * 4);
;                     const f32x2 a01 = (f32x2){a[0], a[1]}, a23 = (f32x2){a[2], a[3]}, w01 = (f32x2){w[0], w[1]}, w23 = (f32x2){w[2], w[3]}, b01 = (f32x2){b[0], b[1]}, b23 = (f32x2){b[2], b[3]};
;                     const f32x2 k01 = (f32x2){k[0], k[1]}, k23 = (f32x2){k[2], k[3]}, r01 = (f32x2){r[0], r[1]}, r23 = (f32x2){r[2], r[3]};
;                     const f32x2 pa = s01 * a01 + s23 * a23;
;                     const float sa = allsum16(pa.x + pa.y);
;                     const f32x2 kv01 = k01 * v, kv23 = k23 * v;
;                     s01 = s01 * w01 + (b01 * sa + kv01); s23 = s23 * w23 + (b23 * sa + kv23);
;                     const f32x2 py = s01 * r01 + s23 * r23;
;                     const float y = allsum16(py.x + py.y);
;                     if ((lane & 15) == (tt & 15)) yreg1 = y;
;                 }
;             }
	ds_read_b128 v[146:149], v217 offset:38976
	ds_read_b128 v[150:153], v217 offset:39232
	ds_read_b128 v[154:157], v217 offset:39488
	ds_read_b128 v[158:161], v217 offset:39744
	ds_read_b128 v[162:165], v217 offset:40000
	ds_read_b32 v30, v218 offset:38976
	v_pk_mul_f32 v[206:207], v[24:25], v[188:189]
	v_pk_mul_f32 v[208:209], v[24:25], v[50:51]
	v_pk_fma_f32 v[206:207], v[22:23], v[186:187], v[206:207]
	v_pk_fma_f32 v[208:209], v[22:23], v[48:49], v[208:209]
	v_pk_mul_f32 v[210:211], v[198:199], v[52:53] op_sel_hi:[1,0]
	v_add_f32_e32 v214, v206, v207
	v_add_f32_e32 v216, v208, v209
	v_pk_mul_f32 v[212:213], v[200:201], v[52:53] op_sel_hi:[1,0]
	v_add_f32_dpp v214, v214, v214 quad_perm:[1,0,3,2] row_mask:0xf bank_mask:0xf bound_ctrl:1
	v_add_f32_dpp v216, v216, v216 quad_perm:[1,0,3,2] row_mask:0xf bank_mask:0xf bound_ctrl:1
	v_pk_fma_f32 v[210:211], v[22:23], v[190:191], v[210:211]
	v_add_f32_dpp v214, v214, v214 quad_perm:[2,3,0,1] row_mask:0xf bank_mask:0xf bound_ctrl:1
	v_add_f32_dpp v216, v216, v216 quad_perm:[2,3,0,1] row_mask:0xf bank_mask:0xf bound_ctrl:1
	v_pk_fma_f32 v[212:213], v[24:25], v[192:193], v[212:213]
	v_add_f32_dpp v214, v214, v214 row_half_mirror row_mask:0xf bank_mask:0xf bound_ctrl:1
	v_add_f32_dpp v216, v216, v216 row_half_mirror row_mask:0xf bank_mask:0xf bound_ctrl:1
	v_cmp_eq_u32_e32 vcc, 10, v106
	v_add_f32_dpp v214, v214, v214 row_mirror row_mask:0xf bank_mask:0xf bound_ctrl:1
	v_add_f32_dpp v216, v216, v216 row_mirror row_mask:0xf bank_mask:0xf bound_ctrl:1
	v_pk_fma_f32 v[22:23], v[194:195], v[214:215], v[210:211] op_sel_hi:[1,0,1]
	v_pk_fma_f32 v[24:25], v[196:197], v[214:215], v[212:213] op_sel_hi:[1,0,1]
	v_cndmask_b32_e32 v26, v26, v216, vcc
	s_waitcnt lgkmcnt(6)
	ds_read_b128 v[32:35], v217 offset:40320
	ds_read_b128 v[36:39], v217 offset:40576
	ds_read_b128 v[40:43], v217 offset:40832
	ds_read_b128 v[44:47], v217 offset:41088
	ds_read_b128 v[48:51], v217 offset:41344
	ds_read_b32 v92, v218 offset:40320
	v_pk_mul_f32 v[206:207], v[24:25], v[122:123]
	v_pk_mul_f32 v[208:209], v[24:25], v[204:205]
	v_pk_fma_f32 v[206:207], v[22:23], v[120:121], v[206:207]
	v_pk_fma_f32 v[208:209], v[22:23], v[202:203], v[208:209]
	v_pk_mul_f32 v[210:211], v[132:133], v[28:29] op_sel_hi:[1,0]
	v_add_f32_e32 v214, v206, v207
	v_add_f32_e32 v216, v208, v209
	v_pk_mul_f32 v[212:213], v[134:135], v[28:29] op_sel_hi:[1,0]
	v_add_f32_dpp v214, v214, v214 quad_perm:[1,0,3,2] row_mask:0xf bank_mask:0xf bound_ctrl:1
	v_add_f32_dpp v216, v216, v216 quad_perm:[1,0,3,2] row_mask:0xf bank_mask:0xf bound_ctrl:1
	v_pk_fma_f32 v[210:211], v[22:23], v[124:125], v[210:211]
	v_add_f32_dpp v214, v214, v214 quad_perm:[2,3,0,1] row_mask:0xf bank_mask:0xf bound_ctrl:1
	v_add_f32_dpp v216, v216, v216 quad_perm:[2,3,0,1] row_mask:0xf bank_mask:0xf bound_ctrl:1
	v_pk_fma_f32 v[212:213], v[24:25], v[126:127], v[212:213]
	v_add_f32_dpp v214, v214, v214 row_half_mirror row_mask:0xf bank_mask:0xf bound_ctrl:1
	v_add_f32_dpp v216, v216, v216 row_half_mirror row_mask:0xf bank_mask:0xf bound_ctrl:1
	v_cmp_eq_u32_e32 vcc, 11, v106
	v_add_f32_dpp v214, v214, v214 row_mirror row_mask:0xf bank_mask:0xf bound_ctrl:1
	v_add_f32_dpp v216, v216, v216 row_mirror row_mask:0xf bank_mask:0xf bound_ctrl:1
	v_pk_fma_f32 v[22:23], v[128:129], v[214:215], v[210:211] op_sel_hi:[1,0,1]
	v_pk_fma_f32 v[24:25], v[130:131], v[214:215], v[212:213] op_sel_hi:[1,0,1]
	v_cndmask_b32_e32 v26, v26, v216, vcc
	s_waitcnt lgkmcnt(6)
	ds_read_b128 v[186:189], v217 offset:41664
	ds_read_b128 v[190:193], v217 offset:41920
	ds_read_b128 v[194:197], v217 offset:42176
	ds_read_b128 v[198:201], v217 offset:42432
	ds_read_b128 v[202:205], v217 offset:42688
	ds_read_b32 v52, v218 offset:41664
	v_pk_mul_f32 v[206:207], v[24:25], v[148:149]
	v_pk_mul_f32 v[208:209], v[24:25], v[138:139]
	v_pk_fma_f32 v[206:207], v[22:23], v[146:147], v[206:207]
	v_pk_fma_f32 v[208:209], v[22:23], v[136:137], v[208:209]
	v_pk_mul_f32 v[210:211], v[158:159], v[30:31] op_sel_hi:[1,0]
	v_add_f32_e32 v214, v206, v207
	v_add_f32_e32 v216, v208, v209
	v_pk_mul_f32 v[212:213], v[160:161], v[30:31] op_sel_hi:[1,0]
	v_add_f32_dpp v214, v214, v214 quad_perm:[1,0,3,2] row_mask:0xf bank_mask:0xf bound_ctrl:1
	v_add_f32_dpp v216, v216, v216 quad_perm:[1,0,3,2] row_mask:0xf bank_mask:0xf bound_ctrl:1
	v_pk_fma_f32 v[210:211], v[22:23], v[150:151], v[210:211]
	v_add_f32_dpp v214, v214, v214 quad_perm:[2,3,0,1] row_mask:0xf bank_mask:0xf bound_ctrl:1
	v_add_f32_dpp v216, v216, v216 quad_perm:[2,3,0,1] row_mask:0xf bank_mask:0xf bound_ctrl:1
	v_pk_fma_f32 v[212:213], v[24:25], v[152:153], v[212:213]
	v_add_f32_dpp v214, v214, v214 row_half_mirror row_mask:0xf bank_mask:0xf bound_ctrl:1
	v_add_f32_dpp v216, v216, v216 row_half_mirror row_mask:0xf bank_mask:0xf bound_ctrl:1
	v_cmp_eq_u32_e32 vcc, 12, v106
	v_add_f32_dpp v214, v214, v214 row_mirror row_mask:0xf bank_mask:0xf bound_ctrl:1
	v_add_f32_dpp v216, v216, v216 row_mirror row_mask:0xf bank_mask:0xf bound_ctrl:1
	v_pk_fma_f32 v[22:23], v[154:155], v[214:215], v[210:211] op_sel_hi:[1,0,1]
	v_pk_fma_f32 v[24:25], v[156:157], v[214:215], v[212:213] op_sel_hi:[1,0,1]
	v_cndmask_b32_e32 v26, v26, v216, vcc
	s_waitcnt lgkmcnt(6)
; __device__ __forceinline__ bf16_t f2bf(float f) { return (bf16_t)(pk2(f, 0.f) & 0xffffu); }
; __device__ void phase_scan(int l, unsigned char* lds) {
;     ...
;             for (int t8 = 16; t8 < (jb.nsteps < 32 ? jb.nsteps : 32); t8 += 4) {
; #pragma unroll
;                 for (int u = 0; u < 4; ++u) {
;                     const int tt = t8 + u;
;                     const unsigned char* tb = buf + tt * SC_TOKB + c0 * 4;
;                     const f32x4 a = *(const f32x4*)(tb), w = *(const f32x4*)(tb + 256), b = *(const f32x4*)(tb + 512), k = *(const f32x4*)(tb + 768), r = *(const f32x4*)(tb + 1024);
;                     const float v = *(const float*)(buf + tt * SC_TOKB + 1280 + rl * 4);
;                     const f32x2 a01 = (f32x2){a[0], a[1]}, a23 = (f32x2){a[2], a[3]}, w01 = (f32x2){w[0], w[1]}, w23 = (f32x2){w[2], w[3]}, b01 = (f32x2){b[0], b[1]}, b23 = (f32x2){b[2], b[3]};
;                     const f32x2 k01 = (f32x2){k[0], k[1]}, k23 = (f32x2){k[2], k[3]}, r01 = (f32x2){r[0], r[1]}, r23 = (f32x2){r[2], r[3]};
;                     const f32x2 pa = s01 * a01 + s23 * a23;
;                     const float sa = allsum16(pa.x + pa.y);
;                     const f32x2 kv01 = k01 * v, kv23 = k23 * v;
;                     s01 = s01 * w01 + (b01 * sa + kv01); s23 = s23 * w23 + (b23 * sa + kv23);
;                     const f32x2 py = s01 * r01 + s23 * r23;
;                     const float y = allsum16(py.x + py.y);
;                     if ((lane & 15) == (tt & 15)) yreg1 = y;
;                 }
;             }
;             if ((lane & 15) < jb.nsteps) ybuf[(size_t)(jb.tok0 + (lane & 15)) * 512 + jb.h * 64 + row] = f2bf(yreg0);
;             if (16 + (lane & 15) < jb.nsteps) ybuf[(size_t)(jb.tok0 + 16 + (lane & 15)) * 512 + jb.h * 64 + row] = f2bf(yreg1);
	v_pk_mul_f32 v[206:207], v[24:25], v[34:35]
	v_pk_mul_f32 v[208:209], v[24:25], v[164:165]
	v_pk_fma_f32 v[206:207], v[22:23], v[32:33], v[206:207]
	v_pk_fma_f32 v[208:209], v[22:23], v[162:163], v[208:209]
	v_pk_mul_f32 v[210:211], v[44:45], v[92:93] op_sel_hi:[1,0]
	v_add_f32_e32 v214, v206, v207
	v_add_f32_e32 v216, v208, v209
	v_pk_mul_f32 v[212:213], v[46:47], v[92:93] op_sel_hi:[1,0]
	v_add_f32_dpp v214, v214, v214 quad_perm:[1,0,3,2] row_mask:0xf bank_mask:0xf bound_ctrl:1
	v_add_f32_dpp v216, v216, v216 quad_perm:[1,0,3,2] row_mask:0xf bank_mask:0xf bound_ctrl:1
	v_pk_fma_f32 v[210:211], v[22:23], v[36:37], v[210:211]
	v_add_f32_dpp v214, v214, v214 quad_perm:[2,3,0,1] row_mask:0xf bank_mask:0xf bound_ctrl:1
	v_add_f32_dpp v216, v216, v216 quad_perm:[2,3,0,1] row_mask:0xf bank_mask:0xf bound_ctrl:1
	v_pk_fma_f32 v[212:213], v[24:25], v[38:39], v[212:213]
	v_add_f32_dpp v214, v214, v214 row_half_mirror row_mask:0xf bank_mask:0xf bound_ctrl:1
	v_add_f32_dpp v216, v216, v216 row_half_mirror row_mask:0xf bank_mask:0xf bound_ctrl:1
	v_cmp_eq_u32_e32 vcc, 13, v106
	v_add_f32_dpp v214, v214, v214 row_mirror row_mask:0xf bank_mask:0xf bound_ctrl:1
	v_add_f32_dpp v216, v216, v216 row_mirror row_mask:0xf bank_mask:0xf bound_ctrl:1
	v_pk_fma_f32 v[22:23], v[40:41], v[214:215], v[210:211] op_sel_hi:[1,0,1]
	v_pk_fma_f32 v[24:25], v[42:43], v[214:215], v[212:213] op_sel_hi:[1,0,1]
	v_cndmask_b32_e32 v26, v26, v216, vcc
	s_waitcnt lgkmcnt(0)
	v_pk_mul_f32 v[206:207], v[24:25], v[188:189]
	v_pk_mul_f32 v[208:209], v[24:25], v[50:51]
	v_pk_fma_f32 v[206:207], v[22:23], v[186:187], v[206:207]
	v_pk_fma_f32 v[208:209], v[22:23], v[48:49], v[208:209]
	v_pk_mul_f32 v[210:211], v[198:199], v[52:53] op_sel_hi:[1,0]
	v_add_f32_e32 v214, v206, v207
	v_add_f32_e32 v216, v208, v209
	v_pk_mul_f32 v[212:213], v[200:201], v[52:53] op_sel_hi:[1,0]
	v_add_f32_dpp v214, v214, v214 quad_perm:[1,0,3,2] row_mask:0xf bank_mask:0xf bound_ctrl:1
	v_add_f32_dpp v216, v216, v216 quad_perm:[1,0,3,2] row_mask:0xf bank_mask:0xf bound_ctrl:1
	v_pk_fma_f32 v[210:211], v[22:23], v[190:191], v[210:211]
	v_add_f32_dpp v214, v214, v214 quad_perm:[2,3,0,1] row_mask:0xf bank_mask:0xf bound_ctrl:1
	v_add_f32_dpp v216, v216, v216 quad_perm:[2,3,0,1] row_mask:0xf bank_mask:0xf bound_ctrl:1
	v_pk_fma_f32 v[212:213], v[24:25], v[192:193], v[212:213]
	v_add_f32_dpp v214, v214, v214 row_half_mirror row_mask:0xf bank_mask:0xf bound_ctrl:1
	v_add_f32_dpp v216, v216, v216 row_half_mirror row_mask:0xf bank_mask:0xf bound_ctrl:1
	v_cmp_eq_u32_e32 vcc, 14, v106
	v_add_f32_dpp v214, v214, v214 row_mirror row_mask:0xf bank_mask:0xf bound_ctrl:1
	v_add_f32_dpp v216, v216, v216 row_mirror row_mask:0xf bank_mask:0xf bound_ctrl:1
	v_pk_fma_f32 v[22:23], v[194:195], v[214:215], v[210:211] op_sel_hi:[1,0,1]
	v_pk_fma_f32 v[24:25], v[196:197], v[214:215], v[212:213] op_sel_hi:[1,0,1]
	v_cndmask_b32_e32 v26, v26, v216, vcc
	v_pk_mul_f32 v[208:209], v[24:25], v[204:205]
	v_pk_fma_f32 v[208:209], v[22:23], v[202:203], v[208:209]
	v_cmp_eq_u32_e32 vcc, 15, v106
	v_add_f32_e32 v216, v208, v209
	s_nop 1
	v_add_f32_dpp v216, v216, v216 quad_perm:[1,0,3,2] row_mask:0xf bank_mask:0xf bound_ctrl:1
	s_nop 1
	v_add_f32_dpp v216, v216, v216 quad_perm:[2,3,0,1] row_mask:0xf bank_mask:0xf bound_ctrl:1
	s_nop 1
	v_add_f32_dpp v216, v216, v216 row_half_mirror row_mask:0xf bank_mask:0xf bound_ctrl:1
	s_nop 1
	v_add_f32_dpp v216, v216, v216 row_mirror row_mask:0xf bank_mask:0xf bound_ctrl:1
	v_cndmask_b32_e32 v26, v26, v216, vcc
	s_branch .LBB0_1678
